# v25 + raised wave priority for the GEMM tile prologue (coords, DMA issue, accumulator zeroing) so a block returns to MFMA work sooner
# speedup vs baseline: 1.0041x; 1.0023x over previous
; #define LAS __attribute__((address_space(3)))
;     ...
;   const int nk = (nk_part < 0) ? (K >> 5) : nk_part;
;   const int lrow = tid >> 2, lpc = tid & 3;
;   const int lch = lpc ^ ((0x78 >> (((lrow >> 2) & 3) * 2)) & 3);
;   const u16* ga = A + (size_t)(m0 + lrow) * lda + kbeg + lch * 8;
;   const u16* gb = Bt + (size_t)(n0 + lrow) * K + kbeg + lch * 8;
;   const size_t ga1 = (size_t)64 * lda, gb1 = (size_t)64 * K;
;   const unsigned lds0 = (unsigned)(uintptr_t)(LAS char*)smem + (unsigned)__builtin_amdgcn_readfirstlane(wid) * 1024u;
; DEVI void run_phase(const Params& p, int ph, char* smem) {
;     ...
;         } else {
;           const int u_ = t - 512, tl_ = u_ / 11, q_ = u_ - tl_ * 11;
;           gemm_tile256<EPI_RESID_ATOMIC>(p, hb, DFF, Bt, DFF, (64 + (tl_ & 1)) * 256, (tl_ >> 1) * 128, nullptr, 0, smem, q_ * 256, 8, q_);
;         }
.LBB0_42:
	s_cmpk_gt_i32 s38, 0x1ff
	s_mov_b64 s[2:3], -1
	s_cbranch_scc0 .LBB0_116
	s_setprio 2
	s_sub_i32 s46, s38, 512
	s_mul_i32 s45, s46, 373
	s_lshr_b32 s45, s45, 12
	s_mul_i32 s47, s45, 11
	s_sub_i32 s47, s46, s47
	s_lshr_b32 s42, s45, 1
	s_and_b32 s45, s45, 1
	s_add_i32 s45, s45, 64
	s_cmp_lt_u32 s45, 64
	s_cselect_b32 s44, 1, 0
	v_readlane_b32 s2, v250, 5
	v_readlane_b32 s3, v250, 6
	v_readlane_b32 s46, v254, 62
	s_mul_i32 s40, s45, 0x160000
	s_add_u32 s4, s2, s40
	s_addc_u32 s5, s3, 0
	s_add_u32 s4, s4, 0xef40000
	s_addc_u32 s5, s5, 0
	s_mul_i32 s40, s46, 0x580000
	s_mul_i32 s41, s42, 0xb0000
	s_add_i32 s40, s40, s41
	s_add_u32 s10, s2, s40
	s_addc_u32 s11, s3, 0
	s_add_u32 s10, s10, 0x19a00000
	s_addc_u32 s11, s11, 0
	s_mul_i32 s40, s47, 512
	s_add_u32 s4, s4, s40
	s_addc_u32 s5, s5, 0
	s_mul_i32 s40, s47, 1024
	s_add_u32 s10, s10, s40
	s_addc_u32 s11, s11, 0
	s_movk_i32 s39, 0x78
	v_lshrrev_b32_e32 v0, 2, v145
	v_and_b32_e32 v131, 3, v145
	v_bfe_u32 v136, v145, 4, 2
	v_lshlrev_b32_e32 v136, 1, v136
	v_lshrrev_b32_e64 v136, v136, s39
	v_and_b32_e32 v136, 3, v136
	v_xor_b32_e32 v131, v131, v136
	v_lshlrev_b32_e32 v131, 4, v131
	s_movk_i32 s41, 0x1600
	v_mad_u32_u24 v0, v0, s41, v131
	v_bfe_u32 v137, v145, 2, 1
	s_movk_i32 s41, 0x15c0
	v_mul_u32_u24_e32 v136, s41, v137
	v_sub_u32_e32 v136, v0, v136
	v_mov_b32_e32 v137, 0
	v_lshl_add_u64 v[134:135], s[10:11], 0, v[136:137]
	v_bfe_u32 v137, v145, 2, 1
	s_mul_i32 s41, s44, 0x15c0
	v_mul_u32_u24_e32 v136, s41, v137
	v_sub_u32_e32 v0, v0, v136
	s_lshl_b32 s12, s44, 6
	s_add_i32 s12, s12, 64
	s_mov_b32 s13, 0
	v_lshl_add_u64 v[132:133], s[4:5], 0, v[0:1]
	v_bfe_u32 v136, v145, 2, 2
	v_lshlrev_b32_e32 v136, 1, v136
	v_lshrrev_b32_e64 v136, v136, s39
	v_and_b32_e32 v136, 3, v136
	v_bfe_u32 v137, v145, 4, 2
	v_xor_b32_e32 v136, v136, v137
	v_lshlrev_b32_e32 v136, 4, v136
	v_and_b32_e32 v131, 15, v145
	v_lshl_or_b32 v136, v131, 6, v136
	v_bfe_u32 v137, v145, 6, 1
	v_lshl_or_b32 v137, v137, 12, v136
	v_lshrrev_b32_e32 v0, 7, v145
	v_lshl_or_b32 v136, v0, 13, v136
	v_and_b32_e32 v140, 1, v131
	v_lshl_or_b32 v131, v0, 7, v131
	v_bfe_u32 v0, v145, 4, 2
	v_lshlrev_b32_e32 v0, 3, v0
	v_bfe_u32 v141, v145, 6, 1
	s_lshl_b32 s40, s45, 19
	s_lshl_b32 s41, s42, 8
	s_add_i32 s40, s40, s41
	s_add_u32 s4, s2, s40
	s_addc_u32 s5, s3, 0
	s_add_u32 s4, s4, 0x4200000
	s_addc_u32 s5, s5, 0
	v_lshlrev_b32_e32 v138, 11, v131
	v_lshl_add_u32 v138, v141, 7, v138
	v_bfe_u32 v139, v145, 4, 1
	v_lshl_add_u32 v138, v139, 5, v138
	v_bfe_u32 v139, v145, 5, 1
	v_lshl_add_u32 v138, v139, 4, v138
	v_mov_b32_e32 v139, 0
	v_lshl_add_u64 v[138:139], s[4:5], 0, v[138:139]
	s_and_b32 s40, s45, 1
	s_lshl_b32 s40, s40, 20
	s_lshl_b32 s41, s47, 21
	s_add_i32 s40, s40, s41
	s_lshl_b32 s41, s42, 9
	s_add_i32 s40, s40, s41
	s_add_u32 s10, s2, s40
	s_addc_u32 s11, s3, 0
	s_add_u32 s10, s10, 0x1dcc0000
	s_addc_u32 s11, s11, 0
	v_lshlrev_b32_e32 v140, 12, v131
	v_lshl_add_u32 v140, v141, 8, v140
	v_lshl_add_u32 v140, v0, 1, v140
	v_mov_b32_e32 v141, 0
	v_lshl_add_u64 v[140:141], s[10:11], 0, v[140:141]
	s_mov_b32 s2, 0x58000
	s_mov_b32 s3, 0
	v_lshrrev_b32_e32 v0, 6, v145
	v_lshlrev_b32_e32 v0, 10, v0
	s_nop 0
	v_readfirstlane_b32 s46, v0
	s_mov_b32 s43, m0
	s_mov_b32 s4, 128
	s_mov_b32 s5, 0
	s_barrier
; #define LAS __attribute__((address_space(3)))
;     ...
;   f32x4 acc[4][8];
; #pragma unroll
;   for (int i = 0; i < 4; i++)
; #pragma unroll
;     for (int j = 0; j < 8; j++) acc[i][j] = (f32x4){0.f, 0.f, 0.f, 0.f};
;   const int nk = (nk_part < 0) ? (K >> 5) : nk_part;
;   const int lrow = tid >> 2, lpc = tid & 3;
;   const int lch = lpc ^ ((0x78 >> (((lrow >> 2) & 3) * 2)) & 3);
;   const u16* ga = A + (size_t)(m0 + lrow) * lda + kbeg + lch * 8;
;   const u16* gb = Bt + (size_t)(n0 + lrow) * K + kbeg + lch * 8;
;   const size_t ga1 = (size_t)64 * lda, gb1 = (size_t)64 * K;
;   const unsigned lds0 = (unsigned)(uintptr_t)(LAS char*)smem + (unsigned)__builtin_amdgcn_readfirstlane(wid) * 1024u;
;     ...
;   __syncthreads();
;   G2_STAGE(0); G2_STAGE(1);
;   const int fsw = (0x78 >> (((r16 >> 2) & 3) * 2)) & 3;
;   const int aoff = (wm * 128 + r16) * 64 + ((quad ^ fsw) << 4);
;   const int boff = 16384 + (wn * 64 + r16) * 64 + ((quad ^ fsw) << 4);
	s_add_i32 s42, s46, 0x0
	s_mov_b32 m0, s42
	v_lshl_add_u64 v[142:143], v[132:133], 0, s[2:3]
	global_load_lds_dwordx4 v[132:133], off
	s_add_i32 m0, m0, 0x1000
	s_nop 0
	global_load_lds_dwordx4 v[142:143], off
	v_lshl_add_u64 v[142:143], v[142:143], 0, s[2:3]
	s_add_i32 m0, m0, 0x1000
	s_nop 0
	global_load_lds_dwordx4 v[142:143], off
	v_lshl_add_u64 v[142:143], v[142:143], 0, s[2:3]
	s_add_i32 m0, m0, 0x1000
	s_nop 0
	global_load_lds_dwordx4 v[142:143], off
	s_add_i32 m0, m0, 0x1000
	v_lshl_add_u64 v[142:143], v[134:135], 0, s[2:3]
	s_nop 0
	global_load_lds_dwordx4 v[134:135], off
	s_add_i32 m0, m0, 0x1000
	v_lshl_add_u64 v[132:133], v[132:133], 0, s[12:13]
	s_nop 0
	global_load_lds_dwordx4 v[142:143], off
	v_lshl_add_u64 v[134:135], v[134:135], 0, s[4:5]
	s_nop 0
	s_add_i32 s42, s46, 0x6000
	s_mov_b32 m0, s42
	v_lshl_add_u64 v[142:143], v[132:133], 0, s[2:3]
	global_load_lds_dwordx4 v[132:133], off
	s_add_i32 m0, m0, 0x1000
	s_nop 0
	global_load_lds_dwordx4 v[142:143], off
	v_lshl_add_u64 v[142:143], v[142:143], 0, s[2:3]
	s_add_i32 m0, m0, 0x1000
	s_nop 0
	global_load_lds_dwordx4 v[142:143], off
	v_lshl_add_u64 v[142:143], v[142:143], 0, s[2:3]
	s_add_i32 m0, m0, 0x1000
	s_nop 0
	global_load_lds_dwordx4 v[142:143], off
	s_add_i32 m0, m0, 0x1000
	v_lshl_add_u64 v[142:143], v[134:135], 0, s[2:3]
	s_nop 0
	global_load_lds_dwordx4 v[134:135], off
	s_add_i32 m0, m0, 0x1000
	v_lshl_add_u64 v[132:133], v[132:133], 0, s[12:13]
	s_nop 0
	global_load_lds_dwordx4 v[142:143], off
	v_lshl_add_u64 v[134:135], v[134:135], 0, s[4:5]
	s_nop 0
	s_add_i32 s42, s46, 0xc000
	s_mov_b32 m0, s42
	v_lshl_add_u64 v[142:143], v[132:133], 0, s[2:3]
	global_load_lds_dwordx4 v[132:133], off
	s_add_i32 m0, m0, 0x1000
	s_nop 0
	global_load_lds_dwordx4 v[142:143], off
	v_lshl_add_u64 v[142:143], v[142:143], 0, s[2:3]
	s_add_i32 m0, m0, 0x1000
	s_nop 0
	global_load_lds_dwordx4 v[142:143], off
	v_lshl_add_u64 v[142:143], v[142:143], 0, s[2:3]
	s_add_i32 m0, m0, 0x1000
	s_nop 0
	global_load_lds_dwordx4 v[142:143], off
	s_add_i32 m0, m0, 0x1000
	v_lshl_add_u64 v[142:143], v[134:135], 0, s[2:3]
	s_nop 0
	global_load_lds_dwordx4 v[134:135], off
	s_add_i32 m0, m0, 0x1000
	v_lshl_add_u64 v[132:133], v[132:133], 0, s[12:13]
	s_nop 0
	global_load_lds_dwordx4 v[142:143], off
	v_lshl_add_u64 v[134:135], v[134:135], 0, s[4:5]
	s_nop 0
	v_mov_b32_e32 v2, 0
	v_mov_b32_e32 v3, 0
	v_mov_b32_e32 v4, 0
	v_mov_b32_e32 v5, 0
	v_mov_b32_e32 v6, 0
	v_mov_b32_e32 v7, 0
	v_mov_b32_e32 v8, 0
	v_mov_b32_e32 v9, 0
	v_mov_b32_e32 v10, 0
	v_mov_b32_e32 v11, 0
	v_mov_b32_e32 v12, 0
	v_mov_b32_e32 v13, 0
	v_mov_b32_e32 v14, 0
	v_mov_b32_e32 v15, 0
	v_mov_b32_e32 v16, 0
	v_mov_b32_e32 v17, 0
	v_mov_b32_e32 v18, 0
	v_mov_b32_e32 v19, 0
	v_mov_b32_e32 v20, 0
	v_mov_b32_e32 v21, 0
	v_mov_b32_e32 v22, 0
	v_mov_b32_e32 v23, 0
	v_mov_b32_e32 v24, 0
	v_mov_b32_e32 v25, 0
	v_mov_b32_e32 v26, 0
	v_mov_b32_e32 v27, 0
	v_mov_b32_e32 v28, 0
	v_mov_b32_e32 v29, 0
	v_mov_b32_e32 v30, 0
	v_mov_b32_e32 v31, 0
	v_mov_b32_e32 v32, 0
	v_mov_b32_e32 v33, 0
	v_mov_b32_e32 v34, 0
	v_mov_b32_e32 v35, 0
	v_mov_b32_e32 v36, 0
	v_mov_b32_e32 v37, 0
	v_mov_b32_e32 v38, 0
	v_mov_b32_e32 v39, 0
	v_mov_b32_e32 v40, 0
	v_mov_b32_e32 v41, 0
	v_mov_b32_e32 v42, 0
	v_mov_b32_e32 v43, 0
	v_mov_b32_e32 v44, 0
	v_mov_b32_e32 v45, 0
	v_mov_b32_e32 v46, 0
	v_mov_b32_e32 v47, 0
	v_mov_b32_e32 v48, 0
	v_mov_b32_e32 v49, 0
	v_mov_b32_e32 v50, 0
	v_mov_b32_e32 v51, 0
	v_mov_b32_e32 v52, 0
	v_mov_b32_e32 v53, 0
	v_mov_b32_e32 v54, 0
	v_mov_b32_e32 v55, 0
	v_mov_b32_e32 v56, 0
	v_mov_b32_e32 v57, 0
	v_mov_b32_e32 v58, 0
	v_mov_b32_e32 v59, 0
	v_mov_b32_e32 v60, 0
	v_mov_b32_e32 v61, 0
	v_mov_b32_e32 v62, 0
	v_mov_b32_e32 v63, 0
	v_mov_b32_e32 v64, 0
	v_mov_b32_e32 v65, 0
	v_mov_b32_e32 v66, 0
	v_mov_b32_e32 v67, 0
	v_mov_b32_e32 v68, 0
	v_mov_b32_e32 v69, 0
	v_mov_b32_e32 v70, 0
	v_mov_b32_e32 v71, 0
	v_mov_b32_e32 v72, 0
	v_mov_b32_e32 v73, 0
	v_mov_b32_e32 v74, 0
	v_mov_b32_e32 v75, 0
	v_mov_b32_e32 v76, 0
	v_mov_b32_e32 v77, 0
	v_mov_b32_e32 v78, 0
	v_mov_b32_e32 v79, 0
	v_mov_b32_e32 v80, 0
	v_mov_b32_e32 v81, 0
	v_mov_b32_e32 v82, 0
	v_mov_b32_e32 v83, 0
	v_mov_b32_e32 v84, 0
	v_mov_b32_e32 v85, 0
	v_mov_b32_e32 v86, 0
	v_mov_b32_e32 v87, 0
	v_mov_b32_e32 v88, 0
	v_mov_b32_e32 v89, 0
	v_mov_b32_e32 v90, 0
	v_mov_b32_e32 v91, 0
	v_mov_b32_e32 v92, 0
	v_mov_b32_e32 v93, 0
	v_mov_b32_e32 v94, 0
	v_mov_b32_e32 v95, 0
	v_mov_b32_e32 v96, 0
	v_mov_b32_e32 v97, 0
	v_mov_b32_e32 v98, 0
	v_mov_b32_e32 v99, 0
	v_mov_b32_e32 v100, 0
	v_mov_b32_e32 v101, 0
	v_mov_b32_e32 v102, 0
	v_mov_b32_e32 v103, 0
	v_mov_b32_e32 v104, 0
	v_mov_b32_e32 v105, 0
	v_mov_b32_e32 v106, 0
	v_mov_b32_e32 v107, 0
	v_mov_b32_e32 v108, 0
	v_mov_b32_e32 v109, 0
	v_mov_b32_e32 v110, 0
	v_mov_b32_e32 v111, 0
	v_mov_b32_e32 v112, 0
	v_mov_b32_e32 v113, 0
	v_mov_b32_e32 v114, 0
	v_mov_b32_e32 v115, 0
	v_mov_b32_e32 v116, 0
	v_mov_b32_e32 v117, 0
	v_mov_b32_e32 v118, 0
	v_mov_b32_e32 v119, 0
	v_mov_b32_e32 v120, 0
	v_mov_b32_e32 v121, 0
	v_mov_b32_e32 v122, 0
	v_mov_b32_e32 v123, 0
	v_mov_b32_e32 v124, 0
	v_mov_b32_e32 v125, 0
	v_mov_b32_e32 v126, 0
	v_mov_b32_e32 v127, 0
	v_mov_b32_e32 v128, 0
	v_mov_b32_e32 v129, 0
	s_setprio 0
	s_waitcnt vmcnt(12)
	s_barrier
	ds_read_b128 v[146:149], v136 offset:0
	ds_read_b128 v[152:155], v136 offset:1024
	ds_read_b128 v[156:159], v136 offset:2048
	ds_read_b128 v[162:165], v136 offset:3072
	ds_read_b128 v[166:169], v136 offset:4096
	ds_read_b128 v[170:173], v136 offset:5120
	ds_read_b128 v[176:179], v136 offset:6144
	ds_read_b128 v[180:183], v136 offset:7168
	ds_read_b128 v[184:187], v137 offset:16384
	ds_read_b128 v[188:191], v137 offset:17408
	ds_read_b128 v[192:195], v137 offset:18432
	ds_read_b128 v[196:199], v137 offset:19456
	s_movk_i32 s40, 0x6000
	s_mov_b32 s41, 0
	s_movk_i32 s39, 2
	.p2align 6

; #define LAS __attribute__((address_space(3)))
; DEVI int tidx() { int t = threadIdx.x; asm volatile("" : "+v"(t)); return t; }
;   const int tid = tidx(), lane = tid & 63, wid = tid >> 6;
;   const int wm = wid >> 1, wn = wid & 1, r16 = lane & 15, quad = lane >> 4;
;   f32x4 acc[4][8];
; #pragma unroll
;   for (int i = 0; i < 4; i++)
; #pragma unroll
;     for (int j = 0; j < 8; j++) acc[i][j] = (f32x4){0.f, 0.f, 0.f, 0.f};
;   const int nk = (nk_part < 0) ? (K >> 5) : nk_part;
;   const int lrow = tid >> 2, lpc = tid & 3;
;   const int lch = lpc ^ ((0x78 >> (((lrow >> 2) & 3) * 2)) & 3);
;   const u16* ga = A + (size_t)(m0 + lrow) * lda + kbeg + lch * 8;
;   const u16* gb = Bt + (size_t)(n0 + lrow) * K + kbeg + lch * 8;
;   const size_t ga1 = (size_t)64 * lda, gb1 = (size_t)64 * K;
;   const unsigned lds0 = (unsigned)(uintptr_t)(LAS char*)smem + (unsigned)__builtin_amdgcn_readfirstlane(wid) * 1024u;
; DEVI void tile_coords(int T, int MT, int NT, int& mt, int& nt) {
;   const int full = MT >> 3, band = T / (8 * NT);
;   if (band < full) { const int r = T - band * 8 * NT; nt = r >> 3; mt = band * 8 + (r & 7); }
.LBB0_116:
	s_and_b64 vcc, exec, s[2:3]
	s_cbranch_vccz .LBB0_41
	s_setprio 2
	v_readlane_b32 s39, v250, 7
	s_cmpk_lg_u32 s39, 0x200
	s_cbranch_scc1 .Lt11_go
	v_readlane_b32 s40, v255, 41
	s_cmp_lg_u32 s40, 0
	s_cbranch_scc1 .Lt11_go
	v_readlane_b32 s40, v250, 0
	s_lshr_b32 s41, s40, 3
	s_cmp_lt_u32 s41, 22
	s_cbranch_scc0 .Lt11_go
	s_and_b32 s40, s40, 7
	s_mul_i32 s40, s40, 22
	s_add_i32 s38, s40, s41
	s_branch .LBB0_41
.Lt11_go:
	s_lshr_b32 s45, s38, 6
	s_and_b32 s46, s38, 63
	s_lshr_b32 s42, s46, 3
	s_and_b32 s46, s46, 7
	s_lshl_b32 s45, s45, 3
	s_add_i32 s45, s45, s46
	s_cmp_lt_u32 s45, 64
	s_cselect_b32 s44, 1, 0
	v_readlane_b32 s2, v250, 5
	v_readlane_b32 s3, v250, 6
	v_readlane_b32 s46, v254, 62
	s_mul_i32 s40, s45, 0x160000
	s_add_u32 s4, s2, s40
	s_addc_u32 s5, s3, 0
	s_add_u32 s4, s4, 0xef40000
	s_addc_u32 s5, s5, 0
	s_mul_i32 s40, s46, 0x580000
	s_mul_i32 s41, s42, 0xb0000
	s_add_i32 s40, s40, s41
	s_add_u32 s10, s2, s40
	s_addc_u32 s11, s3, 0
	s_add_u32 s10, s10, 0x19a00000
	s_addc_u32 s11, s11, 0
	s_movk_i32 s39, 0x78
	v_lshrrev_b32_e32 v0, 2, v145
	v_and_b32_e32 v131, 3, v145
	v_bfe_u32 v136, v145, 4, 2
	v_lshlrev_b32_e32 v136, 1, v136
	v_lshrrev_b32_e64 v136, v136, s39
	v_and_b32_e32 v136, 3, v136
	v_xor_b32_e32 v131, v131, v136
	v_lshlrev_b32_e32 v131, 4, v131
	s_movk_i32 s41, 0x1600
	v_mad_u32_u24 v0, v0, s41, v131
	v_bfe_u32 v137, v145, 2, 1
	s_movk_i32 s41, 0x15c0
	v_mul_u32_u24_e32 v136, s41, v137
	v_sub_u32_e32 v136, v0, v136
	v_mov_b32_e32 v137, 0
	v_lshl_add_u64 v[134:135], s[10:11], 0, v[136:137]
	v_bfe_u32 v137, v145, 2, 1
	s_mul_i32 s41, s44, 0x15c0
	v_mul_u32_u24_e32 v136, s41, v137
	v_sub_u32_e32 v0, v0, v136
	s_lshl_b32 s12, s44, 6
	s_add_i32 s12, s12, 64
	s_mov_b32 s13, 0
	v_lshl_add_u64 v[132:133], s[4:5], 0, v[0:1]
	v_bfe_u32 v136, v145, 2, 2
	v_lshlrev_b32_e32 v136, 1, v136
	v_lshrrev_b32_e64 v136, v136, s39
	v_and_b32_e32 v136, 3, v136
	v_bfe_u32 v137, v145, 4, 2
	v_xor_b32_e32 v136, v136, v137
	v_lshlrev_b32_e32 v136, 4, v136
	v_and_b32_e32 v131, 15, v145
	v_lshl_or_b32 v136, v131, 6, v136
	v_bfe_u32 v137, v145, 6, 1
	v_lshl_or_b32 v137, v137, 12, v136
	v_lshrrev_b32_e32 v0, 7, v145
	v_lshl_or_b32 v136, v0, 13, v136
	v_and_b32_e32 v140, 1, v131
	v_lshl_or_b32 v131, v0, 7, v131
	v_bfe_u32 v0, v145, 4, 2
	v_lshlrev_b32_e32 v0, 3, v0
	v_bfe_u32 v141, v145, 6, 1
	s_lshl_b32 s40, s45, 19
	s_lshl_b32 s41, s42, 9
	s_add_i32 s40, s40, s41
	s_add_u32 s4, s2, s40
	s_addc_u32 s5, s3, 0
	s_add_u32 s4, s4, 0x4200000
	s_addc_u32 s5, s5, 0
	v_lshlrev_b32_e32 v138, 11, v131
	v_lshl_add_u32 v138, v141, 8, v138
	v_bfe_u32 v139, v145, 4, 1
	v_lshl_add_u32 v138, v139, 5, v138
	v_bfe_u32 v139, v145, 5, 1
	v_lshl_add_u32 v138, v139, 4, v138
	s_movk_i32 s41, 1984
	v_mul_u32_u24_e32 v139, s41, v140
	v_sub_u32_e32 v138, v138, v139
	v_mov_b32_e32 v139, 0
	v_lshl_add_u64 v[138:139], s[4:5], 0, v[138:139]
	s_lshl_b32 s40, s45, 20
	s_lshl_b32 s41, s42, 9
	s_add_i32 s40, s40, s41
	s_add_u32 s10, s2, s40
	s_addc_u32 s11, s3, 0
	v_lshlrev_b32_e32 v140, 12, v131
	v_lshl_add_u32 v140, v141, 8, v140
	v_lshl_add_u32 v140, v0, 1, v140
	v_mov_b32_e32 v141, 0
	v_lshl_add_u64 v[140:141], s[10:11], 0, v[140:141]
	s_mov_b32 s2, 0x58000
	s_mov_b32 s3, 0
	v_lshrrev_b32_e32 v0, 6, v145
	v_lshlrev_b32_e32 v0, 10, v0
	s_nop 0
	v_readfirstlane_b32 s46, v0
	s_mov_b32 s43, m0
	s_mov_b32 s4, 128
	s_mov_b32 s5, 0
	s_barrier
; #define LAS __attribute__((address_space(3)))
;     ...
;   f32x4 acc[4][8];
; #pragma unroll
;   for (int i = 0; i < 4; i++)
; #pragma unroll
;     for (int j = 0; j < 8; j++) acc[i][j] = (f32x4){0.f, 0.f, 0.f, 0.f};
;   const int nk = (nk_part < 0) ? (K >> 5) : nk_part;
;   const int lrow = tid >> 2, lpc = tid & 3;
;   const int lch = lpc ^ ((0x78 >> (((lrow >> 2) & 3) * 2)) & 3);
;   const u16* ga = A + (size_t)(m0 + lrow) * lda + kbeg + lch * 8;
;   const u16* gb = Bt + (size_t)(n0 + lrow) * K + kbeg + lch * 8;
;   const size_t ga1 = (size_t)64 * lda, gb1 = (size_t)64 * K;
;   const unsigned lds0 = (unsigned)(uintptr_t)(LAS char*)smem + (unsigned)__builtin_amdgcn_readfirstlane(wid) * 1024u;
;     ...
;   __syncthreads();
;   G2_STAGE(0); G2_STAGE(1);
;   const int fsw = (0x78 >> (((r16 >> 2) & 3) * 2)) & 3;
;   const int aoff = (wm * 128 + r16) * 64 + ((quad ^ fsw) << 4);
;   const int boff = 16384 + (wn * 64 + r16) * 64 + ((quad ^ fsw) << 4);
;   for (int kt = 0; kt < nk; kt++) {
;     if (kt + 1 < nk) asm volatile("s_waitcnt vmcnt(6)" ::: "memory");
;     else asm volatile("s_waitcnt vmcnt(0)" ::: "memory");
;     __builtin_amdgcn_s_barrier();
;     asm volatile("" ::: "memory");
;     if (kt + 2 < nk) G2_STAGE(kt + 2);
;     const char* cS = smem + (kt % 3) * 24576;
;     bf16x8 xa[8], wb[4];
; #pragma unroll
;     for (int f = 0; f < 8; f++) xa[f] = *(const bf16x8*)(cS + aoff + f * 1024);
; #pragma unroll
;     for (int f = 0; f < 4; f++) wb[f] = *(const bf16x8*)(cS + boff + f * 1024);
	s_add_i32 s42, s46, 0x0
	s_mov_b32 m0, s42
	v_lshl_add_u64 v[142:143], v[132:133], 0, s[2:3]
	global_load_lds_dwordx4 v[132:133], off
	s_add_i32 m0, m0, 0x1000
	s_nop 0
	global_load_lds_dwordx4 v[142:143], off
	v_lshl_add_u64 v[142:143], v[142:143], 0, s[2:3]
	s_add_i32 m0, m0, 0x1000
	s_nop 0
	global_load_lds_dwordx4 v[142:143], off
	v_lshl_add_u64 v[142:143], v[142:143], 0, s[2:3]
	s_add_i32 m0, m0, 0x1000
	s_nop 0
	global_load_lds_dwordx4 v[142:143], off
	s_add_i32 m0, m0, 0x1000
	v_lshl_add_u64 v[142:143], v[134:135], 0, s[2:3]
	s_nop 0
	global_load_lds_dwordx4 v[134:135], off
	s_add_i32 m0, m0, 0x1000
	v_lshl_add_u64 v[132:133], v[132:133], 0, s[12:13]
	s_nop 0
	global_load_lds_dwordx4 v[142:143], off
	v_lshl_add_u64 v[134:135], v[134:135], 0, s[4:5]
	s_nop 0
	s_add_i32 s42, s46, 0x6000
	s_mov_b32 m0, s42
	v_lshl_add_u64 v[142:143], v[132:133], 0, s[2:3]
	global_load_lds_dwordx4 v[132:133], off
	s_add_i32 m0, m0, 0x1000
	s_nop 0
	global_load_lds_dwordx4 v[142:143], off
	v_lshl_add_u64 v[142:143], v[142:143], 0, s[2:3]
	s_add_i32 m0, m0, 0x1000
	s_nop 0
	global_load_lds_dwordx4 v[142:143], off
	v_lshl_add_u64 v[142:143], v[142:143], 0, s[2:3]
	s_add_i32 m0, m0, 0x1000
	s_nop 0
	global_load_lds_dwordx4 v[142:143], off
	s_add_i32 m0, m0, 0x1000
	v_lshl_add_u64 v[142:143], v[134:135], 0, s[2:3]
	s_nop 0
	global_load_lds_dwordx4 v[134:135], off
	s_add_i32 m0, m0, 0x1000
	v_lshl_add_u64 v[132:133], v[132:133], 0, s[12:13]
	s_nop 0
	global_load_lds_dwordx4 v[142:143], off
	v_lshl_add_u64 v[134:135], v[134:135], 0, s[4:5]
	s_nop 0
	s_add_i32 s42, s46, 0xc000
	s_mov_b32 m0, s42
	v_lshl_add_u64 v[142:143], v[132:133], 0, s[2:3]
	global_load_lds_dwordx4 v[132:133], off
	s_add_i32 m0, m0, 0x1000
	s_nop 0
	global_load_lds_dwordx4 v[142:143], off
	v_lshl_add_u64 v[142:143], v[142:143], 0, s[2:3]
	s_add_i32 m0, m0, 0x1000
	s_nop 0
	global_load_lds_dwordx4 v[142:143], off
	v_lshl_add_u64 v[142:143], v[142:143], 0, s[2:3]
	s_add_i32 m0, m0, 0x1000
	s_nop 0
	global_load_lds_dwordx4 v[142:143], off
	s_add_i32 m0, m0, 0x1000
	v_lshl_add_u64 v[142:143], v[134:135], 0, s[2:3]
	s_nop 0
	global_load_lds_dwordx4 v[134:135], off
	s_add_i32 m0, m0, 0x1000
	v_lshl_add_u64 v[132:133], v[132:133], 0, s[12:13]
	s_nop 0
	global_load_lds_dwordx4 v[142:143], off
	v_lshl_add_u64 v[134:135], v[134:135], 0, s[4:5]
	s_nop 0
	v_mov_b32_e32 v2, 0
	v_mov_b32_e32 v3, 0
	v_mov_b32_e32 v4, 0
	v_mov_b32_e32 v5, 0
	v_mov_b32_e32 v6, 0
	v_mov_b32_e32 v7, 0
	v_mov_b32_e32 v8, 0
	v_mov_b32_e32 v9, 0
	v_mov_b32_e32 v10, 0
	v_mov_b32_e32 v11, 0
	v_mov_b32_e32 v12, 0
	v_mov_b32_e32 v13, 0
	v_mov_b32_e32 v14, 0
	v_mov_b32_e32 v15, 0
	v_mov_b32_e32 v16, 0
	v_mov_b32_e32 v17, 0
	v_mov_b32_e32 v18, 0
	v_mov_b32_e32 v19, 0
	v_mov_b32_e32 v20, 0
	v_mov_b32_e32 v21, 0
	v_mov_b32_e32 v22, 0
	v_mov_b32_e32 v23, 0
	v_mov_b32_e32 v24, 0
	v_mov_b32_e32 v25, 0
	v_mov_b32_e32 v26, 0
	v_mov_b32_e32 v27, 0
	v_mov_b32_e32 v28, 0
	v_mov_b32_e32 v29, 0
	v_mov_b32_e32 v30, 0
	v_mov_b32_e32 v31, 0
	v_mov_b32_e32 v32, 0
	v_mov_b32_e32 v33, 0
	v_mov_b32_e32 v34, 0
	v_mov_b32_e32 v35, 0
	v_mov_b32_e32 v36, 0
	v_mov_b32_e32 v37, 0
	v_mov_b32_e32 v38, 0
	v_mov_b32_e32 v39, 0
	v_mov_b32_e32 v40, 0
	v_mov_b32_e32 v41, 0
	v_mov_b32_e32 v42, 0
	v_mov_b32_e32 v43, 0
	v_mov_b32_e32 v44, 0
	v_mov_b32_e32 v45, 0
	v_mov_b32_e32 v46, 0
	v_mov_b32_e32 v47, 0
	v_mov_b32_e32 v48, 0
	v_mov_b32_e32 v49, 0
	v_mov_b32_e32 v50, 0
	v_mov_b32_e32 v51, 0
	v_mov_b32_e32 v52, 0
	v_mov_b32_e32 v53, 0
	v_mov_b32_e32 v54, 0
	v_mov_b32_e32 v55, 0
	v_mov_b32_e32 v56, 0
	v_mov_b32_e32 v57, 0
	v_mov_b32_e32 v58, 0
	v_mov_b32_e32 v59, 0
	v_mov_b32_e32 v60, 0
	v_mov_b32_e32 v61, 0
	v_mov_b32_e32 v62, 0
	v_mov_b32_e32 v63, 0
	v_mov_b32_e32 v64, 0
	v_mov_b32_e32 v65, 0
	v_mov_b32_e32 v66, 0
	v_mov_b32_e32 v67, 0
	v_mov_b32_e32 v68, 0
	v_mov_b32_e32 v69, 0
	v_mov_b32_e32 v70, 0
	v_mov_b32_e32 v71, 0
	v_mov_b32_e32 v72, 0
	v_mov_b32_e32 v73, 0
	v_mov_b32_e32 v74, 0
	v_mov_b32_e32 v75, 0
	v_mov_b32_e32 v76, 0
	v_mov_b32_e32 v77, 0
	v_mov_b32_e32 v78, 0
	v_mov_b32_e32 v79, 0
	v_mov_b32_e32 v80, 0
	v_mov_b32_e32 v81, 0
	v_mov_b32_e32 v82, 0
	v_mov_b32_e32 v83, 0
	v_mov_b32_e32 v84, 0
	v_mov_b32_e32 v85, 0
	v_mov_b32_e32 v86, 0
	v_mov_b32_e32 v87, 0
	v_mov_b32_e32 v88, 0
	v_mov_b32_e32 v89, 0
	v_mov_b32_e32 v90, 0
	v_mov_b32_e32 v91, 0
	v_mov_b32_e32 v92, 0
	v_mov_b32_e32 v93, 0
	v_mov_b32_e32 v94, 0
	v_mov_b32_e32 v95, 0
	v_mov_b32_e32 v96, 0
	v_mov_b32_e32 v97, 0
	v_mov_b32_e32 v98, 0
	v_mov_b32_e32 v99, 0
	v_mov_b32_e32 v100, 0
	v_mov_b32_e32 v101, 0
	v_mov_b32_e32 v102, 0
	v_mov_b32_e32 v103, 0
	v_mov_b32_e32 v104, 0
	v_mov_b32_e32 v105, 0
	v_mov_b32_e32 v106, 0
	v_mov_b32_e32 v107, 0
	v_mov_b32_e32 v108, 0
	v_mov_b32_e32 v109, 0
	v_mov_b32_e32 v110, 0
	v_mov_b32_e32 v111, 0
	v_mov_b32_e32 v112, 0
	v_mov_b32_e32 v113, 0
	v_mov_b32_e32 v114, 0
	v_mov_b32_e32 v115, 0
	v_mov_b32_e32 v116, 0
	v_mov_b32_e32 v117, 0
	v_mov_b32_e32 v118, 0
	v_mov_b32_e32 v119, 0
	v_mov_b32_e32 v120, 0
	v_mov_b32_e32 v121, 0
	v_mov_b32_e32 v122, 0
	v_mov_b32_e32 v123, 0
	v_mov_b32_e32 v124, 0
	v_mov_b32_e32 v125, 0
	v_mov_b32_e32 v126, 0
	v_mov_b32_e32 v127, 0
	v_mov_b32_e32 v128, 0
	v_mov_b32_e32 v129, 0
	s_setprio 0
	s_waitcnt vmcnt(12)
	s_barrier
	ds_read_b128 v[146:149], v136 offset:0
	ds_read_b128 v[152:155], v136 offset:1024
	ds_read_b128 v[156:159], v136 offset:2048
	ds_read_b128 v[162:165], v136 offset:3072
	ds_read_b128 v[166:169], v136 offset:4096
	ds_read_b128 v[170:173], v136 offset:5120
	ds_read_b128 v[176:179], v136 offset:6144
	ds_read_b128 v[180:183], v136 offset:7168
	ds_read_b128 v[184:187], v137 offset:16384
	ds_read_b128 v[188:191], v137 offset:17408
	ds_read_b128 v[192:195], v137 offset:18432
	ds_read_b128 v[196:199], v137 offset:19456
	s_movk_i32 s40, 0x6000
	s_mov_b32 s41, 0
	s_movk_i32 s39, 42
	.p2align 6

; DEVI void tile_coords(int T, int MT, int NT, int& mt, int& nt) {
;   const int full = MT >> 3, band = T / (8 * NT);
;   if (band < full) { const int r = T - band * 8 * NT; nt = r >> 3; mt = band * 8 + (r & 7); }
;   else { const int MB = MT - full * 8; const int r = T - full * 8 * NT; nt = r / MB; mt = full * 8 + r % MB; }
; }
.LBB0_124:
	s_setprio 2
	s_lshr_b32 s41, s8, 5
	s_mul_i32 s41, s41, 187
	s_lshr_b32 s41, s41, 11
	s_cmp_lt_u32 s41, 8
	s_cbranch_scc0 .Lt10_rem
	s_mul_i32 s43, s41, 352
	s_sub_i32 s43, s8, s43
	s_lshr_b32 s38, s43, 3
	s_and_b32 s43, s43, 7
	s_lshl_b32 s41, s41, 3
	s_add_i32 s41, s41, s43
	s_branch .Lt10_crd

; #define LAS __attribute__((address_space(3)))
; DEVI int tidx() { int t = threadIdx.x; asm volatile("" : "+v"(t)); return t; }
;   const int tid = tidx(), lane = tid & 63, wid = tid >> 6;
;   const int wm = wid >> 1, wn = wid & 1, r16 = lane & 15, quad = lane >> 4;
;   f32x4 acc[4][8];
; #pragma unroll
;   for (int i = 0; i < 4; i++)
; #pragma unroll
;     for (int j = 0; j < 8; j++) acc[i][j] = (f32x4){0.f, 0.f, 0.f, 0.f};
;   const int nk = (nk_part < 0) ? (K >> 5) : nk_part;
;   const int lrow = tid >> 2, lpc = tid & 3;
;   const int lch = lpc ^ ((0x78 >> (((lrow >> 2) & 3) * 2)) & 3);
;   const u16* ga = A + (size_t)(m0 + lrow) * lda + kbeg + lch * 8;
;   const u16* gb = Bt + (size_t)(n0 + lrow) * K + kbeg + lch * 8;
;   const size_t ga1 = (size_t)64 * lda, gb1 = (size_t)64 * K;
;   const unsigned lds0 = (unsigned)(uintptr_t)(LAS char*)smem + (unsigned)__builtin_amdgcn_readfirstlane(wid) * 1024u;
.Lt10_crd:
	s_cmp_lt_u32 s41, 64
	s_cselect_b32 s40, 1, 0
	v_readlane_b32 s2, v250, 5
	v_readlane_b32 s3, v250, 6
	v_readlane_b32 s43, v254, 62
	s_mul_i32 s36, s41, 0x80000
	s_add_u32 s10, s2, s36
	s_addc_u32 s11, s3, 0
	s_add_u32 s10, s10, 0x4200000
	s_addc_u32 s11, s11, 0
	s_mul_i32 s36, s43, 0xb00000
	s_mul_i32 s37, s38, 0x40000
	s_add_i32 s36, s36, s37
	s_add_u32 s12, s2, s36
	s_addc_u32 s13, s3, 0
	s_add_u32 s12, s12, 0x16e00000
	s_addc_u32 s13, s13, 0
	s_movk_i32 s9, 0x78
	v_lshrrev_b32_e32 v0, 2, v145
	v_and_b32_e32 v131, 3, v145
	v_bfe_u32 v136, v145, 4, 2
	v_lshlrev_b32_e32 v136, 1, v136
	v_lshrrev_b32_e64 v136, v136, s9
	v_and_b32_e32 v136, 3, v136
	v_xor_b32_e32 v131, v131, v136
	v_lshlrev_b32_e32 v131, 4, v131
	s_movk_i32 s37, 0x800
	v_mad_u32_u24 v0, v0, s37, v131
	v_bfe_u32 v137, v145, 2, 1
	s_movk_i32 s37, 0x7c0
	v_mul_u32_u24_e32 v136, s37, v137
	v_sub_u32_e32 v136, v0, v136
	v_mov_b32_e32 v137, 0
	v_lshl_add_u64 v[134:135], s[12:13], 0, v[136:137]
	v_bfe_u32 v137, v145, 2, 1
	s_mul_i32 s37, s40, 0x7c0
	v_mul_u32_u24_e32 v136, s37, v137
	v_sub_u32_e32 v0, v0, v136
	s_lshl_b32 s14, s40, 6
	s_add_i32 s14, s14, 64
	s_mov_b32 s15, 0
	v_lshl_add_u64 v[132:133], s[10:11], 0, v[0:1]
	v_bfe_u32 v136, v145, 2, 2
	v_lshlrev_b32_e32 v136, 1, v136
	v_lshrrev_b32_e64 v136, v136, s9
	v_and_b32_e32 v136, 3, v136
	v_bfe_u32 v137, v145, 4, 2
	v_xor_b32_e32 v136, v136, v137
	v_lshlrev_b32_e32 v136, 4, v136
	v_and_b32_e32 v131, 15, v145
	v_lshl_or_b32 v136, v131, 6, v136
	v_bfe_u32 v137, v145, 6, 1
	v_lshl_or_b32 v137, v137, 12, v136
	v_lshrrev_b32_e32 v0, 7, v145
	v_lshl_or_b32 v136, v0, 13, v136
	v_and_b32_e32 v140, 1, v131
	v_lshl_or_b32 v131, v0, 7, v131
	v_bfe_u32 v0, v145, 4, 1
	v_lshlrev_b32_e32 v0, 5, v0
	v_bfe_u32 v141, v145, 5, 1
	v_lshl_or_b32 v0, v141, 4, v0
	v_bfe_u32 v141, v145, 6, 1
	s_mul_i32 s36, s41, 0x160000
	s_lshl_b32 s37, s38, 7
	s_lshl_b32 s37, s37, s40
	s_add_i32 s36, s36, s37
	s_add_u32 s12, s2, s36
	s_addc_u32 s13, s3, 0
	s_add_u32 s12, s12, 0xef40000
	s_addc_u32 s13, s13, 0
	s_movk_i32 s37, 5632
	v_mad_u32_u24 v138, v131, s37, v0
	v_lshlrev_b32_e32 v139, 6, v141
	v_lshlrev_b32_e64 v139, s40, v139
	v_add_u32_e32 v138, v138, v139
	s_mul_i32 s37, s40, 5568
	v_mul_u32_u24_e32 v139, s37, v140
	v_sub_u32_e32 v138, v138, v139
	v_mov_b32_e32 v139, 0
	v_lshl_add_u64 v[140:141], s[12:13], 0, v[138:139]
	s_mov_b32 s2, 0x20000
	s_mov_b32 s3, 0
	v_lshrrev_b32_e32 v0, 6, v145
	v_lshlrev_b32_e32 v0, 10, v0
	s_nop 0
	v_readfirstlane_b32 s43, v0
	s_mov_b32 s39, m0
	s_mov_b32 s10, 128
	s_mov_b32 s11, 0
	s_barrier
; #define LAS __attribute__((address_space(3)))
;     ...
;   f32x4 acc[4][8];
; #pragma unroll
;   for (int i = 0; i < 4; i++)
; #pragma unroll
;     for (int j = 0; j < 8; j++) acc[i][j] = (f32x4){0.f, 0.f, 0.f, 0.f};
;   const int nk = (nk_part < 0) ? (K >> 5) : nk_part;
;   const int lrow = tid >> 2, lpc = tid & 3;
;   const int lch = lpc ^ ((0x78 >> (((lrow >> 2) & 3) * 2)) & 3);
;   const u16* ga = A + (size_t)(m0 + lrow) * lda + kbeg + lch * 8;
;   const u16* gb = Bt + (size_t)(n0 + lrow) * K + kbeg + lch * 8;
;   const size_t ga1 = (size_t)64 * lda, gb1 = (size_t)64 * K;
;   const unsigned lds0 = (unsigned)(uintptr_t)(LAS char*)smem + (unsigned)__builtin_amdgcn_readfirstlane(wid) * 1024u;
;     ...
;   __syncthreads();
;   G2_STAGE(0); G2_STAGE(1);
;   const int fsw = (0x78 >> (((r16 >> 2) & 3) * 2)) & 3;
;   const int aoff = (wm * 128 + r16) * 64 + ((quad ^ fsw) << 4);
;   const int boff = 16384 + (wn * 64 + r16) * 64 + ((quad ^ fsw) << 4);
;   for (int kt = 0; kt < nk; kt++) {
;     if (kt + 1 < nk) asm volatile("s_waitcnt vmcnt(6)" ::: "memory");
;     else asm volatile("s_waitcnt vmcnt(0)" ::: "memory");
;     __builtin_amdgcn_s_barrier();
;     asm volatile("" ::: "memory");
;     if (kt + 2 < nk) G2_STAGE(kt + 2);
;     const char* cS = smem + (kt % 3) * 24576;
;     bf16x8 xa[8], wb[4];
; #pragma unroll
;     for (int f = 0; f < 8; f++) xa[f] = *(const bf16x8*)(cS + aoff + f * 1024);
; #pragma unroll
;     for (int f = 0; f < 4; f++) wb[f] = *(const bf16x8*)(cS + boff + f * 1024);
	s_add_i32 s38, s43, 0x0
	s_mov_b32 m0, s38
	v_lshl_add_u64 v[142:143], v[132:133], 0, s[2:3]
	global_load_lds_dwordx4 v[132:133], off
	s_add_i32 m0, m0, 0x1000
	s_nop 0
	global_load_lds_dwordx4 v[142:143], off
	v_lshl_add_u64 v[142:143], v[142:143], 0, s[2:3]
	s_add_i32 m0, m0, 0x1000
	s_nop 0
	global_load_lds_dwordx4 v[142:143], off
	v_lshl_add_u64 v[142:143], v[142:143], 0, s[2:3]
	s_add_i32 m0, m0, 0x1000
	s_nop 0
	global_load_lds_dwordx4 v[142:143], off
	s_add_i32 m0, m0, 0x1000
	v_lshl_add_u64 v[142:143], v[134:135], 0, s[2:3]
	s_nop 0
	global_load_lds_dwordx4 v[134:135], off
	s_add_i32 m0, m0, 0x1000
	v_lshl_add_u64 v[132:133], v[132:133], 0, s[14:15]
	s_nop 0
	global_load_lds_dwordx4 v[142:143], off
	v_lshl_add_u64 v[134:135], v[134:135], 0, s[10:11]
	s_nop 0
	s_add_i32 s38, s43, 0x6000
	s_mov_b32 m0, s38
	v_lshl_add_u64 v[142:143], v[132:133], 0, s[2:3]
	global_load_lds_dwordx4 v[132:133], off
	s_add_i32 m0, m0, 0x1000
	s_nop 0
	global_load_lds_dwordx4 v[142:143], off
	v_lshl_add_u64 v[142:143], v[142:143], 0, s[2:3]
	s_add_i32 m0, m0, 0x1000
	s_nop 0
	global_load_lds_dwordx4 v[142:143], off
	v_lshl_add_u64 v[142:143], v[142:143], 0, s[2:3]
	s_add_i32 m0, m0, 0x1000
	s_nop 0
	global_load_lds_dwordx4 v[142:143], off
	s_add_i32 m0, m0, 0x1000
	v_lshl_add_u64 v[142:143], v[134:135], 0, s[2:3]
	s_nop 0
	global_load_lds_dwordx4 v[134:135], off
	s_add_i32 m0, m0, 0x1000
	v_lshl_add_u64 v[132:133], v[132:133], 0, s[14:15]
	s_nop 0
	global_load_lds_dwordx4 v[142:143], off
	v_lshl_add_u64 v[134:135], v[134:135], 0, s[10:11]
	s_nop 0
	s_add_i32 s38, s43, 0xc000
	s_mov_b32 m0, s38
	v_lshl_add_u64 v[142:143], v[132:133], 0, s[2:3]
	global_load_lds_dwordx4 v[132:133], off
	s_add_i32 m0, m0, 0x1000
	s_nop 0
	global_load_lds_dwordx4 v[142:143], off
	v_lshl_add_u64 v[142:143], v[142:143], 0, s[2:3]
	s_add_i32 m0, m0, 0x1000
	s_nop 0
	global_load_lds_dwordx4 v[142:143], off
	v_lshl_add_u64 v[142:143], v[142:143], 0, s[2:3]
	s_add_i32 m0, m0, 0x1000
	s_nop 0
	global_load_lds_dwordx4 v[142:143], off
	s_add_i32 m0, m0, 0x1000
	v_lshl_add_u64 v[142:143], v[134:135], 0, s[2:3]
	s_nop 0
	global_load_lds_dwordx4 v[134:135], off
	s_add_i32 m0, m0, 0x1000
	v_lshl_add_u64 v[132:133], v[132:133], 0, s[14:15]
	s_nop 0
	global_load_lds_dwordx4 v[142:143], off
	v_lshl_add_u64 v[134:135], v[134:135], 0, s[10:11]
	s_nop 0
	v_mov_b32_e32 v2, 0
	v_mov_b32_e32 v3, 0
	v_mov_b32_e32 v4, 0
	v_mov_b32_e32 v5, 0
	v_mov_b32_e32 v6, 0
	v_mov_b32_e32 v7, 0
	v_mov_b32_e32 v8, 0
	v_mov_b32_e32 v9, 0
	v_mov_b32_e32 v10, 0
	v_mov_b32_e32 v11, 0
	v_mov_b32_e32 v12, 0
	v_mov_b32_e32 v13, 0
	v_mov_b32_e32 v14, 0
	v_mov_b32_e32 v15, 0
	v_mov_b32_e32 v16, 0
	v_mov_b32_e32 v17, 0
	v_mov_b32_e32 v18, 0
	v_mov_b32_e32 v19, 0
	v_mov_b32_e32 v20, 0
	v_mov_b32_e32 v21, 0
	v_mov_b32_e32 v22, 0
	v_mov_b32_e32 v23, 0
	v_mov_b32_e32 v24, 0
	v_mov_b32_e32 v25, 0
	v_mov_b32_e32 v26, 0
	v_mov_b32_e32 v27, 0
	v_mov_b32_e32 v28, 0
	v_mov_b32_e32 v29, 0
	v_mov_b32_e32 v30, 0
	v_mov_b32_e32 v31, 0
	v_mov_b32_e32 v32, 0
	v_mov_b32_e32 v33, 0
	v_mov_b32_e32 v34, 0
	v_mov_b32_e32 v35, 0
	v_mov_b32_e32 v36, 0
	v_mov_b32_e32 v37, 0
	v_mov_b32_e32 v38, 0
	v_mov_b32_e32 v39, 0
	v_mov_b32_e32 v40, 0
	v_mov_b32_e32 v41, 0
	v_mov_b32_e32 v42, 0
	v_mov_b32_e32 v43, 0
	v_mov_b32_e32 v44, 0
	v_mov_b32_e32 v45, 0
	v_mov_b32_e32 v46, 0
	v_mov_b32_e32 v47, 0
	v_mov_b32_e32 v48, 0
	v_mov_b32_e32 v49, 0
	v_mov_b32_e32 v50, 0
	v_mov_b32_e32 v51, 0
	v_mov_b32_e32 v52, 0
	v_mov_b32_e32 v53, 0
	v_mov_b32_e32 v54, 0
	v_mov_b32_e32 v55, 0
	v_mov_b32_e32 v56, 0
	v_mov_b32_e32 v57, 0
	v_mov_b32_e32 v58, 0
	v_mov_b32_e32 v59, 0
	v_mov_b32_e32 v60, 0
	v_mov_b32_e32 v61, 0
	v_mov_b32_e32 v62, 0
	v_mov_b32_e32 v63, 0
	v_mov_b32_e32 v64, 0
	v_mov_b32_e32 v65, 0
	v_mov_b32_e32 v66, 0
	v_mov_b32_e32 v67, 0
	v_mov_b32_e32 v68, 0
	v_mov_b32_e32 v69, 0
	v_mov_b32_e32 v70, 0
	v_mov_b32_e32 v71, 0
	v_mov_b32_e32 v72, 0
	v_mov_b32_e32 v73, 0
	v_mov_b32_e32 v74, 0
	v_mov_b32_e32 v75, 0
	v_mov_b32_e32 v76, 0
	v_mov_b32_e32 v77, 0
	v_mov_b32_e32 v78, 0
	v_mov_b32_e32 v79, 0
	v_mov_b32_e32 v80, 0
	v_mov_b32_e32 v81, 0
	v_mov_b32_e32 v82, 0
	v_mov_b32_e32 v83, 0
	v_mov_b32_e32 v84, 0
	v_mov_b32_e32 v85, 0
	v_mov_b32_e32 v86, 0
	v_mov_b32_e32 v87, 0
	v_mov_b32_e32 v88, 0
	v_mov_b32_e32 v89, 0
	v_mov_b32_e32 v90, 0
	v_mov_b32_e32 v91, 0
	v_mov_b32_e32 v92, 0
	v_mov_b32_e32 v93, 0
	v_mov_b32_e32 v94, 0
	v_mov_b32_e32 v95, 0
	v_mov_b32_e32 v96, 0
	v_mov_b32_e32 v97, 0
	v_mov_b32_e32 v98, 0
	v_mov_b32_e32 v99, 0
	v_mov_b32_e32 v100, 0
	v_mov_b32_e32 v101, 0
	v_mov_b32_e32 v102, 0
	v_mov_b32_e32 v103, 0
	v_mov_b32_e32 v104, 0
	v_mov_b32_e32 v105, 0
	v_mov_b32_e32 v106, 0
	v_mov_b32_e32 v107, 0
	v_mov_b32_e32 v108, 0
	v_mov_b32_e32 v109, 0
	v_mov_b32_e32 v110, 0
	v_mov_b32_e32 v111, 0
	v_mov_b32_e32 v112, 0
	v_mov_b32_e32 v113, 0
	v_mov_b32_e32 v114, 0
	v_mov_b32_e32 v115, 0
	v_mov_b32_e32 v116, 0
	v_mov_b32_e32 v117, 0
	v_mov_b32_e32 v118, 0
	v_mov_b32_e32 v119, 0
	v_mov_b32_e32 v120, 0
	v_mov_b32_e32 v121, 0
	v_mov_b32_e32 v122, 0
	v_mov_b32_e32 v123, 0
	v_mov_b32_e32 v124, 0
	v_mov_b32_e32 v125, 0
	v_mov_b32_e32 v126, 0
	v_mov_b32_e32 v127, 0
	v_mov_b32_e32 v128, 0
	v_mov_b32_e32 v129, 0
	s_setprio 0
	s_waitcnt vmcnt(12)
	s_barrier
	ds_read_b128 v[146:149], v136 offset:0
	ds_read_b128 v[152:155], v136 offset:1024
	ds_read_b128 v[156:159], v136 offset:2048
	ds_read_b128 v[162:165], v136 offset:3072
	ds_read_b128 v[166:169], v136 offset:4096
	ds_read_b128 v[170:173], v136 offset:5120
	ds_read_b128 v[176:179], v136 offset:6144
	ds_read_b128 v[180:183], v136 offset:7168
	ds_read_b128 v[184:187], v137 offset:16384
	ds_read_b128 v[188:191], v137 offset:17408
	ds_read_b128 v[192:195], v137 offset:18432
	ds_read_b128 v[196:199], v137 offset:19456
	s_movk_i32 s36, 0x6000
	s_mov_b32 s37, 0
	s_movk_i32 s9, 14
	.p2align 6

; #define LAS __attribute__((address_space(3)))
; DEVI int tidx() { int t = threadIdx.x; asm volatile("" : "+v"(t)); return t; }
;   const int tid = tidx(), lane = tid & 63, wid = tid >> 6;
;   const int wm = wid >> 1, wn = wid & 1, r16 = lane & 15, quad = lane >> 4;
;   f32x4 acc[4][8];
; #pragma unroll
;   for (int i = 0; i < 4; i++)
; #pragma unroll
;     for (int j = 0; j < 8; j++) acc[i][j] = (f32x4){0.f, 0.f, 0.f, 0.f};
;   const int nk = (nk_part < 0) ? (K >> 5) : nk_part;
;   const int lrow = tid >> 2, lpc = tid & 3;
;   const int lch = lpc ^ ((0x78 >> (((lrow >> 2) & 3) * 2)) & 3);
;   const u16* ga = A + (size_t)(m0 + lrow) * lda + kbeg + lch * 8;
;   const u16* gb = Bt + (size_t)(n0 + lrow) * K + kbeg + lch * 8;
;   const size_t ga1 = (size_t)64 * lda, gb1 = (size_t)64 * K;
;   const unsigned lds0 = (unsigned)(uintptr_t)(LAS char*)smem + (unsigned)__builtin_amdgcn_readfirstlane(wid) * 1024u;
;     ...
;   __syncthreads();
;   G2_STAGE(0); G2_STAGE(1);
; DEVI void run_phase(const Params& p, int ph, char* smem) {
;     ...
;           const int u_ = t - 512, tl_ = u_ / 2, q_ = u_ - tl_ * 2;
;           gemm_tile256<EPI_RESID_ATOMIC>(p, ox, 256, Bt, 256, (64 + (tl_ & 1)) * 256, (tl_ >> 1) * 128, nullptr, 0, smem, q_ * 128, 4, q_);
.LBB0_147:
	s_cmpk_gt_i32 s38, 0x1ff
	s_mov_b64 s[2:3], -1
	s_cbranch_scc0 .LBB0_208
	s_setprio 2
	s_sub_i32 s98, s38, 512
	s_lshr_b32 s41, s98, 1
	s_and_b32 s99, s98, 1
	s_lshr_b32 s13, s41, 1
	s_and_b32 s41, s41, 1
	s_add_i32 s41, s41, 64
	v_readlane_b32 s2, v250, 5
	v_readlane_b32 s3, v250, 6
	v_readlane_b32 s98, v254, 62
	s_mul_i32 s1, s41, 0x20000
	s_add_u32 s4, s2, s1
	s_addc_u32 s5, s3, 0
	s_add_u32 s4, s4, 0xe700000
	s_addc_u32 s5, s5, 0
	s_mul_i32 s1, s98, 0x80000
	s_mul_i32 s12, s13, 0x10000
	s_add_i32 s1, s1, s12
	s_add_u32 s8, s2, s1
	s_addc_u32 s9, s3, 0
	s_add_u32 s8, s8, 0x16c00000
	s_addc_u32 s9, s9, 0
	s_mul_i32 s1, s99, 256
	s_add_u32 s4, s4, s1
	s_addc_u32 s5, s5, 0
	s_mul_i32 s1, s99, 512
	s_add_u32 s8, s8, s1
	s_addc_u32 s9, s9, 0
	s_movk_i32 s0, 0x78
	v_lshrrev_b32_e32 v0, 2, v145
	v_and_b32_e32 v131, 3, v145
	v_bfe_u32 v136, v145, 4, 2
	v_lshlrev_b32_e32 v136, 1, v136
	v_lshrrev_b32_e64 v136, v136, s0
	v_and_b32_e32 v136, 3, v136
	v_xor_b32_e32 v131, v131, v136
	v_lshlrev_b32_e32 v131, 4, v131
	s_movk_i32 s12, 0x200
	v_mad_u32_u24 v0, v0, s12, v131
	v_bfe_u32 v137, v145, 2, 1
	s_movk_i32 s12, 0x1c0
	v_mul_u32_u24_e32 v136, s12, v137
	v_sub_u32_e32 v136, v0, v136
	v_mov_b32_e32 v137, 0
	v_lshl_add_u64 v[134:135], s[8:9], 0, v[136:137]
	v_bfe_u32 v137, v145, 2, 1
	s_mov_b32 s10, 64
	s_mov_b32 s11, 0
	v_lshl_add_u64 v[132:133], s[4:5], 0, v[0:1]
	v_bfe_u32 v136, v145, 2, 2
	v_lshlrev_b32_e32 v136, 1, v136
	v_lshrrev_b32_e64 v136, v136, s0
	v_and_b32_e32 v136, 3, v136
	v_bfe_u32 v137, v145, 4, 2
	v_xor_b32_e32 v136, v136, v137
	v_lshlrev_b32_e32 v136, 4, v136
	v_and_b32_e32 v131, 15, v145
	v_lshl_or_b32 v136, v131, 6, v136
	v_bfe_u32 v137, v145, 6, 1
	v_lshl_or_b32 v137, v137, 12, v136
	v_lshrrev_b32_e32 v0, 7, v145
	v_lshl_or_b32 v136, v0, 13, v136
	v_and_b32_e32 v140, 1, v131
	v_lshl_or_b32 v131, v0, 7, v131
	v_bfe_u32 v0, v145, 4, 2
	v_lshlrev_b32_e32 v0, 3, v0
	v_bfe_u32 v141, v145, 6, 1
	s_lshl_b32 s1, s41, 19
	s_lshl_b32 s12, s13, 8
	s_add_i32 s1, s1, s12
	s_add_u32 s4, s2, s1
	s_addc_u32 s5, s3, 0
	s_add_u32 s4, s4, 0x4200000
	s_addc_u32 s5, s5, 0
	v_lshlrev_b32_e32 v138, 11, v131
	v_lshl_add_u32 v138, v141, 7, v138
	v_bfe_u32 v139, v145, 4, 1
	v_lshl_add_u32 v138, v139, 5, v138
	v_bfe_u32 v139, v145, 5, 1
	v_lshl_add_u32 v138, v139, 4, v138
	v_mov_b32_e32 v139, 0
	v_lshl_add_u64 v[138:139], s[4:5], 0, v[138:139]
	s_and_b32 s1, s41, 1
	s_lshl_b32 s1, s1, 20
	s_lshl_b32 s12, s99, 21
	s_add_i32 s1, s1, s12
	s_lshl_b32 s12, s13, 9
	s_add_i32 s1, s1, s12
	s_add_u32 s8, s2, s1
	s_addc_u32 s9, s3, 0
	s_add_u32 s8, s8, 0x1dcc0000
	s_addc_u32 s9, s9, 0
	v_lshlrev_b32_e32 v140, 12, v131
	v_lshl_add_u32 v140, v141, 8, v140
	v_lshl_add_u32 v140, v0, 1, v140
	v_mov_b32_e32 v141, 0
	v_lshl_add_u64 v[140:141], s[8:9], 0, v[140:141]
	s_mov_b32 s2, 0x8000
	s_mov_b32 s3, 0
	v_lshrrev_b32_e32 v0, 6, v145
	v_lshlrev_b32_e32 v0, 10, v0
	s_nop 0
	v_readfirstlane_b32 s98, v0
	s_mov_b32 s39, m0
	s_mov_b32 s4, 128
	s_mov_b32 s5, 0
	s_barrier
	s_add_i32 s13, s98, 0x0
	s_mov_b32 m0, s13
	v_lshl_add_u64 v[142:143], v[132:133], 0, s[2:3]
	global_load_lds_dwordx4 v[132:133], off
	s_add_i32 m0, m0, 0x1000
	s_nop 0
	global_load_lds_dwordx4 v[142:143], off
	v_lshl_add_u64 v[142:143], v[142:143], 0, s[2:3]
	s_add_i32 m0, m0, 0x1000
	s_nop 0
	global_load_lds_dwordx4 v[142:143], off
	v_lshl_add_u64 v[142:143], v[142:143], 0, s[2:3]
	s_add_i32 m0, m0, 0x1000
	s_nop 0
	global_load_lds_dwordx4 v[142:143], off
	s_add_i32 m0, m0, 0x1000
	v_lshl_add_u64 v[142:143], v[134:135], 0, s[2:3]
	s_nop 0
	global_load_lds_dwordx4 v[134:135], off
	s_add_i32 m0, m0, 0x1000
	v_lshl_add_u64 v[132:133], v[132:133], 0, s[10:11]
	s_nop 0
	global_load_lds_dwordx4 v[142:143], off
	v_lshl_add_u64 v[134:135], v[134:135], 0, s[4:5]
	s_nop 0
	s_add_i32 s13, s98, 0x6000
	s_mov_b32 m0, s13
	v_lshl_add_u64 v[142:143], v[132:133], 0, s[2:3]
	global_load_lds_dwordx4 v[132:133], off
	s_add_i32 m0, m0, 0x1000
	s_nop 0
	global_load_lds_dwordx4 v[142:143], off
	v_lshl_add_u64 v[142:143], v[142:143], 0, s[2:3]
	s_add_i32 m0, m0, 0x1000
	s_nop 0
	global_load_lds_dwordx4 v[142:143], off
	v_lshl_add_u64 v[142:143], v[142:143], 0, s[2:3]
	s_add_i32 m0, m0, 0x1000
	s_nop 0
	global_load_lds_dwordx4 v[142:143], off
	s_add_i32 m0, m0, 0x1000
	v_lshl_add_u64 v[142:143], v[134:135], 0, s[2:3]
	s_nop 0
	global_load_lds_dwordx4 v[134:135], off
	s_add_i32 m0, m0, 0x1000
	v_lshl_add_u64 v[132:133], v[132:133], 0, s[10:11]
	s_nop 0
	global_load_lds_dwordx4 v[142:143], off
	v_lshl_add_u64 v[134:135], v[134:135], 0, s[4:5]
	s_nop 0
	s_add_i32 s13, s98, 0xc000
	s_mov_b32 m0, s13
	v_lshl_add_u64 v[142:143], v[132:133], 0, s[2:3]
	global_load_lds_dwordx4 v[132:133], off
	s_add_i32 m0, m0, 0x1000
	s_nop 0
	global_load_lds_dwordx4 v[142:143], off
	v_lshl_add_u64 v[142:143], v[142:143], 0, s[2:3]
	s_add_i32 m0, m0, 0x1000
	s_nop 0
	global_load_lds_dwordx4 v[142:143], off
	v_lshl_add_u64 v[142:143], v[142:143], 0, s[2:3]
	s_add_i32 m0, m0, 0x1000
	s_nop 0
	global_load_lds_dwordx4 v[142:143], off
	s_add_i32 m0, m0, 0x1000
	v_lshl_add_u64 v[142:143], v[134:135], 0, s[2:3]
	s_nop 0
	global_load_lds_dwordx4 v[134:135], off
	s_add_i32 m0, m0, 0x1000
	v_lshl_add_u64 v[132:133], v[132:133], 0, s[10:11]
	s_nop 0
	global_load_lds_dwordx4 v[142:143], off
	v_lshl_add_u64 v[134:135], v[134:135], 0, s[4:5]
	s_nop 0
	v_mov_b32_e32 v2, 0
	v_mov_b32_e32 v3, 0
	v_mov_b32_e32 v4, 0
	v_mov_b32_e32 v5, 0
	v_mov_b32_e32 v6, 0
	v_mov_b32_e32 v7, 0
	v_mov_b32_e32 v8, 0
	v_mov_b32_e32 v9, 0
	v_mov_b32_e32 v10, 0
	v_mov_b32_e32 v11, 0
	v_mov_b32_e32 v12, 0
	v_mov_b32_e32 v13, 0
	v_mov_b32_e32 v14, 0
	v_mov_b32_e32 v15, 0
; #define LAS __attribute__((address_space(3)))
;     ...
;   f32x4 acc[4][8];
; #pragma unroll
;   for (int i = 0; i < 4; i++)
; #pragma unroll
;     for (int j = 0; j < 8; j++) acc[i][j] = (f32x4){0.f, 0.f, 0.f, 0.f};
;   const int nk = (nk_part < 0) ? (K >> 5) : nk_part;
;   const int lrow = tid >> 2, lpc = tid & 3;
;   const int lch = lpc ^ ((0x78 >> (((lrow >> 2) & 3) * 2)) & 3);
;   const u16* ga = A + (size_t)(m0 + lrow) * lda + kbeg + lch * 8;
;   const u16* gb = Bt + (size_t)(n0 + lrow) * K + kbeg + lch * 8;
;   const size_t ga1 = (size_t)64 * lda, gb1 = (size_t)64 * K;
;   const unsigned lds0 = (unsigned)(uintptr_t)(LAS char*)smem + (unsigned)__builtin_amdgcn_readfirstlane(wid) * 1024u;
;     ...
;   __syncthreads();
;   G2_STAGE(0); G2_STAGE(1);
;   const int fsw = (0x78 >> (((r16 >> 2) & 3) * 2)) & 3;
;   const int aoff = (wm * 128 + r16) * 64 + ((quad ^ fsw) << 4);
;   const int boff = 16384 + (wn * 64 + r16) * 64 + ((quad ^ fsw) << 4);
;   for (int kt = 0; kt < nk; kt++) {
;     if (kt + 1 < nk) asm volatile("s_waitcnt vmcnt(6)" ::: "memory");
;     else asm volatile("s_waitcnt vmcnt(0)" ::: "memory");
;     __builtin_amdgcn_s_barrier();
;     asm volatile("" ::: "memory");
;     if (kt + 2 < nk) G2_STAGE(kt + 2);
;     const char* cS = smem + (kt % 3) * 24576;
;     bf16x8 xa[8], wb[4];
; #pragma unroll
;     for (int f = 0; f < 8; f++) xa[f] = *(const bf16x8*)(cS + aoff + f * 1024);
; #pragma unroll
;     for (int f = 0; f < 4; f++) wb[f] = *(const bf16x8*)(cS + boff + f * 1024);
; #pragma unroll
;     for (int nf = 0; nf < 4; nf++)
; #pragma unroll
;       for (int mf = 0; mf < 8; mf++)
;         acc[nf][mf] = __builtin_amdgcn_mfma_f32_16x16x32_bf16(wb[nf], xa[mf], acc[nf][mf], 0, 0, 0);
	v_mov_b32_e32 v16, 0
	v_mov_b32_e32 v17, 0
	v_mov_b32_e32 v18, 0
	v_mov_b32_e32 v19, 0
	v_mov_b32_e32 v20, 0
	v_mov_b32_e32 v21, 0
	v_mov_b32_e32 v22, 0
	v_mov_b32_e32 v23, 0
	v_mov_b32_e32 v24, 0
	v_mov_b32_e32 v25, 0
	v_mov_b32_e32 v26, 0
	v_mov_b32_e32 v27, 0
	v_mov_b32_e32 v28, 0
	v_mov_b32_e32 v29, 0
	v_mov_b32_e32 v30, 0
	v_mov_b32_e32 v31, 0
	v_mov_b32_e32 v32, 0
	v_mov_b32_e32 v33, 0
	v_mov_b32_e32 v34, 0
	v_mov_b32_e32 v35, 0
	v_mov_b32_e32 v36, 0
	v_mov_b32_e32 v37, 0
	v_mov_b32_e32 v38, 0
	v_mov_b32_e32 v39, 0
	v_mov_b32_e32 v40, 0
	v_mov_b32_e32 v41, 0
	v_mov_b32_e32 v42, 0
	v_mov_b32_e32 v43, 0
	v_mov_b32_e32 v44, 0
	v_mov_b32_e32 v45, 0
	v_mov_b32_e32 v46, 0
	v_mov_b32_e32 v47, 0
	v_mov_b32_e32 v48, 0
	v_mov_b32_e32 v49, 0
	v_mov_b32_e32 v50, 0
	v_mov_b32_e32 v51, 0
	v_mov_b32_e32 v52, 0
	v_mov_b32_e32 v53, 0
	v_mov_b32_e32 v54, 0
	v_mov_b32_e32 v55, 0
	v_mov_b32_e32 v56, 0
	v_mov_b32_e32 v57, 0
	v_mov_b32_e32 v58, 0
	v_mov_b32_e32 v59, 0
	v_mov_b32_e32 v60, 0
	v_mov_b32_e32 v61, 0
	v_mov_b32_e32 v62, 0
	v_mov_b32_e32 v63, 0
	v_mov_b32_e32 v64, 0
	v_mov_b32_e32 v65, 0
	v_mov_b32_e32 v66, 0
	v_mov_b32_e32 v67, 0
	v_mov_b32_e32 v68, 0
	v_mov_b32_e32 v69, 0
	v_mov_b32_e32 v70, 0
	v_mov_b32_e32 v71, 0
	v_mov_b32_e32 v72, 0
	v_mov_b32_e32 v73, 0
	v_mov_b32_e32 v74, 0
	v_mov_b32_e32 v75, 0
	v_mov_b32_e32 v76, 0
	v_mov_b32_e32 v77, 0
	v_mov_b32_e32 v78, 0
	v_mov_b32_e32 v79, 0
	v_mov_b32_e32 v80, 0
	v_mov_b32_e32 v81, 0
	v_mov_b32_e32 v82, 0
	v_mov_b32_e32 v83, 0
	v_mov_b32_e32 v84, 0
	v_mov_b32_e32 v85, 0
	v_mov_b32_e32 v86, 0
	v_mov_b32_e32 v87, 0
	v_mov_b32_e32 v88, 0
	v_mov_b32_e32 v89, 0
	v_mov_b32_e32 v90, 0
	v_mov_b32_e32 v91, 0
	v_mov_b32_e32 v92, 0
	v_mov_b32_e32 v93, 0
	v_mov_b32_e32 v94, 0
	v_mov_b32_e32 v95, 0
	v_mov_b32_e32 v96, 0
	v_mov_b32_e32 v97, 0
	v_mov_b32_e32 v98, 0
	v_mov_b32_e32 v99, 0
	v_mov_b32_e32 v100, 0
	v_mov_b32_e32 v101, 0
	v_mov_b32_e32 v102, 0
	v_mov_b32_e32 v103, 0
	v_mov_b32_e32 v104, 0
	v_mov_b32_e32 v105, 0
	v_mov_b32_e32 v106, 0
	v_mov_b32_e32 v107, 0
	v_mov_b32_e32 v108, 0
	v_mov_b32_e32 v109, 0
	v_mov_b32_e32 v110, 0
	v_mov_b32_e32 v111, 0
	v_mov_b32_e32 v112, 0
	v_mov_b32_e32 v113, 0
	v_mov_b32_e32 v114, 0
	v_mov_b32_e32 v115, 0
	v_mov_b32_e32 v116, 0
	v_mov_b32_e32 v117, 0
	v_mov_b32_e32 v118, 0
	v_mov_b32_e32 v119, 0
	v_mov_b32_e32 v120, 0
	v_mov_b32_e32 v121, 0
	v_mov_b32_e32 v122, 0
	v_mov_b32_e32 v123, 0
	v_mov_b32_e32 v124, 0
	v_mov_b32_e32 v125, 0
	v_mov_b32_e32 v126, 0
	v_mov_b32_e32 v127, 0
	v_mov_b32_e32 v128, 0
	v_mov_b32_e32 v129, 0
	s_setprio 0
	s_waitcnt vmcnt(12)
	s_barrier
	ds_read_b128 v[146:149], v136 offset:0
	ds_read_b128 v[152:155], v136 offset:1024
	ds_read_b128 v[156:159], v136 offset:2048
	ds_read_b128 v[162:165], v136 offset:3072
	ds_read_b128 v[166:169], v136 offset:4096
	ds_read_b128 v[170:173], v136 offset:5120
	ds_read_b128 v[176:179], v136 offset:6144
	ds_read_b128 v[180:183], v136 offset:7168
	ds_read_b128 v[184:187], v137 offset:16384
	ds_read_b128 v[188:191], v137 offset:17408
	ds_read_b128 v[192:195], v137 offset:18432
	ds_read_b128 v[196:199], v137 offset:19456
	s_movk_i32 s1, 0x6000
	s_mov_b32 s12, 0
	.p2align 3
	s_waitcnt vmcnt(6) lgkmcnt(0)
	s_barrier
	s_setprio 1
	v_add_u32_e32 v144, s1, v136
	v_mfma_f32_16x16x32_bf16 v[126:129], v[184:187], v[146:149], v[126:129]
	ds_read_b128 v[200:203], v144 offset:0
	v_mfma_f32_16x16x32_bf16 v[122:125], v[184:187], v[152:155], v[122:125]
	ds_read_b128 v[204:207], v144 offset:1024
	v_mfma_f32_16x16x32_bf16 v[118:121], v[184:187], v[156:159], v[118:121]
	ds_read_b128 v[208:211], v144 offset:2048
	v_mfma_f32_16x16x32_bf16 v[114:117], v[184:187], v[162:165], v[114:117]
	ds_read_b128 v[212:215], v144 offset:3072
	v_mfma_f32_16x16x32_bf16 v[110:113], v[184:187], v[166:169], v[110:113]
	ds_read_b128 v[216:219], v144 offset:4096
	v_mfma_f32_16x16x32_bf16 v[106:109], v[184:187], v[170:173], v[106:109]
	ds_read_b128 v[220:223], v144 offset:5120
	v_mfma_f32_16x16x32_bf16 v[102:105], v[184:187], v[176:179], v[102:105]
	ds_read_b128 v[224:227], v144 offset:6144
	v_mfma_f32_16x16x32_bf16 v[98:101], v[184:187], v[180:183], v[98:101]
	ds_read_b128 v[228:231], v144 offset:7168
	v_mfma_f32_16x16x32_bf16 v[94:97], v[188:191], v[146:149], v[94:97]
	v_add_u32_e64 v144, s1, v137
	v_mfma_f32_16x16x32_bf16 v[90:93], v[188:191], v[152:155], v[90:93]
	v_mfma_f32_16x16x32_bf16 v[86:89], v[188:191], v[156:159], v[86:89]
	ds_read_b128 v[232:235], v144 offset:16384
	v_mfma_f32_16x16x32_bf16 v[82:85], v[188:191], v[162:165], v[82:85]
	ds_read_b128 v[236:239], v144 offset:17408
	v_mfma_f32_16x16x32_bf16 v[78:81], v[188:191], v[166:169], v[78:81]
	ds_read_b128 v[240:243], v144 offset:18432
	v_mfma_f32_16x16x32_bf16 v[74:77], v[188:191], v[170:173], v[74:77]
	ds_read_b128 v[244:247], v144 offset:19456
	v_mfma_f32_16x16x32_bf16 v[70:73], v[188:191], v[176:179], v[70:73]
	s_add_i32 s13, s98, s12
	s_mov_b32 m0, s13
	v_lshl_add_u64 v[142:143], v[132:133], 0, s[2:3]
	v_mfma_f32_16x16x32_bf16 v[66:69], v[188:191], v[180:183], v[66:69]
	global_load_lds_dwordx4 v[132:133], off
	s_add_i32 m0, m0, 0x1000
	v_mfma_f32_16x16x32_bf16 v[62:65], v[192:195], v[146:149], v[62:65]
	v_mfma_f32_16x16x32_bf16 v[58:61], v[192:195], v[152:155], v[58:61]
	v_mfma_f32_16x16x32_bf16 v[54:57], v[192:195], v[156:159], v[54:57]
	global_load_lds_dwordx4 v[142:143], off
	v_lshl_add_u64 v[142:143], v[142:143], 0, s[2:3]
	s_add_i32 m0, m0, 0x1000
	v_mfma_f32_16x16x32_bf16 v[50:53], v[192:195], v[162:165], v[50:53]
	v_mfma_f32_16x16x32_bf16 v[46:49], v[192:195], v[166:169], v[46:49]
	v_mfma_f32_16x16x32_bf16 v[42:45], v[192:195], v[170:173], v[42:45]
	global_load_lds_dwordx4 v[142:143], off
	v_lshl_add_u64 v[142:143], v[142:143], 0, s[2:3]
	s_add_i32 m0, m0, 0x1000
	v_mfma_f32_16x16x32_bf16 v[38:41], v[192:195], v[176:179], v[38:41]
	v_mfma_f32_16x16x32_bf16 v[34:37], v[192:195], v[180:183], v[34:37]
	v_mfma_f32_16x16x32_bf16 v[30:33], v[196:199], v[146:149], v[30:33]
	global_load_lds_dwordx4 v[142:143], off
	s_add_i32 m0, m0, 0x1000
	v_lshl_add_u64 v[142:143], v[134:135], 0, s[2:3]
	v_mfma_f32_16x16x32_bf16 v[26:29], v[196:199], v[152:155], v[26:29]
	v_mfma_f32_16x16x32_bf16 v[22:25], v[196:199], v[156:159], v[22:25]
	v_mfma_f32_16x16x32_bf16 v[18:21], v[196:199], v[162:165], v[18:21]
	global_load_lds_dwordx4 v[134:135], off
	s_add_i32 m0, m0, 0x1000
	v_lshl_add_u64 v[132:133], v[132:133], 0, s[10:11]
	v_mfma_f32_16x16x32_bf16 v[14:17], v[196:199], v[166:169], v[14:17]
	v_mfma_f32_16x16x32_bf16 v[10:13], v[196:199], v[170:173], v[10:13]
	v_mfma_f32_16x16x32_bf16 v[6:9], v[196:199], v[176:179], v[6:9]
	global_load_lds_dwordx4 v[142:143], off
	v_lshl_add_u64 v[134:135], v[134:135], 0, s[4:5]
	v_mfma_f32_16x16x32_bf16 v[2:5], v[196:199], v[180:183], v[2:5]
	s_setprio 0
	s_mov_b32 s12, s1
	s_add_i32 s1, s1, 0x6000
	s_cmp_eq_u32 s1, 0x12000
	s_cselect_b32 s1, 0, s1
	s_nop 0
	.p2align 3
	s_waitcnt vmcnt(6) lgkmcnt(0)
	s_barrier
;     ...
;   for (int kt = 0; kt < nk; kt++) {
;     if (kt + 1 < nk) asm volatile("s_waitcnt vmcnt(6)" ::: "memory");
;     else asm volatile("s_waitcnt vmcnt(0)" ::: "memory");
;     __builtin_amdgcn_s_barrier();
;     asm volatile("" ::: "memory");
;     if (kt + 2 < nk) G2_STAGE(kt + 2);
;     const char* cS = smem + (kt % 3) * 24576;
;     bf16x8 xa[8], wb[4];
; #pragma unroll
;     for (int f = 0; f < 8; f++) xa[f] = *(const bf16x8*)(cS + aoff + f * 1024);
; #pragma unroll
;     for (int f = 0; f < 4; f++) wb[f] = *(const bf16x8*)(cS + boff + f * 1024);
; #pragma unroll
;     for (int nf = 0; nf < 4; nf++)
; #pragma unroll
;       for (int mf = 0; mf < 8; mf++)
;         acc[nf][mf] = __builtin_amdgcn_mfma_f32_16x16x32_bf16(wb[nf], xa[mf], acc[nf][mf], 0, 0, 0);
	s_setprio 1
	v_add_u32_e32 v144, s1, v136
	v_mfma_f32_16x16x32_bf16 v[126:129], v[232:235], v[200:203], v[126:129]
	ds_read_b128 v[146:149], v144 offset:0
	v_mfma_f32_16x16x32_bf16 v[122:125], v[232:235], v[204:207], v[122:125]
	ds_read_b128 v[152:155], v144 offset:1024
	v_mfma_f32_16x16x32_bf16 v[118:121], v[232:235], v[208:211], v[118:121]
	ds_read_b128 v[156:159], v144 offset:2048
	v_mfma_f32_16x16x32_bf16 v[114:117], v[232:235], v[212:215], v[114:117]
	ds_read_b128 v[162:165], v144 offset:3072
	v_mfma_f32_16x16x32_bf16 v[110:113], v[232:235], v[216:219], v[110:113]
	ds_read_b128 v[166:169], v144 offset:4096
	v_mfma_f32_16x16x32_bf16 v[106:109], v[232:235], v[220:223], v[106:109]
	ds_read_b128 v[170:173], v144 offset:5120
	v_mfma_f32_16x16x32_bf16 v[102:105], v[232:235], v[224:227], v[102:105]
	ds_read_b128 v[176:179], v144 offset:6144
	v_mfma_f32_16x16x32_bf16 v[98:101], v[232:235], v[228:231], v[98:101]
	ds_read_b128 v[180:183], v144 offset:7168
	v_mfma_f32_16x16x32_bf16 v[94:97], v[236:239], v[200:203], v[94:97]
	v_add_u32_e64 v144, s1, v137
	v_mfma_f32_16x16x32_bf16 v[90:93], v[236:239], v[204:207], v[90:93]
	v_mfma_f32_16x16x32_bf16 v[86:89], v[236:239], v[208:211], v[86:89]
	ds_read_b128 v[184:187], v144 offset:16384
	v_mfma_f32_16x16x32_bf16 v[82:85], v[236:239], v[212:215], v[82:85]
	ds_read_b128 v[188:191], v144 offset:17408
	v_mfma_f32_16x16x32_bf16 v[78:81], v[236:239], v[216:219], v[78:81]
	ds_read_b128 v[192:195], v144 offset:18432
	v_mfma_f32_16x16x32_bf16 v[74:77], v[236:239], v[220:223], v[74:77]
	ds_read_b128 v[196:199], v144 offset:19456
	v_mfma_f32_16x16x32_bf16 v[70:73], v[236:239], v[224:227], v[70:73]
	v_mfma_f32_16x16x32_bf16 v[66:69], v[236:239], v[228:231], v[66:69]
	v_mfma_f32_16x16x32_bf16 v[62:65], v[240:243], v[200:203], v[62:65]
	v_mfma_f32_16x16x32_bf16 v[58:61], v[240:243], v[204:207], v[58:61]
	v_mfma_f32_16x16x32_bf16 v[54:57], v[240:243], v[208:211], v[54:57]
	v_mfma_f32_16x16x32_bf16 v[50:53], v[240:243], v[212:215], v[50:53]
	v_mfma_f32_16x16x32_bf16 v[46:49], v[240:243], v[216:219], v[46:49]
	v_mfma_f32_16x16x32_bf16 v[42:45], v[240:243], v[220:223], v[42:45]
	v_mfma_f32_16x16x32_bf16 v[38:41], v[240:243], v[224:227], v[38:41]
	v_mfma_f32_16x16x32_bf16 v[34:37], v[240:243], v[228:231], v[34:37]
	v_mfma_f32_16x16x32_bf16 v[30:33], v[244:247], v[200:203], v[30:33]
	v_mfma_f32_16x16x32_bf16 v[26:29], v[244:247], v[204:207], v[26:29]
	v_mfma_f32_16x16x32_bf16 v[22:25], v[244:247], v[208:211], v[22:25]
	v_mfma_f32_16x16x32_bf16 v[18:21], v[244:247], v[212:215], v[18:21]
	v_mfma_f32_16x16x32_bf16 v[14:17], v[244:247], v[216:219], v[14:17]
	v_mfma_f32_16x16x32_bf16 v[10:13], v[244:247], v[220:223], v[10:13]
	v_mfma_f32_16x16x32_bf16 v[6:9], v[244:247], v[224:227], v[6:9]
	v_mfma_f32_16x16x32_bf16 v[2:5], v[244:247], v[228:231], v[2:5]
	s_setprio 0
	s_mov_b32 s12, s1
	s_add_i32 s1, s1, 0x6000
	s_cmp_eq_u32 s1, 0x12000
	s_cselect_b32 s1, 0, s1
	s_nop 0
	.p2align 3
	s_waitcnt vmcnt(0) lgkmcnt(0)
	s_barrier
	s_setprio 1
	v_add_u32_e32 v144, s1, v136
	v_mfma_f32_16x16x32_bf16 v[126:129], v[184:187], v[146:149], v[126:129]
	ds_read_b128 v[200:203], v144 offset:0
	v_mfma_f32_16x16x32_bf16 v[122:125], v[184:187], v[152:155], v[122:125]
	ds_read_b128 v[204:207], v144 offset:1024
	v_mfma_f32_16x16x32_bf16 v[118:121], v[184:187], v[156:159], v[118:121]
	ds_read_b128 v[208:211], v144 offset:2048
	v_mfma_f32_16x16x32_bf16 v[114:117], v[184:187], v[162:165], v[114:117]
	ds_read_b128 v[212:215], v144 offset:3072
	v_mfma_f32_16x16x32_bf16 v[110:113], v[184:187], v[166:169], v[110:113]
	ds_read_b128 v[216:219], v144 offset:4096
	v_mfma_f32_16x16x32_bf16 v[106:109], v[184:187], v[170:173], v[106:109]
	ds_read_b128 v[220:223], v144 offset:5120
	v_mfma_f32_16x16x32_bf16 v[102:105], v[184:187], v[176:179], v[102:105]
	ds_read_b128 v[224:227], v144 offset:6144
	v_mfma_f32_16x16x32_bf16 v[98:101], v[184:187], v[180:183], v[98:101]
	ds_read_b128 v[228:231], v144 offset:7168
	v_mfma_f32_16x16x32_bf16 v[94:97], v[188:191], v[146:149], v[94:97]
	v_add_u32_e64 v144, s1, v137
	v_mfma_f32_16x16x32_bf16 v[90:93], v[188:191], v[152:155], v[90:93]
	v_mfma_f32_16x16x32_bf16 v[86:89], v[188:191], v[156:159], v[86:89]
	ds_read_b128 v[232:235], v144 offset:16384
	v_mfma_f32_16x16x32_bf16 v[82:85], v[188:191], v[162:165], v[82:85]
	ds_read_b128 v[236:239], v144 offset:17408
	v_mfma_f32_16x16x32_bf16 v[78:81], v[188:191], v[166:169], v[78:81]
	ds_read_b128 v[240:243], v144 offset:18432
	v_mfma_f32_16x16x32_bf16 v[74:77], v[188:191], v[170:173], v[74:77]
	ds_read_b128 v[244:247], v144 offset:19456
	v_mfma_f32_16x16x32_bf16 v[70:73], v[188:191], v[176:179], v[70:73]
	v_mfma_f32_16x16x32_bf16 v[66:69], v[188:191], v[180:183], v[66:69]
	v_mfma_f32_16x16x32_bf16 v[62:65], v[192:195], v[146:149], v[62:65]
	v_mfma_f32_16x16x32_bf16 v[58:61], v[192:195], v[152:155], v[58:61]
	v_mfma_f32_16x16x32_bf16 v[54:57], v[192:195], v[156:159], v[54:57]
	v_mfma_f32_16x16x32_bf16 v[50:53], v[192:195], v[162:165], v[50:53]
	v_mfma_f32_16x16x32_bf16 v[46:49], v[192:195], v[166:169], v[46:49]
	v_mfma_f32_16x16x32_bf16 v[42:45], v[192:195], v[170:173], v[42:45]
	v_mfma_f32_16x16x32_bf16 v[38:41], v[192:195], v[176:179], v[38:41]
	v_mfma_f32_16x16x32_bf16 v[34:37], v[192:195], v[180:183], v[34:37]
	v_mfma_f32_16x16x32_bf16 v[30:33], v[196:199], v[146:149], v[30:33]
	v_mfma_f32_16x16x32_bf16 v[26:29], v[196:199], v[152:155], v[26:29]
	v_mfma_f32_16x16x32_bf16 v[22:25], v[196:199], v[156:159], v[22:25]
	v_mfma_f32_16x16x32_bf16 v[18:21], v[196:199], v[162:165], v[18:21]
	v_mfma_f32_16x16x32_bf16 v[14:17], v[196:199], v[166:169], v[14:17]
	v_mfma_f32_16x16x32_bf16 v[10:13], v[196:199], v[170:173], v[10:13]
	v_mfma_f32_16x16x32_bf16 v[6:9], v[196:199], v[176:179], v[6:9]
	v_mfma_f32_16x16x32_bf16 v[2:5], v[196:199], v[180:183], v[2:5]
	s_setprio 0
	s_mov_b32 s12, s1
	s_add_i32 s1, s1, 0x6000
	s_cmp_eq_u32 s1, 0x12000
	s_cselect_b32 s1, 0, s1
	s_nop 0
	s_mov_b32 s4, 0x8000
	s_mov_b32 s5, 0
	s_mov_b32 s8, 0x10000
	s_mov_b32 s9, 0
	s_mov_b32 s40, 0x3fd744fd
	.p2align 3
	s_waitcnt lgkmcnt(0)
; DEVI unsigned pack2(float a, float b) { return __builtin_bit_cast(unsigned, __builtin_convertvector((f32x2_t){a, b}, bf16x2_t)); }
; DEVI float blo(unsigned u) { return __uint_as_float(u << 16); }
; DEVI float bhi(unsigned u) { return __uint_as_float(u & 0xffff0000u); }
; DEVI float siluf_(float x) { return x * __builtin_amdgcn_rcpf(1.f + __expf(-x)); }
;     ...
;     for (int nf = 0; nf < 4; nf++)
; #pragma unroll
;       for (int mf = 0; mf < 8; mf++)
;         acc[nf][mf] = __builtin_amdgcn_mfma_f32_16x16x32_bf16(wb[nf], xa[mf], acc[nf][mf], 0, 0, 0);
;   }
;     ...
; #pragma unroll
;   for (int mf = 0; mf < 8; mf++) {
;     const int row = m0 + wm * 128 + mf * 16 + r16;
;     if (EPI == EPI_SWIGLU) {
; #pragma unroll
;       for (int nf = 0; nf < 2; nf++) {
;         const int hcol = (n0 >> 1) + wn * 32 + nf * 16 + quad * 4;
;         f32x4 g = acc[nf][mf], u = acc[nf + 2][mf];
;         u32x2 pk;
;         pk[0] = pack2(siluf_(g[0]) * u[0], siluf_(g[1]) * u[1]);
;         pk[1] = pack2(siluf_(g[2]) * u[2], siluf_(g[3]) * u[3]);
;         *(u32x2*)(outb + (size_t)row * DFF + hcol) = pk;
;       }
;     } else {
; #pragma unroll
;       for (int nf = 0; nf < 4; nf++) {
;         const int col = n0 + wn * 64 + nf * 16 + quad * 4;
;         f32x4 a = acc[nf][mf];
;         if (EPI == EPI_RESID || EPI == EPI_RESID_ATOMIC) {
;           f32x4 x = a;
;           if (EPI == EPI_RESID || kpart == 0) {
;             const u32x2 xr = *(const u32x2*)((const u16*)(p.ws + WS_XB) + (size_t)row * 1024 + col);
;             x[0] += ALPHA * blo(xr[0]); x[1] += ALPHA * bhi(xr[0]); x[2] += ALPHA * blo(xr[1]); x[3] += ALPHA * bhi(xr[1]);
;           }
;           if (EPI == EPI_RESID) *(f32x4*)((float*)(p.ws + WS_XF) + (size_t)row * 1024 + col) = x;
;           else *(f32x4*)((float*)(p.ws + WS_SLAB) + ((size_t)kpart * 512 + (row - T_P)) * 1024 + col) = x;
	s_nop 0
	v_mfma_f32_16x16x32_bf16 v[126:129], v[232:235], v[200:203], v[126:129]
	v_mfma_f32_16x16x32_bf16 v[122:125], v[232:235], v[204:207], v[122:125]
	v_mfma_f32_16x16x32_bf16 v[118:121], v[232:235], v[208:211], v[118:121]
	v_mfma_f32_16x16x32_bf16 v[114:117], v[232:235], v[212:215], v[114:117]
	v_mfma_f32_16x16x32_bf16 v[110:113], v[232:235], v[216:219], v[110:113]
	v_mfma_f32_16x16x32_bf16 v[106:109], v[232:235], v[220:223], v[106:109]
	v_mfma_f32_16x16x32_bf16 v[102:105], v[232:235], v[224:227], v[102:105]
	v_mfma_f32_16x16x32_bf16 v[98:101], v[232:235], v[228:231], v[98:101]
	v_mfma_f32_16x16x32_bf16 v[94:97], v[236:239], v[200:203], v[94:97]
	v_mfma_f32_16x16x32_bf16 v[90:93], v[236:239], v[204:207], v[90:93]
	v_mfma_f32_16x16x32_bf16 v[86:89], v[236:239], v[208:211], v[86:89]
	v_mfma_f32_16x16x32_bf16 v[82:85], v[236:239], v[212:215], v[82:85]
	v_mfma_f32_16x16x32_bf16 v[78:81], v[236:239], v[216:219], v[78:81]
	v_mfma_f32_16x16x32_bf16 v[74:77], v[236:239], v[220:223], v[74:77]
	v_mfma_f32_16x16x32_bf16 v[70:73], v[236:239], v[224:227], v[70:73]
	v_mfma_f32_16x16x32_bf16 v[66:69], v[236:239], v[228:231], v[66:69]
	v_mfma_f32_16x16x32_bf16 v[62:65], v[240:243], v[200:203], v[62:65]
	v_mfma_f32_16x16x32_bf16 v[58:61], v[240:243], v[204:207], v[58:61]
	v_mfma_f32_16x16x32_bf16 v[54:57], v[240:243], v[208:211], v[54:57]
	v_mfma_f32_16x16x32_bf16 v[50:53], v[240:243], v[212:215], v[50:53]
	v_mfma_f32_16x16x32_bf16 v[46:49], v[240:243], v[216:219], v[46:49]
	v_mfma_f32_16x16x32_bf16 v[42:45], v[240:243], v[220:223], v[42:45]
	v_mfma_f32_16x16x32_bf16 v[38:41], v[240:243], v[224:227], v[38:41]
	v_mfma_f32_16x16x32_bf16 v[34:37], v[240:243], v[228:231], v[34:37]
	v_mfma_f32_16x16x32_bf16 v[30:33], v[244:247], v[200:203], v[30:33]
	v_mfma_f32_16x16x32_bf16 v[26:29], v[244:247], v[204:207], v[26:29]
	v_mfma_f32_16x16x32_bf16 v[22:25], v[244:247], v[208:211], v[22:25]
	v_mfma_f32_16x16x32_bf16 v[18:21], v[244:247], v[212:215], v[18:21]
	v_mfma_f32_16x16x32_bf16 v[14:17], v[244:247], v[216:219], v[14:17]
	v_mfma_f32_16x16x32_bf16 v[10:13], v[244:247], v[220:223], v[10:13]
	v_mfma_f32_16x16x32_bf16 v[6:9], v[244:247], v[224:227], v[6:9]
	v_mfma_f32_16x16x32_bf16 v[2:5], v[244:247], v[228:231], v[2:5]
	s_mov_b32 m0, s39
	s_cmp_eq_u32 s99, 0
	s_cbranch_scc1 .Lta8_first
	s_nop 7
	global_store_dwordx4 v[140:141], v[126:129], off offset:0
	global_store_dwordx4 v[140:141], v[94:97], off offset:64
	global_store_dwordx4 v[140:141], v[62:65], off offset:128
	global_store_dwordx4 v[140:141], v[30:33], off offset:192
	v_lshl_add_u64 v[140:141], v[140:141], 0, s[8:9]
	global_store_dwordx4 v[140:141], v[122:125], off offset:0
	global_store_dwordx4 v[140:141], v[90:93], off offset:64
	global_store_dwordx4 v[140:141], v[58:61], off offset:128
	global_store_dwordx4 v[140:141], v[26:29], off offset:192
	v_lshl_add_u64 v[140:141], v[140:141], 0, s[8:9]
	global_store_dwordx4 v[140:141], v[118:121], off offset:0
	global_store_dwordx4 v[140:141], v[86:89], off offset:64
	global_store_dwordx4 v[140:141], v[54:57], off offset:128
	global_store_dwordx4 v[140:141], v[22:25], off offset:192
	v_lshl_add_u64 v[140:141], v[140:141], 0, s[8:9]
	global_store_dwordx4 v[140:141], v[114:117], off offset:0
	global_store_dwordx4 v[140:141], v[82:85], off offset:64
	global_store_dwordx4 v[140:141], v[50:53], off offset:128
	global_store_dwordx4 v[140:141], v[18:21], off offset:192
	v_lshl_add_u64 v[140:141], v[140:141], 0, s[8:9]
	global_store_dwordx4 v[140:141], v[110:113], off offset:0
	global_store_dwordx4 v[140:141], v[78:81], off offset:64
	global_store_dwordx4 v[140:141], v[46:49], off offset:128
	global_store_dwordx4 v[140:141], v[14:17], off offset:192
	v_lshl_add_u64 v[140:141], v[140:141], 0, s[8:9]
	global_store_dwordx4 v[140:141], v[106:109], off offset:0
	global_store_dwordx4 v[140:141], v[74:77], off offset:64
	global_store_dwordx4 v[140:141], v[42:45], off offset:128
	global_store_dwordx4 v[140:141], v[10:13], off offset:192
	v_lshl_add_u64 v[140:141], v[140:141], 0, s[8:9]
	global_store_dwordx4 v[140:141], v[102:105], off offset:0
	global_store_dwordx4 v[140:141], v[70:73], off offset:64
	global_store_dwordx4 v[140:141], v[38:41], off offset:128
	global_store_dwordx4 v[140:141], v[6:9], off offset:192
	v_lshl_add_u64 v[140:141], v[140:141], 0, s[8:9]
	global_store_dwordx4 v[140:141], v[98:101], off offset:0
	global_store_dwordx4 v[140:141], v[66:69], off offset:64
	global_store_dwordx4 v[140:141], v[34:37], off offset:128
	global_store_dwordx4 v[140:141], v[2:5], off offset:192
	v_readlane_b32 s0, v250, 7
	s_cmpk_lg_u32 s0, 0x200
	s_cbranch_scc1 .Lta8_ar1
	s_mov_b32 s0, 1
	v_writelane_b32 v255, s0, 41
	v_readlane_b32 s1, v250, 0
	s_lshr_b32 s12, s1, 3
	s_and_b32 s1, s1, 7
	s_lshl_b32 s1, s1, 6
	s_add_i32 s1, s1, s12
	s_sub_i32 s38, s1, 0x200

; #define LAS __attribute__((address_space(3)))
; DEVI int tidx() { int t = threadIdx.x; asm volatile("" : "+v"(t)); return t; }
; DEVI int xcd_first_tile() { return (blockIdx.x & 7) * (gridDim.x >> 3) + (blockIdx.x >> 3); }
;   const int tid = tidx(), lane = tid & 63, wid = tid >> 6;
;   const int wm = wid >> 1, wn = wid & 1, r16 = lane & 15, quad = lane >> 4;
;   f32x4 acc[4][8];
; #pragma unroll
;   for (int i = 0; i < 4; i++)
; #pragma unroll
;     for (int j = 0; j < 8; j++) acc[i][j] = (f32x4){0.f, 0.f, 0.f, 0.f};
;   const int nk = (nk_part < 0) ? (K >> 5) : nk_part;
;   const int lrow = tid >> 2, lpc = tid & 3;
;   const int lch = lpc ^ ((0x78 >> (((lrow >> 2) & 3) * 2)) & 3);
;   const u16* ga = A + (size_t)(m0 + lrow) * lda + kbeg + lch * 8;
;   const u16* gb = Bt + (size_t)(n0 + lrow) * K + kbeg + lch * 8;
;   const size_t ga1 = (size_t)64 * lda, gb1 = (size_t)64 * K;
;   const unsigned lds0 = (unsigned)(uintptr_t)(LAS char*)smem + (unsigned)__builtin_amdgcn_readfirstlane(wid) * 1024u;
; DEVI void run_phase(const Params& p, int ph, char* smem) {
;     ...
;       for (int t = xcd_first_tile(); t < 512 + 16 * 2; t += xcd_tile_step()) {
;         if (t < 512) {
;           int mt_, nt_; tile_coords(t, 64, 8, mt_, nt_);
;           gemm_tile256<EPI_RESID>(p, ox, 256, Bt, 256, mt_ * 256, nt_ * 128, nullptr, 0, smem);
.LBB0_208:
	s_and_b64 vcc, exec, s[2:3]
	s_cbranch_vccz .LBB0_146
	s_setprio 2
	v_readlane_b32 s39, v250, 7
	s_cmpk_lg_u32 s39, 0x200
	s_cbranch_scc1 .Lt8_go
	v_readlane_b32 s40, v255, 41
	s_cmp_lg_u32 s40, 0
	s_cbranch_scc1 .Lt8_go
	v_readlane_b32 s40, v250, 0
	s_lshr_b32 s41, s40, 3
	s_cmp_lt_u32 s41, 4
	s_cbranch_scc0 .Lt8_go
	s_and_b32 s40, s40, 7
	s_mul_i32 s40, s40, 4
	s_add_i32 s38, s40, s41
	s_branch .LBB0_146
.Lt8_go:
	s_lshr_b32 s45, s38, 6
	s_and_b32 s46, s38, 63
	s_lshr_b32 s42, s46, 3
	s_and_b32 s46, s46, 7
	s_lshl_b32 s45, s45, 3
	s_add_i32 s45, s45, s46
	v_readlane_b32 s2, v250, 5
	v_readlane_b32 s3, v250, 6
	v_readlane_b32 s46, v254, 62
	s_mul_i32 s40, s45, 0x20000
	s_add_u32 s4, s2, s40
	s_addc_u32 s5, s3, 0
	s_add_u32 s4, s4, 0xe700000
	s_addc_u32 s5, s5, 0
	s_mul_i32 s40, s46, 0x80000
	s_mul_i32 s41, s42, 0x10000
	s_add_i32 s40, s40, s41
	s_add_u32 s10, s2, s40
	s_addc_u32 s11, s3, 0
	s_add_u32 s10, s10, 0x16c00000
	s_addc_u32 s11, s11, 0
	s_movk_i32 s39, 0x78
	v_lshrrev_b32_e32 v0, 2, v145
	v_and_b32_e32 v131, 3, v145
	v_bfe_u32 v136, v145, 4, 2
	v_lshlrev_b32_e32 v136, 1, v136
	v_lshrrev_b32_e64 v136, v136, s39
	v_and_b32_e32 v136, 3, v136
	v_xor_b32_e32 v131, v131, v136
	v_lshlrev_b32_e32 v131, 4, v131
	s_movk_i32 s41, 0x200
	v_mad_u32_u24 v0, v0, s41, v131
	v_bfe_u32 v137, v145, 2, 1
	s_movk_i32 s41, 0x1c0
	v_mul_u32_u24_e32 v136, s41, v137
	v_sub_u32_e32 v136, v0, v136
	v_mov_b32_e32 v137, 0
	v_lshl_add_u64 v[134:135], s[10:11], 0, v[136:137]
	v_bfe_u32 v137, v145, 2, 1
	s_mov_b32 s12, 64
	s_mov_b32 s13, 0
	v_lshl_add_u64 v[132:133], s[4:5], 0, v[0:1]
	v_bfe_u32 v136, v145, 2, 2
	v_lshlrev_b32_e32 v136, 1, v136
	v_lshrrev_b32_e64 v136, v136, s39
	v_and_b32_e32 v136, 3, v136
	v_bfe_u32 v137, v145, 4, 2
	v_xor_b32_e32 v136, v136, v137
	v_lshlrev_b32_e32 v136, 4, v136
	v_and_b32_e32 v131, 15, v145
	v_lshl_or_b32 v136, v131, 6, v136
	v_bfe_u32 v137, v145, 6, 1
	v_lshl_or_b32 v137, v137, 12, v136
	v_lshrrev_b32_e32 v0, 7, v145
	v_lshl_or_b32 v136, v0, 13, v136
	v_and_b32_e32 v140, 1, v131
	v_lshl_or_b32 v131, v0, 7, v131
	v_bfe_u32 v0, v145, 4, 2
	v_lshlrev_b32_e32 v0, 3, v0
	v_bfe_u32 v141, v145, 6, 1
	s_lshl_b32 s40, s45, 19
	s_lshl_b32 s41, s42, 8
	s_add_i32 s40, s40, s41
	s_add_u32 s4, s2, s40
	s_addc_u32 s5, s3, 0
	s_add_u32 s4, s4, 0x4200000
	s_addc_u32 s5, s5, 0
	v_lshlrev_b32_e32 v138, 11, v131
	v_lshl_add_u32 v138, v141, 7, v138
	v_bfe_u32 v139, v145, 4, 1
	v_lshl_add_u32 v138, v139, 5, v138
	v_bfe_u32 v139, v145, 5, 1
	v_lshl_add_u32 v138, v139, 4, v138
	v_mov_b32_e32 v139, 0
	v_lshl_add_u64 v[138:139], s[4:5], 0, v[138:139]
	s_lshl_b32 s40, s45, 20
	s_lshl_b32 s41, s42, 9
	s_add_i32 s40, s40, s41
	s_add_u32 s10, s2, s40
	s_addc_u32 s11, s3, 0
	v_lshlrev_b32_e32 v140, 12, v131
	v_lshl_add_u32 v140, v141, 8, v140
	v_lshl_add_u32 v140, v0, 1, v140
	v_mov_b32_e32 v141, 0
	v_lshl_add_u64 v[140:141], s[10:11], 0, v[140:141]
	s_mov_b32 s2, 0x8000
	s_mov_b32 s3, 0
	v_lshrrev_b32_e32 v0, 6, v145
	v_lshlrev_b32_e32 v0, 10, v0
	s_nop 0
	v_readfirstlane_b32 s46, v0
	s_mov_b32 s43, m0
	s_mov_b32 s4, 128
	s_mov_b32 s5, 0
	s_barrier
; #define LAS __attribute__((address_space(3)))
;     ...
;   f32x4 acc[4][8];
; #pragma unroll
;   for (int i = 0; i < 4; i++)
; #pragma unroll
;     for (int j = 0; j < 8; j++) acc[i][j] = (f32x4){0.f, 0.f, 0.f, 0.f};
;   const int nk = (nk_part < 0) ? (K >> 5) : nk_part;
;   const int lrow = tid >> 2, lpc = tid & 3;
;   const int lch = lpc ^ ((0x78 >> (((lrow >> 2) & 3) * 2)) & 3);
;   const u16* ga = A + (size_t)(m0 + lrow) * lda + kbeg + lch * 8;
;   const u16* gb = Bt + (size_t)(n0 + lrow) * K + kbeg + lch * 8;
;   const size_t ga1 = (size_t)64 * lda, gb1 = (size_t)64 * K;
;   const unsigned lds0 = (unsigned)(uintptr_t)(LAS char*)smem + (unsigned)__builtin_amdgcn_readfirstlane(wid) * 1024u;
;     ...
;   __syncthreads();
;   G2_STAGE(0); G2_STAGE(1);
;   const int fsw = (0x78 >> (((r16 >> 2) & 3) * 2)) & 3;
;   const int aoff = (wm * 128 + r16) * 64 + ((quad ^ fsw) << 4);
;   const int boff = 16384 + (wn * 64 + r16) * 64 + ((quad ^ fsw) << 4);
;   for (int kt = 0; kt < nk; kt++) {
;     if (kt + 1 < nk) asm volatile("s_waitcnt vmcnt(6)" ::: "memory");
;     else asm volatile("s_waitcnt vmcnt(0)" ::: "memory");
;     __builtin_amdgcn_s_barrier();
;     asm volatile("" ::: "memory");
;     if (kt + 2 < nk) G2_STAGE(kt + 2);
;     const char* cS = smem + (kt % 3) * 24576;
;     bf16x8 xa[8], wb[4];
; #pragma unroll
;     for (int f = 0; f < 8; f++) xa[f] = *(const bf16x8*)(cS + aoff + f * 1024);
; #pragma unroll
;     for (int f = 0; f < 4; f++) wb[f] = *(const bf16x8*)(cS + boff + f * 1024);
	s_add_i32 s42, s46, 0x0
	s_mov_b32 m0, s42
	v_lshl_add_u64 v[142:143], v[132:133], 0, s[2:3]
	global_load_lds_dwordx4 v[132:133], off
	s_add_i32 m0, m0, 0x1000
	s_nop 0
	global_load_lds_dwordx4 v[142:143], off
	v_lshl_add_u64 v[142:143], v[142:143], 0, s[2:3]
	s_add_i32 m0, m0, 0x1000
	s_nop 0
	global_load_lds_dwordx4 v[142:143], off
	v_lshl_add_u64 v[142:143], v[142:143], 0, s[2:3]
	s_add_i32 m0, m0, 0x1000
	s_nop 0
	global_load_lds_dwordx4 v[142:143], off
	s_add_i32 m0, m0, 0x1000
	v_lshl_add_u64 v[142:143], v[134:135], 0, s[2:3]
	s_nop 0
	global_load_lds_dwordx4 v[134:135], off
	s_add_i32 m0, m0, 0x1000
	v_lshl_add_u64 v[132:133], v[132:133], 0, s[12:13]
	s_nop 0
	global_load_lds_dwordx4 v[142:143], off
	v_lshl_add_u64 v[134:135], v[134:135], 0, s[4:5]
	s_nop 0
	s_add_i32 s42, s46, 0x6000
	s_mov_b32 m0, s42
	v_lshl_add_u64 v[142:143], v[132:133], 0, s[2:3]
	global_load_lds_dwordx4 v[132:133], off
	s_add_i32 m0, m0, 0x1000
	s_nop 0
	global_load_lds_dwordx4 v[142:143], off
	v_lshl_add_u64 v[142:143], v[142:143], 0, s[2:3]
	s_add_i32 m0, m0, 0x1000
	s_nop 0
	global_load_lds_dwordx4 v[142:143], off
	v_lshl_add_u64 v[142:143], v[142:143], 0, s[2:3]
	s_add_i32 m0, m0, 0x1000
	s_nop 0
	global_load_lds_dwordx4 v[142:143], off
	s_add_i32 m0, m0, 0x1000
	v_lshl_add_u64 v[142:143], v[134:135], 0, s[2:3]
	s_nop 0
	global_load_lds_dwordx4 v[134:135], off
	s_add_i32 m0, m0, 0x1000
	v_lshl_add_u64 v[132:133], v[132:133], 0, s[12:13]
	s_nop 0
	global_load_lds_dwordx4 v[142:143], off
	v_lshl_add_u64 v[134:135], v[134:135], 0, s[4:5]
	s_nop 0
	s_add_i32 s42, s46, 0xc000
	s_mov_b32 m0, s42
	v_lshl_add_u64 v[142:143], v[132:133], 0, s[2:3]
	global_load_lds_dwordx4 v[132:133], off
	s_add_i32 m0, m0, 0x1000
	s_nop 0
	global_load_lds_dwordx4 v[142:143], off
	v_lshl_add_u64 v[142:143], v[142:143], 0, s[2:3]
	s_add_i32 m0, m0, 0x1000
	s_nop 0
	global_load_lds_dwordx4 v[142:143], off
	v_lshl_add_u64 v[142:143], v[142:143], 0, s[2:3]
	s_add_i32 m0, m0, 0x1000
	s_nop 0
	global_load_lds_dwordx4 v[142:143], off
	s_add_i32 m0, m0, 0x1000
	v_lshl_add_u64 v[142:143], v[134:135], 0, s[2:3]
	s_nop 0
	global_load_lds_dwordx4 v[134:135], off
	s_add_i32 m0, m0, 0x1000
	v_lshl_add_u64 v[132:133], v[132:133], 0, s[12:13]
	s_nop 0
	global_load_lds_dwordx4 v[142:143], off
	v_lshl_add_u64 v[134:135], v[134:135], 0, s[4:5]
	s_nop 0
	v_mov_b32_e32 v2, 0
	v_mov_b32_e32 v3, 0
	v_mov_b32_e32 v4, 0
	v_mov_b32_e32 v5, 0
	v_mov_b32_e32 v6, 0
	v_mov_b32_e32 v7, 0
	v_mov_b32_e32 v8, 0
	v_mov_b32_e32 v9, 0
	v_mov_b32_e32 v10, 0
	v_mov_b32_e32 v11, 0
	v_mov_b32_e32 v12, 0
	v_mov_b32_e32 v13, 0
	v_mov_b32_e32 v14, 0
	v_mov_b32_e32 v15, 0
	v_mov_b32_e32 v16, 0
	v_mov_b32_e32 v17, 0
	v_mov_b32_e32 v18, 0
	v_mov_b32_e32 v19, 0
	v_mov_b32_e32 v20, 0
	v_mov_b32_e32 v21, 0
	v_mov_b32_e32 v22, 0
	v_mov_b32_e32 v23, 0
	v_mov_b32_e32 v24, 0
	v_mov_b32_e32 v25, 0
	v_mov_b32_e32 v26, 0
	v_mov_b32_e32 v27, 0
	v_mov_b32_e32 v28, 0
	v_mov_b32_e32 v29, 0
	v_mov_b32_e32 v30, 0
	v_mov_b32_e32 v31, 0
	v_mov_b32_e32 v32, 0
	v_mov_b32_e32 v33, 0
	v_mov_b32_e32 v34, 0
	v_mov_b32_e32 v35, 0
	v_mov_b32_e32 v36, 0
	v_mov_b32_e32 v37, 0
	v_mov_b32_e32 v38, 0
	v_mov_b32_e32 v39, 0
	v_mov_b32_e32 v40, 0
	v_mov_b32_e32 v41, 0
	v_mov_b32_e32 v42, 0
	v_mov_b32_e32 v43, 0
	v_mov_b32_e32 v44, 0
	v_mov_b32_e32 v45, 0
	v_mov_b32_e32 v46, 0
	v_mov_b32_e32 v47, 0
	v_mov_b32_e32 v48, 0
	v_mov_b32_e32 v49, 0
	v_mov_b32_e32 v50, 0
	v_mov_b32_e32 v51, 0
	v_mov_b32_e32 v52, 0
	v_mov_b32_e32 v53, 0
	v_mov_b32_e32 v54, 0
	v_mov_b32_e32 v55, 0
	v_mov_b32_e32 v56, 0
	v_mov_b32_e32 v57, 0
	v_mov_b32_e32 v58, 0
	v_mov_b32_e32 v59, 0
	v_mov_b32_e32 v60, 0
	v_mov_b32_e32 v61, 0
	v_mov_b32_e32 v62, 0
	v_mov_b32_e32 v63, 0
	v_mov_b32_e32 v64, 0
	v_mov_b32_e32 v65, 0
	v_mov_b32_e32 v66, 0
	v_mov_b32_e32 v67, 0
	v_mov_b32_e32 v68, 0
	v_mov_b32_e32 v69, 0
	v_mov_b32_e32 v70, 0
	v_mov_b32_e32 v71, 0
	v_mov_b32_e32 v72, 0
	v_mov_b32_e32 v73, 0
	v_mov_b32_e32 v74, 0
	v_mov_b32_e32 v75, 0
	v_mov_b32_e32 v76, 0
	v_mov_b32_e32 v77, 0
	v_mov_b32_e32 v78, 0
	v_mov_b32_e32 v79, 0
	v_mov_b32_e32 v80, 0
	v_mov_b32_e32 v81, 0
	v_mov_b32_e32 v82, 0
	v_mov_b32_e32 v83, 0
	v_mov_b32_e32 v84, 0
	v_mov_b32_e32 v85, 0
	v_mov_b32_e32 v86, 0
	v_mov_b32_e32 v87, 0
	v_mov_b32_e32 v88, 0
	v_mov_b32_e32 v89, 0
	v_mov_b32_e32 v90, 0
	v_mov_b32_e32 v91, 0
	v_mov_b32_e32 v92, 0
	v_mov_b32_e32 v93, 0
	v_mov_b32_e32 v94, 0
	v_mov_b32_e32 v95, 0
	v_mov_b32_e32 v96, 0
	v_mov_b32_e32 v97, 0
	v_mov_b32_e32 v98, 0
	v_mov_b32_e32 v99, 0
	v_mov_b32_e32 v100, 0
	v_mov_b32_e32 v101, 0
	v_mov_b32_e32 v102, 0
	v_mov_b32_e32 v103, 0
	v_mov_b32_e32 v104, 0
	v_mov_b32_e32 v105, 0
	v_mov_b32_e32 v106, 0
	v_mov_b32_e32 v107, 0
	v_mov_b32_e32 v108, 0
	v_mov_b32_e32 v109, 0
	v_mov_b32_e32 v110, 0
	v_mov_b32_e32 v111, 0
	v_mov_b32_e32 v112, 0
	v_mov_b32_e32 v113, 0
	v_mov_b32_e32 v114, 0
	v_mov_b32_e32 v115, 0
	v_mov_b32_e32 v116, 0
	v_mov_b32_e32 v117, 0
	v_mov_b32_e32 v118, 0
	v_mov_b32_e32 v119, 0
	v_mov_b32_e32 v120, 0
	v_mov_b32_e32 v121, 0
	v_mov_b32_e32 v122, 0
	v_mov_b32_e32 v123, 0
	v_mov_b32_e32 v124, 0
	v_mov_b32_e32 v125, 0
	v_mov_b32_e32 v126, 0
	v_mov_b32_e32 v127, 0
	v_mov_b32_e32 v128, 0
	v_mov_b32_e32 v129, 0
	s_setprio 0
	s_waitcnt vmcnt(12)
	s_barrier
	ds_read_b128 v[146:149], v136 offset:0
	ds_read_b128 v[152:155], v136 offset:1024
	ds_read_b128 v[156:159], v136 offset:2048
	ds_read_b128 v[162:165], v136 offset:3072
	ds_read_b128 v[166:169], v136 offset:4096
	ds_read_b128 v[170:173], v136 offset:5120
	ds_read_b128 v[176:179], v136 offset:6144
	ds_read_b128 v[180:183], v136 offset:7168
	ds_read_b128 v[184:187], v137 offset:16384
	ds_read_b128 v[188:191], v137 offset:17408
	ds_read_b128 v[192:195], v137 offset:18432
	ds_read_b128 v[196:199], v137 offset:19456
	s_movk_i32 s40, 0x6000
	s_mov_b32 s41, 0
	s_movk_i32 s39, 2
	.p2align 6

; #define LAS __attribute__((address_space(3)))
; DEVI int tidx() { int t = threadIdx.x; asm volatile("" : "+v"(t)); return t; }
;   const int tid = tidx(), lane = tid & 63, wid = tid >> 6;
;   const int wm = wid >> 1, wn = wid & 1, r16 = lane & 15, quad = lane >> 4;
;   f32x4 acc[4][8];
; #pragma unroll
;   for (int i = 0; i < 4; i++)
; #pragma unroll
;     for (int j = 0; j < 8; j++) acc[i][j] = (f32x4){0.f, 0.f, 0.f, 0.f};
;   const int nk = (nk_part < 0) ? (K >> 5) : nk_part;
;   const int lrow = tid >> 2, lpc = tid & 3;
;   const int lch = lpc ^ ((0x78 >> (((lrow >> 2) & 3) * 2)) & 3);
;   const u16* ga = A + (size_t)(m0 + lrow) * lda + kbeg + lch * 8;
;   const u16* gb = Bt + (size_t)(n0 + lrow) * K + kbeg + lch * 8;
;   const size_t ga1 = (size_t)64 * lda, gb1 = (size_t)64 * K;
;   const unsigned lds0 = (unsigned)(uintptr_t)(LAS char*)smem + (unsigned)__builtin_amdgcn_readfirstlane(wid) * 1024u;
;     ...
;   __syncthreads();
;   G2_STAGE(0); G2_STAGE(1);
; DEVI void run_phase(const Params& p, int ph, char* smem) {
;     ...
;           const int u_ = t - 512, tl_ = u_ / 8, q_ = u_ - tl_ * 8;
;           gemm_tile256<EPI_RESID_ATOMIC>(p, mix, 1024, Bt, 1024, (64 + (tl_ & 1)) * 256, (tl_ >> 1) * 128, nullptr, 0, smem, q_ * 128, 4, q_);
.LBB0_758:
	s_cmpk_gt_i32 s39, 0x1ff
	s_mov_b64 s[2:3], -1
	s_cbranch_scc0 .LBB0_812
	s_setprio 2
	s_sub_i32 s43, s39, 512
	s_lshr_b32 s42, s43, 3
	s_and_b32 s98, s43, 7
	s_lshr_b32 s15, s42, 1
	s_and_b32 s42, s42, 1
	s_add_i32 s42, s42, 64
	v_readlane_b32 s2, v250, 5
	v_readlane_b32 s3, v250, 6
	v_readlane_b32 s43, v254, 62
	s_mul_i32 s1, s42, 0x80000
	s_add_u32 s4, s2, s1
	s_addc_u32 s5, s3, 0
	s_add_u32 s4, s4, 0xb580000
	s_addc_u32 s5, s5, 0
	s_mul_i32 s1, s43, 0x200000
	s_mul_i32 s14, s15, 0x40000
	s_add_i32 s1, s1, s14
	s_add_u32 s10, s2, s1
	s_addc_u32 s11, s3, 0
	s_add_u32 s10, s10, 0x15e00000
	s_addc_u32 s11, s11, 0
	s_mul_i32 s1, s98, 256
	s_add_u32 s4, s4, s1
	s_addc_u32 s5, s5, 0
	s_mul_i32 s1, s98, 512
	s_add_u32 s10, s10, s1
	s_addc_u32 s11, s11, 0
	s_movk_i32 s0, 0x78
	v_lshrrev_b32_e32 v0, 2, v145
	v_and_b32_e32 v131, 3, v145
	v_bfe_u32 v136, v145, 4, 2
	v_lshlrev_b32_e32 v136, 1, v136
	v_lshrrev_b32_e64 v136, v136, s0
	v_and_b32_e32 v136, 3, v136
	v_xor_b32_e32 v131, v131, v136
	v_lshlrev_b32_e32 v131, 4, v131
	s_movk_i32 s14, 0x800
	v_mad_u32_u24 v0, v0, s14, v131
	v_bfe_u32 v137, v145, 2, 1
	s_movk_i32 s14, 0x7c0
	v_mul_u32_u24_e32 v136, s14, v137
	v_sub_u32_e32 v136, v0, v136
	v_mov_b32_e32 v137, 0
	v_lshl_add_u64 v[134:135], s[10:11], 0, v[136:137]
	v_bfe_u32 v137, v145, 2, 1
	s_mov_b32 s12, 64
	s_mov_b32 s13, 0
	v_lshl_add_u64 v[132:133], s[4:5], 0, v[0:1]
	v_bfe_u32 v136, v145, 2, 2
	v_lshlrev_b32_e32 v136, 1, v136
	v_lshrrev_b32_e64 v136, v136, s0
	v_and_b32_e32 v136, 3, v136
	v_bfe_u32 v137, v145, 4, 2
	v_xor_b32_e32 v136, v136, v137
	v_lshlrev_b32_e32 v136, 4, v136
	v_and_b32_e32 v131, 15, v145
	v_lshl_or_b32 v136, v131, 6, v136
	v_bfe_u32 v137, v145, 6, 1
	v_lshl_or_b32 v137, v137, 12, v136
	v_lshrrev_b32_e32 v0, 7, v145
	v_lshl_or_b32 v136, v0, 13, v136
	v_and_b32_e32 v140, 1, v131
	v_lshl_or_b32 v131, v0, 7, v131
	v_bfe_u32 v0, v145, 4, 2
	v_lshlrev_b32_e32 v0, 3, v0
	v_bfe_u32 v141, v145, 6, 1
	s_lshl_b32 s1, s42, 19
	s_lshl_b32 s14, s15, 8
	s_add_i32 s1, s1, s14
	s_add_u32 s4, s2, s1
	s_addc_u32 s5, s3, 0
	s_add_u32 s4, s4, 0x4200000
	s_addc_u32 s5, s5, 0
	v_lshlrev_b32_e32 v138, 11, v131
	v_lshl_add_u32 v138, v141, 7, v138
	v_bfe_u32 v139, v145, 4, 1
	v_lshl_add_u32 v138, v139, 5, v138
	v_bfe_u32 v139, v145, 5, 1
	v_lshl_add_u32 v138, v139, 4, v138
	v_mov_b32_e32 v139, 0
	v_lshl_add_u64 v[138:139], s[4:5], 0, v[138:139]
	s_and_b32 s1, s42, 1
	s_lshl_b32 s1, s1, 20
	s_lshl_b32 s14, s98, 21
	s_add_i32 s1, s1, s14
	s_lshl_b32 s14, s15, 9
	s_add_i32 s1, s1, s14
	s_add_u32 s10, s2, s1
	s_addc_u32 s11, s3, 0
	s_add_u32 s10, s10, 0x1dcc0000
	s_addc_u32 s11, s11, 0
	v_lshlrev_b32_e32 v140, 12, v131
	v_lshl_add_u32 v140, v141, 8, v140
	v_lshl_add_u32 v140, v0, 1, v140
	v_mov_b32_e32 v141, 0
	v_lshl_add_u64 v[140:141], s[10:11], 0, v[140:141]
	s_mov_b32 s2, 0x20000
	s_mov_b32 s3, 0
	v_lshrrev_b32_e32 v0, 6, v145
	v_lshlrev_b32_e32 v0, 10, v0
	s_nop 0
	v_readfirstlane_b32 s43, v0
	s_mov_b32 s40, m0
	s_mov_b32 s4, 128
	s_mov_b32 s5, 0
	s_barrier
	s_add_i32 s15, s43, 0x0
	s_mov_b32 m0, s15
	v_lshl_add_u64 v[142:143], v[132:133], 0, s[2:3]
	global_load_lds_dwordx4 v[132:133], off
	s_add_i32 m0, m0, 0x1000
	s_nop 0
	global_load_lds_dwordx4 v[142:143], off
	v_lshl_add_u64 v[142:143], v[142:143], 0, s[2:3]
	s_add_i32 m0, m0, 0x1000
	s_nop 0
	global_load_lds_dwordx4 v[142:143], off
	v_lshl_add_u64 v[142:143], v[142:143], 0, s[2:3]
	s_add_i32 m0, m0, 0x1000
	s_nop 0
	global_load_lds_dwordx4 v[142:143], off
	s_add_i32 m0, m0, 0x1000
	v_lshl_add_u64 v[142:143], v[134:135], 0, s[2:3]
	s_nop 0
	global_load_lds_dwordx4 v[134:135], off
	s_add_i32 m0, m0, 0x1000
	v_lshl_add_u64 v[132:133], v[132:133], 0, s[12:13]
	s_nop 0
	global_load_lds_dwordx4 v[142:143], off
	v_lshl_add_u64 v[134:135], v[134:135], 0, s[4:5]
	s_nop 0
	s_add_i32 s15, s43, 0x6000
	s_mov_b32 m0, s15
	v_lshl_add_u64 v[142:143], v[132:133], 0, s[2:3]
	global_load_lds_dwordx4 v[132:133], off
	s_add_i32 m0, m0, 0x1000
	s_nop 0
	global_load_lds_dwordx4 v[142:143], off
	v_lshl_add_u64 v[142:143], v[142:143], 0, s[2:3]
	s_add_i32 m0, m0, 0x1000
	s_nop 0
	global_load_lds_dwordx4 v[142:143], off
	v_lshl_add_u64 v[142:143], v[142:143], 0, s[2:3]
	s_add_i32 m0, m0, 0x1000
	s_nop 0
	global_load_lds_dwordx4 v[142:143], off
	s_add_i32 m0, m0, 0x1000
	v_lshl_add_u64 v[142:143], v[134:135], 0, s[2:3]
	s_nop 0
	global_load_lds_dwordx4 v[134:135], off
	s_add_i32 m0, m0, 0x1000
	v_lshl_add_u64 v[132:133], v[132:133], 0, s[12:13]
	s_nop 0
	global_load_lds_dwordx4 v[142:143], off
	v_lshl_add_u64 v[134:135], v[134:135], 0, s[4:5]
	s_nop 0
	s_add_i32 s15, s43, 0xc000
	s_mov_b32 m0, s15
	v_lshl_add_u64 v[142:143], v[132:133], 0, s[2:3]
	global_load_lds_dwordx4 v[132:133], off
	s_add_i32 m0, m0, 0x1000
	s_nop 0
	global_load_lds_dwordx4 v[142:143], off
	v_lshl_add_u64 v[142:143], v[142:143], 0, s[2:3]
	s_add_i32 m0, m0, 0x1000
	s_nop 0
	global_load_lds_dwordx4 v[142:143], off
	v_lshl_add_u64 v[142:143], v[142:143], 0, s[2:3]
	s_add_i32 m0, m0, 0x1000
	s_nop 0
	global_load_lds_dwordx4 v[142:143], off
	s_add_i32 m0, m0, 0x1000
	v_lshl_add_u64 v[142:143], v[134:135], 0, s[2:3]
	s_nop 0
	global_load_lds_dwordx4 v[134:135], off
	s_add_i32 m0, m0, 0x1000
	v_lshl_add_u64 v[132:133], v[132:133], 0, s[12:13]
	s_nop 0
	global_load_lds_dwordx4 v[142:143], off
	v_lshl_add_u64 v[134:135], v[134:135], 0, s[4:5]
	s_nop 0
	v_mov_b32_e32 v2, 0
	v_mov_b32_e32 v3, 0
	v_mov_b32_e32 v4, 0
	v_mov_b32_e32 v5, 0
	v_mov_b32_e32 v6, 0
	v_mov_b32_e32 v7, 0
	v_mov_b32_e32 v8, 0
	v_mov_b32_e32 v9, 0
	v_mov_b32_e32 v10, 0
	v_mov_b32_e32 v11, 0
	v_mov_b32_e32 v12, 0
	v_mov_b32_e32 v13, 0
	v_mov_b32_e32 v14, 0
; #define LAS __attribute__((address_space(3)))
;     ...
;   f32x4 acc[4][8];
; #pragma unroll
;   for (int i = 0; i < 4; i++)
; #pragma unroll
;     for (int j = 0; j < 8; j++) acc[i][j] = (f32x4){0.f, 0.f, 0.f, 0.f};
;   const int nk = (nk_part < 0) ? (K >> 5) : nk_part;
;   const int lrow = tid >> 2, lpc = tid & 3;
;   const int lch = lpc ^ ((0x78 >> (((lrow >> 2) & 3) * 2)) & 3);
;   const u16* ga = A + (size_t)(m0 + lrow) * lda + kbeg + lch * 8;
;   const u16* gb = Bt + (size_t)(n0 + lrow) * K + kbeg + lch * 8;
;   const size_t ga1 = (size_t)64 * lda, gb1 = (size_t)64 * K;
;   const unsigned lds0 = (unsigned)(uintptr_t)(LAS char*)smem + (unsigned)__builtin_amdgcn_readfirstlane(wid) * 1024u;
;     ...
;   __syncthreads();
;   G2_STAGE(0); G2_STAGE(1);
;   const int fsw = (0x78 >> (((r16 >> 2) & 3) * 2)) & 3;
;   const int aoff = (wm * 128 + r16) * 64 + ((quad ^ fsw) << 4);
;   const int boff = 16384 + (wn * 64 + r16) * 64 + ((quad ^ fsw) << 4);
;   for (int kt = 0; kt < nk; kt++) {
;     if (kt + 1 < nk) asm volatile("s_waitcnt vmcnt(6)" ::: "memory");
;     else asm volatile("s_waitcnt vmcnt(0)" ::: "memory");
;     __builtin_amdgcn_s_barrier();
;     asm volatile("" ::: "memory");
;     if (kt + 2 < nk) G2_STAGE(kt + 2);
;     const char* cS = smem + (kt % 3) * 24576;
;     bf16x8 xa[8], wb[4];
; #pragma unroll
;     for (int f = 0; f < 8; f++) xa[f] = *(const bf16x8*)(cS + aoff + f * 1024);
; #pragma unroll
;     for (int f = 0; f < 4; f++) wb[f] = *(const bf16x8*)(cS + boff + f * 1024);
; #pragma unroll
;     for (int nf = 0; nf < 4; nf++)
; #pragma unroll
;       for (int mf = 0; mf < 8; mf++)
;         acc[nf][mf] = __builtin_amdgcn_mfma_f32_16x16x32_bf16(wb[nf], xa[mf], acc[nf][mf], 0, 0, 0);
	v_mov_b32_e32 v15, 0
	v_mov_b32_e32 v16, 0
	v_mov_b32_e32 v17, 0
	v_mov_b32_e32 v18, 0
	v_mov_b32_e32 v19, 0
	v_mov_b32_e32 v20, 0
	v_mov_b32_e32 v21, 0
	v_mov_b32_e32 v22, 0
	v_mov_b32_e32 v23, 0
	v_mov_b32_e32 v24, 0
	v_mov_b32_e32 v25, 0
	v_mov_b32_e32 v26, 0
	v_mov_b32_e32 v27, 0
	v_mov_b32_e32 v28, 0
	v_mov_b32_e32 v29, 0
	v_mov_b32_e32 v30, 0
	v_mov_b32_e32 v31, 0
	v_mov_b32_e32 v32, 0
	v_mov_b32_e32 v33, 0
	v_mov_b32_e32 v34, 0
	v_mov_b32_e32 v35, 0
	v_mov_b32_e32 v36, 0
	v_mov_b32_e32 v37, 0
	v_mov_b32_e32 v38, 0
	v_mov_b32_e32 v39, 0
	v_mov_b32_e32 v40, 0
	v_mov_b32_e32 v41, 0
	v_mov_b32_e32 v42, 0
	v_mov_b32_e32 v43, 0
	v_mov_b32_e32 v44, 0
	v_mov_b32_e32 v45, 0
	v_mov_b32_e32 v46, 0
	v_mov_b32_e32 v47, 0
	v_mov_b32_e32 v48, 0
	v_mov_b32_e32 v49, 0
	v_mov_b32_e32 v50, 0
	v_mov_b32_e32 v51, 0
	v_mov_b32_e32 v52, 0
	v_mov_b32_e32 v53, 0
	v_mov_b32_e32 v54, 0
	v_mov_b32_e32 v55, 0
	v_mov_b32_e32 v56, 0
	v_mov_b32_e32 v57, 0
	v_mov_b32_e32 v58, 0
	v_mov_b32_e32 v59, 0
	v_mov_b32_e32 v60, 0
	v_mov_b32_e32 v61, 0
	v_mov_b32_e32 v62, 0
	v_mov_b32_e32 v63, 0
	v_mov_b32_e32 v64, 0
	v_mov_b32_e32 v65, 0
	v_mov_b32_e32 v66, 0
	v_mov_b32_e32 v67, 0
	v_mov_b32_e32 v68, 0
	v_mov_b32_e32 v69, 0
	v_mov_b32_e32 v70, 0
	v_mov_b32_e32 v71, 0
	v_mov_b32_e32 v72, 0
	v_mov_b32_e32 v73, 0
	v_mov_b32_e32 v74, 0
	v_mov_b32_e32 v75, 0
	v_mov_b32_e32 v76, 0
	v_mov_b32_e32 v77, 0
	v_mov_b32_e32 v78, 0
	v_mov_b32_e32 v79, 0
	v_mov_b32_e32 v80, 0
	v_mov_b32_e32 v81, 0
	v_mov_b32_e32 v82, 0
	v_mov_b32_e32 v83, 0
	v_mov_b32_e32 v84, 0
	v_mov_b32_e32 v85, 0
	v_mov_b32_e32 v86, 0
	v_mov_b32_e32 v87, 0
	v_mov_b32_e32 v88, 0
	v_mov_b32_e32 v89, 0
	v_mov_b32_e32 v90, 0
	v_mov_b32_e32 v91, 0
	v_mov_b32_e32 v92, 0
	v_mov_b32_e32 v93, 0
	v_mov_b32_e32 v94, 0
	v_mov_b32_e32 v95, 0
	v_mov_b32_e32 v96, 0
	v_mov_b32_e32 v97, 0
	v_mov_b32_e32 v98, 0
	v_mov_b32_e32 v99, 0
	v_mov_b32_e32 v100, 0
	v_mov_b32_e32 v101, 0
	v_mov_b32_e32 v102, 0
	v_mov_b32_e32 v103, 0
	v_mov_b32_e32 v104, 0
	v_mov_b32_e32 v105, 0
	v_mov_b32_e32 v106, 0
	v_mov_b32_e32 v107, 0
	v_mov_b32_e32 v108, 0
	v_mov_b32_e32 v109, 0
	v_mov_b32_e32 v110, 0
	v_mov_b32_e32 v111, 0
	v_mov_b32_e32 v112, 0
	v_mov_b32_e32 v113, 0
	v_mov_b32_e32 v114, 0
	v_mov_b32_e32 v115, 0
	v_mov_b32_e32 v116, 0
	v_mov_b32_e32 v117, 0
	v_mov_b32_e32 v118, 0
	v_mov_b32_e32 v119, 0
	v_mov_b32_e32 v120, 0
	v_mov_b32_e32 v121, 0
	v_mov_b32_e32 v122, 0
	v_mov_b32_e32 v123, 0
	v_mov_b32_e32 v124, 0
	v_mov_b32_e32 v125, 0
	v_mov_b32_e32 v126, 0
	v_mov_b32_e32 v127, 0
	v_mov_b32_e32 v128, 0
	v_mov_b32_e32 v129, 0
	s_setprio 0
	s_waitcnt vmcnt(12)
	s_barrier
	ds_read_b128 v[146:149], v136 offset:0
	ds_read_b128 v[152:155], v136 offset:1024
	ds_read_b128 v[156:159], v136 offset:2048
	ds_read_b128 v[162:165], v136 offset:3072
	ds_read_b128 v[166:169], v136 offset:4096
	ds_read_b128 v[170:173], v136 offset:5120
	ds_read_b128 v[176:179], v136 offset:6144
	ds_read_b128 v[180:183], v136 offset:7168
	ds_read_b128 v[184:187], v137 offset:16384
	ds_read_b128 v[188:191], v137 offset:17408
	ds_read_b128 v[192:195], v137 offset:18432
	ds_read_b128 v[196:199], v137 offset:19456
	s_movk_i32 s1, 0x6000
	s_mov_b32 s14, 0
	.p2align 3
	s_waitcnt vmcnt(6) lgkmcnt(0)
	s_barrier
	s_setprio 1
	v_add_u32_e32 v144, s1, v136
	v_mfma_f32_16x16x32_bf16 v[126:129], v[184:187], v[146:149], v[126:129]
	ds_read_b128 v[200:203], v144 offset:0
	v_mfma_f32_16x16x32_bf16 v[122:125], v[184:187], v[152:155], v[122:125]
	ds_read_b128 v[204:207], v144 offset:1024
	v_mfma_f32_16x16x32_bf16 v[118:121], v[184:187], v[156:159], v[118:121]
	ds_read_b128 v[208:211], v144 offset:2048
	v_mfma_f32_16x16x32_bf16 v[114:117], v[184:187], v[162:165], v[114:117]
	ds_read_b128 v[212:215], v144 offset:3072
	v_mfma_f32_16x16x32_bf16 v[110:113], v[184:187], v[166:169], v[110:113]
	ds_read_b128 v[216:219], v144 offset:4096
	v_mfma_f32_16x16x32_bf16 v[106:109], v[184:187], v[170:173], v[106:109]
	ds_read_b128 v[220:223], v144 offset:5120
	v_mfma_f32_16x16x32_bf16 v[102:105], v[184:187], v[176:179], v[102:105]
	ds_read_b128 v[224:227], v144 offset:6144
	v_mfma_f32_16x16x32_bf16 v[98:101], v[184:187], v[180:183], v[98:101]
	ds_read_b128 v[228:231], v144 offset:7168
	v_mfma_f32_16x16x32_bf16 v[94:97], v[188:191], v[146:149], v[94:97]
	v_add_u32_e64 v144, s1, v137
	v_mfma_f32_16x16x32_bf16 v[90:93], v[188:191], v[152:155], v[90:93]
	v_mfma_f32_16x16x32_bf16 v[86:89], v[188:191], v[156:159], v[86:89]
	ds_read_b128 v[232:235], v144 offset:16384
	v_mfma_f32_16x16x32_bf16 v[82:85], v[188:191], v[162:165], v[82:85]
	ds_read_b128 v[236:239], v144 offset:17408
	v_mfma_f32_16x16x32_bf16 v[78:81], v[188:191], v[166:169], v[78:81]
	ds_read_b128 v[240:243], v144 offset:18432
	v_mfma_f32_16x16x32_bf16 v[74:77], v[188:191], v[170:173], v[74:77]
	ds_read_b128 v[244:247], v144 offset:19456
	v_mfma_f32_16x16x32_bf16 v[70:73], v[188:191], v[176:179], v[70:73]
	s_add_i32 s15, s43, s14
	s_mov_b32 m0, s15
	v_lshl_add_u64 v[142:143], v[132:133], 0, s[2:3]
	v_mfma_f32_16x16x32_bf16 v[66:69], v[188:191], v[180:183], v[66:69]
	global_load_lds_dwordx4 v[132:133], off
	s_add_i32 m0, m0, 0x1000
	v_mfma_f32_16x16x32_bf16 v[62:65], v[192:195], v[146:149], v[62:65]
	v_mfma_f32_16x16x32_bf16 v[58:61], v[192:195], v[152:155], v[58:61]
	v_mfma_f32_16x16x32_bf16 v[54:57], v[192:195], v[156:159], v[54:57]
	global_load_lds_dwordx4 v[142:143], off
	v_lshl_add_u64 v[142:143], v[142:143], 0, s[2:3]
	s_add_i32 m0, m0, 0x1000
	v_mfma_f32_16x16x32_bf16 v[50:53], v[192:195], v[162:165], v[50:53]
	v_mfma_f32_16x16x32_bf16 v[46:49], v[192:195], v[166:169], v[46:49]
	v_mfma_f32_16x16x32_bf16 v[42:45], v[192:195], v[170:173], v[42:45]
	global_load_lds_dwordx4 v[142:143], off
	v_lshl_add_u64 v[142:143], v[142:143], 0, s[2:3]
	s_add_i32 m0, m0, 0x1000
	v_mfma_f32_16x16x32_bf16 v[38:41], v[192:195], v[176:179], v[38:41]
	v_mfma_f32_16x16x32_bf16 v[34:37], v[192:195], v[180:183], v[34:37]
	v_mfma_f32_16x16x32_bf16 v[30:33], v[196:199], v[146:149], v[30:33]
	global_load_lds_dwordx4 v[142:143], off
	s_add_i32 m0, m0, 0x1000
	v_lshl_add_u64 v[142:143], v[134:135], 0, s[2:3]
	v_mfma_f32_16x16x32_bf16 v[26:29], v[196:199], v[152:155], v[26:29]
	v_mfma_f32_16x16x32_bf16 v[22:25], v[196:199], v[156:159], v[22:25]
	v_mfma_f32_16x16x32_bf16 v[18:21], v[196:199], v[162:165], v[18:21]
	global_load_lds_dwordx4 v[134:135], off
	s_add_i32 m0, m0, 0x1000
	v_lshl_add_u64 v[132:133], v[132:133], 0, s[12:13]
	v_mfma_f32_16x16x32_bf16 v[14:17], v[196:199], v[166:169], v[14:17]
	v_mfma_f32_16x16x32_bf16 v[10:13], v[196:199], v[170:173], v[10:13]
	v_mfma_f32_16x16x32_bf16 v[6:9], v[196:199], v[176:179], v[6:9]
	global_load_lds_dwordx4 v[142:143], off
	v_lshl_add_u64 v[134:135], v[134:135], 0, s[4:5]
	v_mfma_f32_16x16x32_bf16 v[2:5], v[196:199], v[180:183], v[2:5]
	s_setprio 0
	s_mov_b32 s14, s1
	s_add_i32 s1, s1, 0x6000
	s_cmp_eq_u32 s1, 0x12000
	s_cselect_b32 s1, 0, s1
	s_nop 0
	.p2align 3
	s_waitcnt vmcnt(6) lgkmcnt(0)
	s_barrier
;     ...
;   for (int kt = 0; kt < nk; kt++) {
;     if (kt + 1 < nk) asm volatile("s_waitcnt vmcnt(6)" ::: "memory");
;     else asm volatile("s_waitcnt vmcnt(0)" ::: "memory");
;     __builtin_amdgcn_s_barrier();
;     asm volatile("" ::: "memory");
;     if (kt + 2 < nk) G2_STAGE(kt + 2);
;     const char* cS = smem + (kt % 3) * 24576;
;     bf16x8 xa[8], wb[4];
; #pragma unroll
;     for (int f = 0; f < 8; f++) xa[f] = *(const bf16x8*)(cS + aoff + f * 1024);
; #pragma unroll
;     for (int f = 0; f < 4; f++) wb[f] = *(const bf16x8*)(cS + boff + f * 1024);
; #pragma unroll
;     for (int nf = 0; nf < 4; nf++)
; #pragma unroll
;       for (int mf = 0; mf < 8; mf++)
;         acc[nf][mf] = __builtin_amdgcn_mfma_f32_16x16x32_bf16(wb[nf], xa[mf], acc[nf][mf], 0, 0, 0);
	s_setprio 1
	v_add_u32_e32 v144, s1, v136
	v_mfma_f32_16x16x32_bf16 v[126:129], v[232:235], v[200:203], v[126:129]
	ds_read_b128 v[146:149], v144 offset:0
	v_mfma_f32_16x16x32_bf16 v[122:125], v[232:235], v[204:207], v[122:125]
	ds_read_b128 v[152:155], v144 offset:1024
	v_mfma_f32_16x16x32_bf16 v[118:121], v[232:235], v[208:211], v[118:121]
	ds_read_b128 v[156:159], v144 offset:2048
	v_mfma_f32_16x16x32_bf16 v[114:117], v[232:235], v[212:215], v[114:117]
	ds_read_b128 v[162:165], v144 offset:3072
	v_mfma_f32_16x16x32_bf16 v[110:113], v[232:235], v[216:219], v[110:113]
	ds_read_b128 v[166:169], v144 offset:4096
	v_mfma_f32_16x16x32_bf16 v[106:109], v[232:235], v[220:223], v[106:109]
	ds_read_b128 v[170:173], v144 offset:5120
	v_mfma_f32_16x16x32_bf16 v[102:105], v[232:235], v[224:227], v[102:105]
	ds_read_b128 v[176:179], v144 offset:6144
	v_mfma_f32_16x16x32_bf16 v[98:101], v[232:235], v[228:231], v[98:101]
	ds_read_b128 v[180:183], v144 offset:7168
	v_mfma_f32_16x16x32_bf16 v[94:97], v[236:239], v[200:203], v[94:97]
	v_add_u32_e64 v144, s1, v137
	v_mfma_f32_16x16x32_bf16 v[90:93], v[236:239], v[204:207], v[90:93]
	v_mfma_f32_16x16x32_bf16 v[86:89], v[236:239], v[208:211], v[86:89]
	ds_read_b128 v[184:187], v144 offset:16384
	v_mfma_f32_16x16x32_bf16 v[82:85], v[236:239], v[212:215], v[82:85]
	ds_read_b128 v[188:191], v144 offset:17408
	v_mfma_f32_16x16x32_bf16 v[78:81], v[236:239], v[216:219], v[78:81]
	ds_read_b128 v[192:195], v144 offset:18432
	v_mfma_f32_16x16x32_bf16 v[74:77], v[236:239], v[220:223], v[74:77]
	ds_read_b128 v[196:199], v144 offset:19456
	v_mfma_f32_16x16x32_bf16 v[70:73], v[236:239], v[224:227], v[70:73]
	v_mfma_f32_16x16x32_bf16 v[66:69], v[236:239], v[228:231], v[66:69]
	v_mfma_f32_16x16x32_bf16 v[62:65], v[240:243], v[200:203], v[62:65]
	v_mfma_f32_16x16x32_bf16 v[58:61], v[240:243], v[204:207], v[58:61]
	v_mfma_f32_16x16x32_bf16 v[54:57], v[240:243], v[208:211], v[54:57]
	v_mfma_f32_16x16x32_bf16 v[50:53], v[240:243], v[212:215], v[50:53]
	v_mfma_f32_16x16x32_bf16 v[46:49], v[240:243], v[216:219], v[46:49]
	v_mfma_f32_16x16x32_bf16 v[42:45], v[240:243], v[220:223], v[42:45]
	v_mfma_f32_16x16x32_bf16 v[38:41], v[240:243], v[224:227], v[38:41]
	v_mfma_f32_16x16x32_bf16 v[34:37], v[240:243], v[228:231], v[34:37]
	v_mfma_f32_16x16x32_bf16 v[30:33], v[244:247], v[200:203], v[30:33]
	v_mfma_f32_16x16x32_bf16 v[26:29], v[244:247], v[204:207], v[26:29]
	v_mfma_f32_16x16x32_bf16 v[22:25], v[244:247], v[208:211], v[22:25]
	v_mfma_f32_16x16x32_bf16 v[18:21], v[244:247], v[212:215], v[18:21]
	v_mfma_f32_16x16x32_bf16 v[14:17], v[244:247], v[216:219], v[14:17]
	v_mfma_f32_16x16x32_bf16 v[10:13], v[244:247], v[220:223], v[10:13]
	v_mfma_f32_16x16x32_bf16 v[6:9], v[244:247], v[224:227], v[6:9]
	v_mfma_f32_16x16x32_bf16 v[2:5], v[244:247], v[228:231], v[2:5]
	s_setprio 0
	s_mov_b32 s14, s1
	s_add_i32 s1, s1, 0x6000
	s_cmp_eq_u32 s1, 0x12000
	s_cselect_b32 s1, 0, s1
	s_nop 0
	.p2align 3
	s_waitcnt vmcnt(0) lgkmcnt(0)
	s_barrier
	s_setprio 1
	v_add_u32_e32 v144, s1, v136
	v_mfma_f32_16x16x32_bf16 v[126:129], v[184:187], v[146:149], v[126:129]
	ds_read_b128 v[200:203], v144 offset:0
	v_mfma_f32_16x16x32_bf16 v[122:125], v[184:187], v[152:155], v[122:125]
	ds_read_b128 v[204:207], v144 offset:1024
	v_mfma_f32_16x16x32_bf16 v[118:121], v[184:187], v[156:159], v[118:121]
	ds_read_b128 v[208:211], v144 offset:2048
	v_mfma_f32_16x16x32_bf16 v[114:117], v[184:187], v[162:165], v[114:117]
	ds_read_b128 v[212:215], v144 offset:3072
	v_mfma_f32_16x16x32_bf16 v[110:113], v[184:187], v[166:169], v[110:113]
	ds_read_b128 v[216:219], v144 offset:4096
	v_mfma_f32_16x16x32_bf16 v[106:109], v[184:187], v[170:173], v[106:109]
	ds_read_b128 v[220:223], v144 offset:5120
	v_mfma_f32_16x16x32_bf16 v[102:105], v[184:187], v[176:179], v[102:105]
	ds_read_b128 v[224:227], v144 offset:6144
	v_mfma_f32_16x16x32_bf16 v[98:101], v[184:187], v[180:183], v[98:101]
	ds_read_b128 v[228:231], v144 offset:7168
	v_mfma_f32_16x16x32_bf16 v[94:97], v[188:191], v[146:149], v[94:97]
	v_add_u32_e64 v144, s1, v137
	v_mfma_f32_16x16x32_bf16 v[90:93], v[188:191], v[152:155], v[90:93]
	v_mfma_f32_16x16x32_bf16 v[86:89], v[188:191], v[156:159], v[86:89]
	ds_read_b128 v[232:235], v144 offset:16384
	v_mfma_f32_16x16x32_bf16 v[82:85], v[188:191], v[162:165], v[82:85]
	ds_read_b128 v[236:239], v144 offset:17408
	v_mfma_f32_16x16x32_bf16 v[78:81], v[188:191], v[166:169], v[78:81]
	ds_read_b128 v[240:243], v144 offset:18432
	v_mfma_f32_16x16x32_bf16 v[74:77], v[188:191], v[170:173], v[74:77]
	ds_read_b128 v[244:247], v144 offset:19456
	v_mfma_f32_16x16x32_bf16 v[70:73], v[188:191], v[176:179], v[70:73]
	v_mfma_f32_16x16x32_bf16 v[66:69], v[188:191], v[180:183], v[66:69]
	v_mfma_f32_16x16x32_bf16 v[62:65], v[192:195], v[146:149], v[62:65]
	v_mfma_f32_16x16x32_bf16 v[58:61], v[192:195], v[152:155], v[58:61]
	v_mfma_f32_16x16x32_bf16 v[54:57], v[192:195], v[156:159], v[54:57]
	v_mfma_f32_16x16x32_bf16 v[50:53], v[192:195], v[162:165], v[50:53]
	v_mfma_f32_16x16x32_bf16 v[46:49], v[192:195], v[166:169], v[46:49]
	v_mfma_f32_16x16x32_bf16 v[42:45], v[192:195], v[170:173], v[42:45]
	v_mfma_f32_16x16x32_bf16 v[38:41], v[192:195], v[176:179], v[38:41]
	v_mfma_f32_16x16x32_bf16 v[34:37], v[192:195], v[180:183], v[34:37]
	v_mfma_f32_16x16x32_bf16 v[30:33], v[196:199], v[146:149], v[30:33]
	v_mfma_f32_16x16x32_bf16 v[26:29], v[196:199], v[152:155], v[26:29]
	v_mfma_f32_16x16x32_bf16 v[22:25], v[196:199], v[156:159], v[22:25]
	v_mfma_f32_16x16x32_bf16 v[18:21], v[196:199], v[162:165], v[18:21]
	v_mfma_f32_16x16x32_bf16 v[14:17], v[196:199], v[166:169], v[14:17]
	v_mfma_f32_16x16x32_bf16 v[10:13], v[196:199], v[170:173], v[10:13]
	v_mfma_f32_16x16x32_bf16 v[6:9], v[196:199], v[176:179], v[6:9]
	v_mfma_f32_16x16x32_bf16 v[2:5], v[196:199], v[180:183], v[2:5]
	s_setprio 0
	s_mov_b32 s14, s1
	s_add_i32 s1, s1, 0x6000
	s_cmp_eq_u32 s1, 0x12000
	s_cselect_b32 s1, 0, s1
	s_nop 0
	s_mov_b32 s4, 0x8000
	s_mov_b32 s5, 0
	s_mov_b32 s10, 0x10000
	s_mov_b32 s11, 0
	s_mov_b32 s41, 0x3fd744fd
	.p2align 3
	s_waitcnt lgkmcnt(0)
; DEVI unsigned pack2(float a, float b) { return __builtin_bit_cast(unsigned, __builtin_convertvector((f32x2_t){a, b}, bf16x2_t)); }
; DEVI float blo(unsigned u) { return __uint_as_float(u << 16); }
; DEVI float bhi(unsigned u) { return __uint_as_float(u & 0xffff0000u); }
; DEVI float siluf_(float x) { return x * __builtin_amdgcn_rcpf(1.f + __expf(-x)); }
;     ...
;     for (int nf = 0; nf < 4; nf++)
; #pragma unroll
;       for (int mf = 0; mf < 8; mf++)
;         acc[nf][mf] = __builtin_amdgcn_mfma_f32_16x16x32_bf16(wb[nf], xa[mf], acc[nf][mf], 0, 0, 0);
;   }
;     ...
; #pragma unroll
;   for (int mf = 0; mf < 8; mf++) {
;     const int row = m0 + wm * 128 + mf * 16 + r16;
;     if (EPI == EPI_SWIGLU) {
; #pragma unroll
;       for (int nf = 0; nf < 2; nf++) {
;         const int hcol = (n0 >> 1) + wn * 32 + nf * 16 + quad * 4;
;         f32x4 g = acc[nf][mf], u = acc[nf + 2][mf];
;         u32x2 pk;
;         pk[0] = pack2(siluf_(g[0]) * u[0], siluf_(g[1]) * u[1]);
;         pk[1] = pack2(siluf_(g[2]) * u[2], siluf_(g[3]) * u[3]);
;         *(u32x2*)(outb + (size_t)row * DFF + hcol) = pk;
;       }
;     } else {
; #pragma unroll
;       for (int nf = 0; nf < 4; nf++) {
;         const int col = n0 + wn * 64 + nf * 16 + quad * 4;
;         f32x4 a = acc[nf][mf];
;         if (EPI == EPI_RESID || EPI == EPI_RESID_ATOMIC) {
;           f32x4 x = a;
;           if (EPI == EPI_RESID || kpart == 0) {
;             const u32x2 xr = *(const u32x2*)((const u16*)(p.ws + WS_XB) + (size_t)row * 1024 + col);
;             x[0] += ALPHA * blo(xr[0]); x[1] += ALPHA * bhi(xr[0]); x[2] += ALPHA * blo(xr[1]); x[3] += ALPHA * bhi(xr[1]);
;           }
;           if (EPI == EPI_RESID) *(f32x4*)((float*)(p.ws + WS_XF) + (size_t)row * 1024 + col) = x;
;           else *(f32x4*)((float*)(p.ws + WS_SLAB) + ((size_t)kpart * 512 + (row - T_P)) * 1024 + col) = x;
	s_nop 0
	v_mfma_f32_16x16x32_bf16 v[126:129], v[232:235], v[200:203], v[126:129]
	v_mfma_f32_16x16x32_bf16 v[122:125], v[232:235], v[204:207], v[122:125]
	v_mfma_f32_16x16x32_bf16 v[118:121], v[232:235], v[208:211], v[118:121]
	v_mfma_f32_16x16x32_bf16 v[114:117], v[232:235], v[212:215], v[114:117]
	v_mfma_f32_16x16x32_bf16 v[110:113], v[232:235], v[216:219], v[110:113]
	v_mfma_f32_16x16x32_bf16 v[106:109], v[232:235], v[220:223], v[106:109]
	v_mfma_f32_16x16x32_bf16 v[102:105], v[232:235], v[224:227], v[102:105]
	v_mfma_f32_16x16x32_bf16 v[98:101], v[232:235], v[228:231], v[98:101]
	v_mfma_f32_16x16x32_bf16 v[94:97], v[236:239], v[200:203], v[94:97]
	v_mfma_f32_16x16x32_bf16 v[90:93], v[236:239], v[204:207], v[90:93]
	v_mfma_f32_16x16x32_bf16 v[86:89], v[236:239], v[208:211], v[86:89]
	v_mfma_f32_16x16x32_bf16 v[82:85], v[236:239], v[212:215], v[82:85]
	v_mfma_f32_16x16x32_bf16 v[78:81], v[236:239], v[216:219], v[78:81]
	v_mfma_f32_16x16x32_bf16 v[74:77], v[236:239], v[220:223], v[74:77]
	v_mfma_f32_16x16x32_bf16 v[70:73], v[236:239], v[224:227], v[70:73]
	v_mfma_f32_16x16x32_bf16 v[66:69], v[236:239], v[228:231], v[66:69]
	v_mfma_f32_16x16x32_bf16 v[62:65], v[240:243], v[200:203], v[62:65]
	v_mfma_f32_16x16x32_bf16 v[58:61], v[240:243], v[204:207], v[58:61]
	v_mfma_f32_16x16x32_bf16 v[54:57], v[240:243], v[208:211], v[54:57]
	v_mfma_f32_16x16x32_bf16 v[50:53], v[240:243], v[212:215], v[50:53]
	v_mfma_f32_16x16x32_bf16 v[46:49], v[240:243], v[216:219], v[46:49]
	v_mfma_f32_16x16x32_bf16 v[42:45], v[240:243], v[220:223], v[42:45]
	v_mfma_f32_16x16x32_bf16 v[38:41], v[240:243], v[224:227], v[38:41]
	v_mfma_f32_16x16x32_bf16 v[34:37], v[240:243], v[228:231], v[34:37]
	v_mfma_f32_16x16x32_bf16 v[30:33], v[244:247], v[200:203], v[30:33]
	v_mfma_f32_16x16x32_bf16 v[26:29], v[244:247], v[204:207], v[26:29]
	v_mfma_f32_16x16x32_bf16 v[22:25], v[244:247], v[208:211], v[22:25]
	v_mfma_f32_16x16x32_bf16 v[18:21], v[244:247], v[212:215], v[18:21]
	v_mfma_f32_16x16x32_bf16 v[14:17], v[244:247], v[216:219], v[14:17]
	v_mfma_f32_16x16x32_bf16 v[10:13], v[244:247], v[220:223], v[10:13]
	v_mfma_f32_16x16x32_bf16 v[6:9], v[244:247], v[224:227], v[6:9]
	v_mfma_f32_16x16x32_bf16 v[2:5], v[244:247], v[228:231], v[2:5]
	s_mov_b32 m0, s40
	s_cmp_eq_u32 s98, 0
	s_cbranch_scc1 .Lta4_first
	s_nop 7
	global_store_dwordx4 v[140:141], v[126:129], off offset:0
	global_store_dwordx4 v[140:141], v[94:97], off offset:64
	global_store_dwordx4 v[140:141], v[62:65], off offset:128
	global_store_dwordx4 v[140:141], v[30:33], off offset:192
	v_lshl_add_u64 v[140:141], v[140:141], 0, s[10:11]
	global_store_dwordx4 v[140:141], v[122:125], off offset:0
	global_store_dwordx4 v[140:141], v[90:93], off offset:64
	global_store_dwordx4 v[140:141], v[58:61], off offset:128
	global_store_dwordx4 v[140:141], v[26:29], off offset:192
	v_lshl_add_u64 v[140:141], v[140:141], 0, s[10:11]
	global_store_dwordx4 v[140:141], v[118:121], off offset:0
	global_store_dwordx4 v[140:141], v[86:89], off offset:64
	global_store_dwordx4 v[140:141], v[54:57], off offset:128
	global_store_dwordx4 v[140:141], v[22:25], off offset:192
	v_lshl_add_u64 v[140:141], v[140:141], 0, s[10:11]
	global_store_dwordx4 v[140:141], v[114:117], off offset:0
	global_store_dwordx4 v[140:141], v[82:85], off offset:64
	global_store_dwordx4 v[140:141], v[50:53], off offset:128
	global_store_dwordx4 v[140:141], v[18:21], off offset:192
	v_lshl_add_u64 v[140:141], v[140:141], 0, s[10:11]
	global_store_dwordx4 v[140:141], v[110:113], off offset:0
	global_store_dwordx4 v[140:141], v[78:81], off offset:64
	global_store_dwordx4 v[140:141], v[46:49], off offset:128
	global_store_dwordx4 v[140:141], v[14:17], off offset:192
	v_lshl_add_u64 v[140:141], v[140:141], 0, s[10:11]
	global_store_dwordx4 v[140:141], v[106:109], off offset:0
	global_store_dwordx4 v[140:141], v[74:77], off offset:64
	global_store_dwordx4 v[140:141], v[42:45], off offset:128
	global_store_dwordx4 v[140:141], v[10:13], off offset:192
	v_lshl_add_u64 v[140:141], v[140:141], 0, s[10:11]
	global_store_dwordx4 v[140:141], v[102:105], off offset:0
	global_store_dwordx4 v[140:141], v[70:73], off offset:64
	global_store_dwordx4 v[140:141], v[38:41], off offset:128
	global_store_dwordx4 v[140:141], v[6:9], off offset:192
	v_lshl_add_u64 v[140:141], v[140:141], 0, s[10:11]
	global_store_dwordx4 v[140:141], v[98:101], off offset:0
	global_store_dwordx4 v[140:141], v[66:69], off offset:64
	global_store_dwordx4 v[140:141], v[34:37], off offset:128
	global_store_dwordx4 v[140:141], v[2:5], off offset:192
	v_readlane_b32 s0, v250, 7
	s_cmpk_lg_u32 s0, 0x200
	s_cbranch_scc1 .Lta4_ar1
	s_mov_b32 s0, 1
	v_writelane_b32 v255, s0, 41
	v_readlane_b32 s1, v250, 0
	s_lshr_b32 s14, s1, 3
	s_and_b32 s1, s1, 7
	s_lshl_b32 s1, s1, 6
	s_add_i32 s1, s1, s14
	s_sub_i32 s39, s1, 0x200

; #define LAS __attribute__((address_space(3)))
; DEVI int tidx() { int t = threadIdx.x; asm volatile("" : "+v"(t)); return t; }
; DEVI int xcd_first_tile() { return (blockIdx.x & 7) * (gridDim.x >> 3) + (blockIdx.x >> 3); }
;   const int tid = tidx(), lane = tid & 63, wid = tid >> 6;
;   const int wm = wid >> 1, wn = wid & 1, r16 = lane & 15, quad = lane >> 4;
;   f32x4 acc[4][8];
; #pragma unroll
;   for (int i = 0; i < 4; i++)
; #pragma unroll
;     for (int j = 0; j < 8; j++) acc[i][j] = (f32x4){0.f, 0.f, 0.f, 0.f};
;   const int nk = (nk_part < 0) ? (K >> 5) : nk_part;
;   const int lrow = tid >> 2, lpc = tid & 3;
;   const int lch = lpc ^ ((0x78 >> (((lrow >> 2) & 3) * 2)) & 3);
;   const u16* ga = A + (size_t)(m0 + lrow) * lda + kbeg + lch * 8;
;   const u16* gb = Bt + (size_t)(n0 + lrow) * K + kbeg + lch * 8;
;   const size_t ga1 = (size_t)64 * lda, gb1 = (size_t)64 * K;
;   const unsigned lds0 = (unsigned)(uintptr_t)(LAS char*)smem + (unsigned)__builtin_amdgcn_readfirstlane(wid) * 1024u;
; DEVI void run_phase(const Params& p, int ph, char* smem) {
;     ...
;       for (int t = xcd_first_tile(); t < 512 + 16 * 8; t += xcd_tile_step()) {
;         if (t < 512) {
;           int mt_, nt_; tile_coords(t, 64, 8, mt_, nt_);
;           gemm_tile256<EPI_RESID>(p, mix, 1024, Bt, 1024, mt_ * 256, nt_ * 128, nullptr, 0, smem);
.LBB0_812:
	s_and_b64 vcc, exec, s[2:3]
	s_cbranch_vccz .LBB0_757
	s_setprio 2
	v_readlane_b32 s40, v250, 7
	s_cmpk_lg_u32 s40, 0x200
	s_cbranch_scc1 .Lt4_go
	v_readlane_b32 s41, v255, 41
	s_cmp_lg_u32 s41, 0
	s_cbranch_scc1 .Lt4_go
	v_readlane_b32 s41, v250, 0
	s_lshr_b32 s42, s41, 3
	s_cmp_lt_u32 s42, 16
	s_cbranch_scc0 .Lt4_go
	s_and_b32 s41, s41, 7
	s_mul_i32 s41, s41, 16
	s_add_i32 s39, s41, s42
	s_branch .LBB0_757
.Lt4_go:
	s_lshr_b32 s46, s39, 6
	s_and_b32 s47, s39, 63
	s_lshr_b32 s43, s47, 3
	s_and_b32 s47, s47, 7
	s_lshl_b32 s46, s46, 3
	s_add_i32 s46, s46, s47
	v_readlane_b32 s2, v250, 5
	v_readlane_b32 s3, v250, 6
	v_readlane_b32 s47, v254, 62
	s_mul_i32 s41, s46, 0x80000
	s_add_u32 s4, s2, s41
	s_addc_u32 s5, s3, 0
	s_add_u32 s4, s4, 0xb580000
	s_addc_u32 s5, s5, 0
	s_mul_i32 s41, s47, 0x200000
	s_mul_i32 s42, s43, 0x40000
	s_add_i32 s41, s41, s42
	s_add_u32 s10, s2, s41
	s_addc_u32 s11, s3, 0
	s_add_u32 s10, s10, 0x15e00000
	s_addc_u32 s11, s11, 0
	s_movk_i32 s40, 0x78
	v_lshrrev_b32_e32 v0, 2, v145
	v_and_b32_e32 v131, 3, v145
	v_bfe_u32 v136, v145, 4, 2
	v_lshlrev_b32_e32 v136, 1, v136
	v_lshrrev_b32_e64 v136, v136, s40
	v_and_b32_e32 v136, 3, v136
	v_xor_b32_e32 v131, v131, v136
	v_lshlrev_b32_e32 v131, 4, v131
	s_movk_i32 s42, 0x800
	v_mad_u32_u24 v0, v0, s42, v131
	v_bfe_u32 v137, v145, 2, 1
	s_movk_i32 s42, 0x7c0
	v_mul_u32_u24_e32 v136, s42, v137
	v_sub_u32_e32 v136, v0, v136
	v_mov_b32_e32 v137, 0
	v_lshl_add_u64 v[134:135], s[10:11], 0, v[136:137]
	v_bfe_u32 v137, v145, 2, 1
	s_mov_b32 s12, 64
	s_mov_b32 s13, 0
	v_lshl_add_u64 v[132:133], s[4:5], 0, v[0:1]
	v_bfe_u32 v136, v145, 2, 2
	v_lshlrev_b32_e32 v136, 1, v136
	v_lshrrev_b32_e64 v136, v136, s40
	v_and_b32_e32 v136, 3, v136
	v_bfe_u32 v137, v145, 4, 2
	v_xor_b32_e32 v136, v136, v137
	v_lshlrev_b32_e32 v136, 4, v136
	v_and_b32_e32 v131, 15, v145
	v_lshl_or_b32 v136, v131, 6, v136
	v_bfe_u32 v137, v145, 6, 1
	v_lshl_or_b32 v137, v137, 12, v136
	v_lshrrev_b32_e32 v0, 7, v145
	v_lshl_or_b32 v136, v0, 13, v136
	v_and_b32_e32 v140, 1, v131
	v_lshl_or_b32 v131, v0, 7, v131
	v_bfe_u32 v0, v145, 4, 2
	v_lshlrev_b32_e32 v0, 3, v0
	v_bfe_u32 v141, v145, 6, 1
	s_lshl_b32 s41, s46, 19
	s_lshl_b32 s42, s43, 9
	s_add_i32 s41, s41, s42
	s_add_u32 s4, s2, s41
	s_addc_u32 s5, s3, 0
	s_add_u32 s4, s4, 0x4200000
	s_addc_u32 s5, s5, 0
	v_lshlrev_b32_e32 v138, 11, v131
	v_lshl_add_u32 v138, v141, 8, v138
	v_bfe_u32 v139, v145, 4, 1
	v_lshl_add_u32 v138, v139, 5, v138
	v_bfe_u32 v139, v145, 5, 1
	v_lshl_add_u32 v138, v139, 4, v138
	s_movk_i32 s42, 1984
	v_mul_u32_u24_e32 v139, s42, v140
	v_sub_u32_e32 v138, v138, v139
	v_mov_b32_e32 v139, 0
	v_lshl_add_u64 v[138:139], s[4:5], 0, v[138:139]
	s_lshl_b32 s41, s46, 20
	s_lshl_b32 s42, s43, 9
	s_add_i32 s41, s41, s42
	s_add_u32 s10, s2, s41
	s_addc_u32 s11, s3, 0
	v_lshlrev_b32_e32 v140, 12, v131
	v_lshl_add_u32 v140, v141, 8, v140
	v_lshl_add_u32 v140, v0, 1, v140
	v_mov_b32_e32 v141, 0
	v_lshl_add_u64 v[140:141], s[10:11], 0, v[140:141]
	s_mov_b32 s2, 0x20000
	s_mov_b32 s3, 0
	v_lshrrev_b32_e32 v0, 6, v145
	v_lshlrev_b32_e32 v0, 10, v0
	s_nop 0
	v_readfirstlane_b32 s47, v0
	s_mov_b32 s44, m0
	s_mov_b32 s4, 128
	s_mov_b32 s5, 0
	s_barrier
; #define LAS __attribute__((address_space(3)))
;     ...
;   f32x4 acc[4][8];
; #pragma unroll
;   for (int i = 0; i < 4; i++)
; #pragma unroll
;     for (int j = 0; j < 8; j++) acc[i][j] = (f32x4){0.f, 0.f, 0.f, 0.f};
;   const int nk = (nk_part < 0) ? (K >> 5) : nk_part;
;   const int lrow = tid >> 2, lpc = tid & 3;
;   const int lch = lpc ^ ((0x78 >> (((lrow >> 2) & 3) * 2)) & 3);
;   const u16* ga = A + (size_t)(m0 + lrow) * lda + kbeg + lch * 8;
;   const u16* gb = Bt + (size_t)(n0 + lrow) * K + kbeg + lch * 8;
;   const size_t ga1 = (size_t)64 * lda, gb1 = (size_t)64 * K;
;   const unsigned lds0 = (unsigned)(uintptr_t)(LAS char*)smem + (unsigned)__builtin_amdgcn_readfirstlane(wid) * 1024u;
;     ...
;   __syncthreads();
;   G2_STAGE(0); G2_STAGE(1);
;   const int fsw = (0x78 >> (((r16 >> 2) & 3) * 2)) & 3;
;   const int aoff = (wm * 128 + r16) * 64 + ((quad ^ fsw) << 4);
;   const int boff = 16384 + (wn * 64 + r16) * 64 + ((quad ^ fsw) << 4);
;   for (int kt = 0; kt < nk; kt++) {
;     if (kt + 1 < nk) asm volatile("s_waitcnt vmcnt(6)" ::: "memory");
;     else asm volatile("s_waitcnt vmcnt(0)" ::: "memory");
;     __builtin_amdgcn_s_barrier();
;     asm volatile("" ::: "memory");
;     if (kt + 2 < nk) G2_STAGE(kt + 2);
;     const char* cS = smem + (kt % 3) * 24576;
;     bf16x8 xa[8], wb[4];
; #pragma unroll
;     for (int f = 0; f < 8; f++) xa[f] = *(const bf16x8*)(cS + aoff + f * 1024);
; #pragma unroll
;     for (int f = 0; f < 4; f++) wb[f] = *(const bf16x8*)(cS + boff + f * 1024);
	s_add_i32 s43, s47, 0x0
	s_mov_b32 m0, s43
	v_lshl_add_u64 v[142:143], v[132:133], 0, s[2:3]
	global_load_lds_dwordx4 v[132:133], off
	s_add_i32 m0, m0, 0x1000
	s_nop 0
	global_load_lds_dwordx4 v[142:143], off
	v_lshl_add_u64 v[142:143], v[142:143], 0, s[2:3]
	s_add_i32 m0, m0, 0x1000
	s_nop 0
	global_load_lds_dwordx4 v[142:143], off
	v_lshl_add_u64 v[142:143], v[142:143], 0, s[2:3]
	s_add_i32 m0, m0, 0x1000
	s_nop 0
	global_load_lds_dwordx4 v[142:143], off
	s_add_i32 m0, m0, 0x1000
	v_lshl_add_u64 v[142:143], v[134:135], 0, s[2:3]
	s_nop 0
	global_load_lds_dwordx4 v[134:135], off
	s_add_i32 m0, m0, 0x1000
	v_lshl_add_u64 v[132:133], v[132:133], 0, s[12:13]
	s_nop 0
	global_load_lds_dwordx4 v[142:143], off
	v_lshl_add_u64 v[134:135], v[134:135], 0, s[4:5]
	s_nop 0
	s_add_i32 s43, s47, 0x6000
	s_mov_b32 m0, s43
	v_lshl_add_u64 v[142:143], v[132:133], 0, s[2:3]
	global_load_lds_dwordx4 v[132:133], off
	s_add_i32 m0, m0, 0x1000
	s_nop 0
	global_load_lds_dwordx4 v[142:143], off
	v_lshl_add_u64 v[142:143], v[142:143], 0, s[2:3]
	s_add_i32 m0, m0, 0x1000
	s_nop 0
	global_load_lds_dwordx4 v[142:143], off
	v_lshl_add_u64 v[142:143], v[142:143], 0, s[2:3]
	s_add_i32 m0, m0, 0x1000
	s_nop 0
	global_load_lds_dwordx4 v[142:143], off
	s_add_i32 m0, m0, 0x1000
	v_lshl_add_u64 v[142:143], v[134:135], 0, s[2:3]
	s_nop 0
	global_load_lds_dwordx4 v[134:135], off
	s_add_i32 m0, m0, 0x1000
	v_lshl_add_u64 v[132:133], v[132:133], 0, s[12:13]
	s_nop 0
	global_load_lds_dwordx4 v[142:143], off
	v_lshl_add_u64 v[134:135], v[134:135], 0, s[4:5]
	s_nop 0
	s_add_i32 s43, s47, 0xc000
	s_mov_b32 m0, s43
	v_lshl_add_u64 v[142:143], v[132:133], 0, s[2:3]
	global_load_lds_dwordx4 v[132:133], off
	s_add_i32 m0, m0, 0x1000
	s_nop 0
	global_load_lds_dwordx4 v[142:143], off
	v_lshl_add_u64 v[142:143], v[142:143], 0, s[2:3]
	s_add_i32 m0, m0, 0x1000
	s_nop 0
	global_load_lds_dwordx4 v[142:143], off
	v_lshl_add_u64 v[142:143], v[142:143], 0, s[2:3]
	s_add_i32 m0, m0, 0x1000
	s_nop 0
	global_load_lds_dwordx4 v[142:143], off
	s_add_i32 m0, m0, 0x1000
	v_lshl_add_u64 v[142:143], v[134:135], 0, s[2:3]
	s_nop 0
	global_load_lds_dwordx4 v[134:135], off
	s_add_i32 m0, m0, 0x1000
	v_lshl_add_u64 v[132:133], v[132:133], 0, s[12:13]
	s_nop 0
	global_load_lds_dwordx4 v[142:143], off
	v_lshl_add_u64 v[134:135], v[134:135], 0, s[4:5]
	s_nop 0
	v_mov_b32_e32 v2, 0
	v_mov_b32_e32 v3, 0
	v_mov_b32_e32 v4, 0
	v_mov_b32_e32 v5, 0
	v_mov_b32_e32 v6, 0
	v_mov_b32_e32 v7, 0
	v_mov_b32_e32 v8, 0
	v_mov_b32_e32 v9, 0
	v_mov_b32_e32 v10, 0
	v_mov_b32_e32 v11, 0
	v_mov_b32_e32 v12, 0
	v_mov_b32_e32 v13, 0
	v_mov_b32_e32 v14, 0
	v_mov_b32_e32 v15, 0
	v_mov_b32_e32 v16, 0
	v_mov_b32_e32 v17, 0
	v_mov_b32_e32 v18, 0
	v_mov_b32_e32 v19, 0
	v_mov_b32_e32 v20, 0
	v_mov_b32_e32 v21, 0
	v_mov_b32_e32 v22, 0
	v_mov_b32_e32 v23, 0
	v_mov_b32_e32 v24, 0
	v_mov_b32_e32 v25, 0
	v_mov_b32_e32 v26, 0
	v_mov_b32_e32 v27, 0
	v_mov_b32_e32 v28, 0
	v_mov_b32_e32 v29, 0
	v_mov_b32_e32 v30, 0
	v_mov_b32_e32 v31, 0
	v_mov_b32_e32 v32, 0
	v_mov_b32_e32 v33, 0
	v_mov_b32_e32 v34, 0
	v_mov_b32_e32 v35, 0
	v_mov_b32_e32 v36, 0
	v_mov_b32_e32 v37, 0
	v_mov_b32_e32 v38, 0
	v_mov_b32_e32 v39, 0
	v_mov_b32_e32 v40, 0
	v_mov_b32_e32 v41, 0
	v_mov_b32_e32 v42, 0
	v_mov_b32_e32 v43, 0
	v_mov_b32_e32 v44, 0
	v_mov_b32_e32 v45, 0
	v_mov_b32_e32 v46, 0
	v_mov_b32_e32 v47, 0
	v_mov_b32_e32 v48, 0
	v_mov_b32_e32 v49, 0
	v_mov_b32_e32 v50, 0
	v_mov_b32_e32 v51, 0
	v_mov_b32_e32 v52, 0
	v_mov_b32_e32 v53, 0
	v_mov_b32_e32 v54, 0
	v_mov_b32_e32 v55, 0
	v_mov_b32_e32 v56, 0
	v_mov_b32_e32 v57, 0
	v_mov_b32_e32 v58, 0
	v_mov_b32_e32 v59, 0
	v_mov_b32_e32 v60, 0
	v_mov_b32_e32 v61, 0
	v_mov_b32_e32 v62, 0
	v_mov_b32_e32 v63, 0
	v_mov_b32_e32 v64, 0
	v_mov_b32_e32 v65, 0
	v_mov_b32_e32 v66, 0
	v_mov_b32_e32 v67, 0
	v_mov_b32_e32 v68, 0
	v_mov_b32_e32 v69, 0
	v_mov_b32_e32 v70, 0
	v_mov_b32_e32 v71, 0
	v_mov_b32_e32 v72, 0
	v_mov_b32_e32 v73, 0
	v_mov_b32_e32 v74, 0
	v_mov_b32_e32 v75, 0
	v_mov_b32_e32 v76, 0
	v_mov_b32_e32 v77, 0
	v_mov_b32_e32 v78, 0
	v_mov_b32_e32 v79, 0
	v_mov_b32_e32 v80, 0
	v_mov_b32_e32 v81, 0
	v_mov_b32_e32 v82, 0
	v_mov_b32_e32 v83, 0
	v_mov_b32_e32 v84, 0
	v_mov_b32_e32 v85, 0
	v_mov_b32_e32 v86, 0
	v_mov_b32_e32 v87, 0
	v_mov_b32_e32 v88, 0
	v_mov_b32_e32 v89, 0
	v_mov_b32_e32 v90, 0
	v_mov_b32_e32 v91, 0
	v_mov_b32_e32 v92, 0
	v_mov_b32_e32 v93, 0
	v_mov_b32_e32 v94, 0
	v_mov_b32_e32 v95, 0
	v_mov_b32_e32 v96, 0
	v_mov_b32_e32 v97, 0
	v_mov_b32_e32 v98, 0
	v_mov_b32_e32 v99, 0
	v_mov_b32_e32 v100, 0
	v_mov_b32_e32 v101, 0
	v_mov_b32_e32 v102, 0
	v_mov_b32_e32 v103, 0
	v_mov_b32_e32 v104, 0
	v_mov_b32_e32 v105, 0
	v_mov_b32_e32 v106, 0
	v_mov_b32_e32 v107, 0
	v_mov_b32_e32 v108, 0
	v_mov_b32_e32 v109, 0
	v_mov_b32_e32 v110, 0
	v_mov_b32_e32 v111, 0
	v_mov_b32_e32 v112, 0
	v_mov_b32_e32 v113, 0
	v_mov_b32_e32 v114, 0
	v_mov_b32_e32 v115, 0
	v_mov_b32_e32 v116, 0
	v_mov_b32_e32 v117, 0
	v_mov_b32_e32 v118, 0
	v_mov_b32_e32 v119, 0
	v_mov_b32_e32 v120, 0
	v_mov_b32_e32 v121, 0
	v_mov_b32_e32 v122, 0
	v_mov_b32_e32 v123, 0
	v_mov_b32_e32 v124, 0
	v_mov_b32_e32 v125, 0
	v_mov_b32_e32 v126, 0
	v_mov_b32_e32 v127, 0
	v_mov_b32_e32 v128, 0
	v_mov_b32_e32 v129, 0
	s_setprio 0
	s_waitcnt vmcnt(12)
	s_barrier
	ds_read_b128 v[146:149], v136 offset:0
	ds_read_b128 v[152:155], v136 offset:1024
	ds_read_b128 v[156:159], v136 offset:2048
	ds_read_b128 v[162:165], v136 offset:3072
	ds_read_b128 v[166:169], v136 offset:4096
	ds_read_b128 v[170:173], v136 offset:5120
	ds_read_b128 v[176:179], v136 offset:6144
	ds_read_b128 v[180:183], v136 offset:7168
	ds_read_b128 v[184:187], v137 offset:16384
	ds_read_b128 v[188:191], v137 offset:17408
	ds_read_b128 v[192:195], v137 offset:18432
	ds_read_b128 v[196:199], v137 offset:19456
	s_movk_i32 s41, 0x6000
	s_mov_b32 s42, 0
	s_movk_i32 s40, 14
	.p2align 6

; DEVI void tile_coords(int T, int MT, int NT, int& mt, int& nt) {
;   const int full = MT >> 3, band = T / (8 * NT);
;   if (band < full) { const int r = T - band * 8 * NT; nt = r >> 3; mt = band * 8 + (r & 7); }
;   else { const int MB = MT - full * 8; const int r = T - full * 8 * NT; nt = r / MB; mt = full * 8 + r % MB; }
; }
.LBB0_909:
	s_and_b64 vcc, exec, s[2:3]
	s_cbranch_vccz .LBB0_886
	s_setprio 2
	s_lshr_b32 s43, s14, 5
	s_mul_i32 s43, s43, 52
	s_lshr_b32 s43, s43, 8
	s_cmp_lt_u32 s43, 8
	s_cbranch_scc0 .Lt0_rem
	s_mul_i32 s44, s43, 160
	s_sub_i32 s44, s14, s44
	s_lshr_b32 s40, s44, 3
	s_and_b32 s44, s44, 7
	s_lshl_b32 s43, s43, 3
	s_add_i32 s43, s43, s44
	s_branch .Lt0_crd

; #define LAS __attribute__((address_space(3)))
; DEVI int tidx() { int t = threadIdx.x; asm volatile("" : "+v"(t)); return t; }
;   const int tid = tidx(), lane = tid & 63, wid = tid >> 6;
;   const int wm = wid >> 1, wn = wid & 1, r16 = lane & 15, quad = lane >> 4;
;   f32x4 acc[4][8];
; #pragma unroll
;   for (int i = 0; i < 4; i++)
; #pragma unroll
;     for (int j = 0; j < 8; j++) acc[i][j] = (f32x4){0.f, 0.f, 0.f, 0.f};
;   const int nk = (nk_part < 0) ? (K >> 5) : nk_part;
;   const int lrow = tid >> 2, lpc = tid & 3;
;   const int lch = lpc ^ ((0x78 >> (((lrow >> 2) & 3) * 2)) & 3);
;   const u16* ga = A + (size_t)(m0 + lrow) * lda + kbeg + lch * 8;
;   const u16* gb = Bt + (size_t)(n0 + lrow) * K + kbeg + lch * 8;
;   const size_t ga1 = (size_t)64 * lda, gb1 = (size_t)64 * K;
;   const unsigned lds0 = (unsigned)(uintptr_t)(LAS char*)smem + (unsigned)__builtin_amdgcn_readfirstlane(wid) * 1024u;
.Lt0_crd:
	s_cmp_lt_u32 s43, 64
	s_cselect_b32 s42, 1, 0
	v_readlane_b32 s2, v250, 5
	v_readlane_b32 s3, v250, 6
	v_readlane_b32 s44, v254, 62
	s_mul_i32 s38, s43, 0x80000
	s_add_u32 s8, s2, s38
	s_addc_u32 s9, s3, 0
	s_add_u32 s8, s8, 0x4200000
	s_addc_u32 s9, s9, 0
	s_mul_i32 s38, s44, 0x500000
	s_mul_i32 s39, s40, 0x40000
	s_add_i32 s38, s38, s39
	s_add_u32 s10, s2, s38
	s_addc_u32 s11, s3, 0
	s_add_u32 s10, s10, 0x14a00000
	s_addc_u32 s11, s11, 0
	s_movk_i32 s15, 0x78
	v_lshrrev_b32_e32 v0, 2, v145
	v_and_b32_e32 v131, 3, v145
	v_bfe_u32 v136, v145, 4, 2
	v_lshlrev_b32_e32 v136, 1, v136
	v_lshrrev_b32_e64 v136, v136, s15
	v_and_b32_e32 v136, 3, v136
	v_xor_b32_e32 v131, v131, v136
	v_lshlrev_b32_e32 v131, 4, v131
	s_movk_i32 s39, 0x800
	v_mad_u32_u24 v0, v0, s39, v131
	v_bfe_u32 v137, v145, 2, 1
	s_movk_i32 s39, 0x7c0
	v_mul_u32_u24_e32 v136, s39, v137
	v_sub_u32_e32 v136, v0, v136
	v_mov_b32_e32 v137, 0
	v_lshl_add_u64 v[134:135], s[10:11], 0, v[136:137]
	v_bfe_u32 v137, v145, 2, 1
	s_mul_i32 s39, s42, 0x7c0
	v_mul_u32_u24_e32 v136, s39, v137
	v_sub_u32_e32 v0, v0, v136
	s_lshl_b32 s36, s42, 6
	s_add_i32 s36, s36, 64
	s_mov_b32 s37, 0
	v_lshl_add_u64 v[132:133], s[8:9], 0, v[0:1]
	v_bfe_u32 v136, v145, 2, 2
	v_lshlrev_b32_e32 v136, 1, v136
	v_lshrrev_b32_e64 v136, v136, s15
	v_and_b32_e32 v136, 3, v136
	v_bfe_u32 v137, v145, 4, 2
	v_xor_b32_e32 v136, v136, v137
	v_lshlrev_b32_e32 v136, 4, v136
	v_and_b32_e32 v131, 15, v145
	v_lshl_or_b32 v136, v131, 6, v136
	v_bfe_u32 v137, v145, 6, 1
	v_lshl_or_b32 v137, v137, 12, v136
	v_lshrrev_b32_e32 v0, 7, v145
	v_lshl_or_b32 v136, v0, 13, v136
	v_and_b32_e32 v140, 1, v131
	v_lshl_or_b32 v131, v0, 7, v131
	v_bfe_u32 v0, v145, 4, 1
	v_lshlrev_b32_e32 v0, 5, v0
	v_bfe_u32 v141, v145, 5, 1
	v_lshl_or_b32 v0, v141, 4, v0
	v_bfe_u32 v141, v145, 6, 1
	s_mul_i32 s38, s43, 0x140000
	s_lshl_b32 s39, s40, 8
	s_add_i32 s38, s38, s39
	s_add_u32 s10, s2, s38
	s_addc_u32 s11, s3, 0
	s_add_u32 s10, s10, 0x6300000
	s_addc_u32 s11, s11, 0
	s_movk_i32 s39, 5120
	v_mad_u32_u24 v138, v131, s39, v0
	v_lshl_add_u32 v138, v141, 7, v138
	v_mov_b32_e32 v139, 0
	v_lshl_add_u64 v[140:141], s[10:11], 0, v[138:139]
	s_mov_b32 s2, 0x20000
	s_mov_b32 s3, 0
	v_lshrrev_b32_e32 v0, 6, v145
	v_lshlrev_b32_e32 v0, 10, v0
	s_nop 0
	v_readfirstlane_b32 s44, v0
	s_mov_b32 s41, m0
	s_mov_b32 s8, 128
	s_mov_b32 s9, 0
	s_barrier
; #define LAS __attribute__((address_space(3)))
;     ...
;   f32x4 acc[4][8];
; #pragma unroll
;   for (int i = 0; i < 4; i++)
; #pragma unroll
;     for (int j = 0; j < 8; j++) acc[i][j] = (f32x4){0.f, 0.f, 0.f, 0.f};
;   const int nk = (nk_part < 0) ? (K >> 5) : nk_part;
;   const int lrow = tid >> 2, lpc = tid & 3;
;   const int lch = lpc ^ ((0x78 >> (((lrow >> 2) & 3) * 2)) & 3);
;   const u16* ga = A + (size_t)(m0 + lrow) * lda + kbeg + lch * 8;
;   const u16* gb = Bt + (size_t)(n0 + lrow) * K + kbeg + lch * 8;
;   const size_t ga1 = (size_t)64 * lda, gb1 = (size_t)64 * K;
;   const unsigned lds0 = (unsigned)(uintptr_t)(LAS char*)smem + (unsigned)__builtin_amdgcn_readfirstlane(wid) * 1024u;
;     ...
;   __syncthreads();
;   G2_STAGE(0); G2_STAGE(1);
;   const int fsw = (0x78 >> (((r16 >> 2) & 3) * 2)) & 3;
;   const int aoff = (wm * 128 + r16) * 64 + ((quad ^ fsw) << 4);
;   const int boff = 16384 + (wn * 64 + r16) * 64 + ((quad ^ fsw) << 4);
;   for (int kt = 0; kt < nk; kt++) {
;     if (kt + 1 < nk) asm volatile("s_waitcnt vmcnt(6)" ::: "memory");
;     else asm volatile("s_waitcnt vmcnt(0)" ::: "memory");
;     __builtin_amdgcn_s_barrier();
;     asm volatile("" ::: "memory");
;     if (kt + 2 < nk) G2_STAGE(kt + 2);
;     const char* cS = smem + (kt % 3) * 24576;
;     bf16x8 xa[8], wb[4];
; #pragma unroll
;     for (int f = 0; f < 8; f++) xa[f] = *(const bf16x8*)(cS + aoff + f * 1024);
; #pragma unroll
;     for (int f = 0; f < 4; f++) wb[f] = *(const bf16x8*)(cS + boff + f * 1024);
	s_add_i32 s40, s44, 0x0
	s_mov_b32 m0, s40
	v_lshl_add_u64 v[142:143], v[132:133], 0, s[2:3]
	global_load_lds_dwordx4 v[132:133], off
	s_add_i32 m0, m0, 0x1000
	s_nop 0
	global_load_lds_dwordx4 v[142:143], off
	v_lshl_add_u64 v[142:143], v[142:143], 0, s[2:3]
	s_add_i32 m0, m0, 0x1000
	s_nop 0
	global_load_lds_dwordx4 v[142:143], off
	v_lshl_add_u64 v[142:143], v[142:143], 0, s[2:3]
	s_add_i32 m0, m0, 0x1000
	s_nop 0
	global_load_lds_dwordx4 v[142:143], off
	s_add_i32 m0, m0, 0x1000
	v_lshl_add_u64 v[142:143], v[134:135], 0, s[2:3]
	s_nop 0
	global_load_lds_dwordx4 v[134:135], off
	s_add_i32 m0, m0, 0x1000
	v_lshl_add_u64 v[132:133], v[132:133], 0, s[36:37]
	s_nop 0
	global_load_lds_dwordx4 v[142:143], off
	v_lshl_add_u64 v[134:135], v[134:135], 0, s[8:9]
	s_nop 0
	s_add_i32 s40, s44, 0x6000
	s_mov_b32 m0, s40
	v_lshl_add_u64 v[142:143], v[132:133], 0, s[2:3]
	global_load_lds_dwordx4 v[132:133], off
	s_add_i32 m0, m0, 0x1000
	s_nop 0
	global_load_lds_dwordx4 v[142:143], off
	v_lshl_add_u64 v[142:143], v[142:143], 0, s[2:3]
	s_add_i32 m0, m0, 0x1000
	s_nop 0
	global_load_lds_dwordx4 v[142:143], off
	v_lshl_add_u64 v[142:143], v[142:143], 0, s[2:3]
	s_add_i32 m0, m0, 0x1000
	s_nop 0
	global_load_lds_dwordx4 v[142:143], off
	s_add_i32 m0, m0, 0x1000
	v_lshl_add_u64 v[142:143], v[134:135], 0, s[2:3]
	s_nop 0
	global_load_lds_dwordx4 v[134:135], off
	s_add_i32 m0, m0, 0x1000
	v_lshl_add_u64 v[132:133], v[132:133], 0, s[36:37]
	s_nop 0
	global_load_lds_dwordx4 v[142:143], off
	v_lshl_add_u64 v[134:135], v[134:135], 0, s[8:9]
	s_nop 0
	s_add_i32 s40, s44, 0xc000
	s_mov_b32 m0, s40
	v_lshl_add_u64 v[142:143], v[132:133], 0, s[2:3]
	global_load_lds_dwordx4 v[132:133], off
	s_add_i32 m0, m0, 0x1000
	s_nop 0
	global_load_lds_dwordx4 v[142:143], off
	v_lshl_add_u64 v[142:143], v[142:143], 0, s[2:3]
	s_add_i32 m0, m0, 0x1000
	s_nop 0
	global_load_lds_dwordx4 v[142:143], off
	v_lshl_add_u64 v[142:143], v[142:143], 0, s[2:3]
	s_add_i32 m0, m0, 0x1000
	s_nop 0
	global_load_lds_dwordx4 v[142:143], off
	s_add_i32 m0, m0, 0x1000
	v_lshl_add_u64 v[142:143], v[134:135], 0, s[2:3]
	s_nop 0
	global_load_lds_dwordx4 v[134:135], off
	s_add_i32 m0, m0, 0x1000
	v_lshl_add_u64 v[132:133], v[132:133], 0, s[36:37]
	s_nop 0
	global_load_lds_dwordx4 v[142:143], off
	v_lshl_add_u64 v[134:135], v[134:135], 0, s[8:9]
	s_nop 0
	v_mov_b32_e32 v2, 0
	v_mov_b32_e32 v3, 0
	v_mov_b32_e32 v4, 0
	v_mov_b32_e32 v5, 0
	v_mov_b32_e32 v6, 0
	v_mov_b32_e32 v7, 0
	v_mov_b32_e32 v8, 0
	v_mov_b32_e32 v9, 0
	v_mov_b32_e32 v10, 0
	v_mov_b32_e32 v11, 0
	v_mov_b32_e32 v12, 0
	v_mov_b32_e32 v13, 0
	v_mov_b32_e32 v14, 0
	v_mov_b32_e32 v15, 0
	v_mov_b32_e32 v16, 0
	v_mov_b32_e32 v17, 0
	v_mov_b32_e32 v18, 0
	v_mov_b32_e32 v19, 0
	v_mov_b32_e32 v20, 0
	v_mov_b32_e32 v21, 0
	v_mov_b32_e32 v22, 0
	v_mov_b32_e32 v23, 0
	v_mov_b32_e32 v24, 0
	v_mov_b32_e32 v25, 0
	v_mov_b32_e32 v26, 0
	v_mov_b32_e32 v27, 0
	v_mov_b32_e32 v28, 0
	v_mov_b32_e32 v29, 0
	v_mov_b32_e32 v30, 0
	v_mov_b32_e32 v31, 0
	v_mov_b32_e32 v32, 0
	v_mov_b32_e32 v33, 0
	v_mov_b32_e32 v34, 0
	v_mov_b32_e32 v35, 0
	v_mov_b32_e32 v36, 0
	v_mov_b32_e32 v37, 0
	v_mov_b32_e32 v38, 0
	v_mov_b32_e32 v39, 0
	v_mov_b32_e32 v40, 0
	v_mov_b32_e32 v41, 0
	v_mov_b32_e32 v42, 0
	v_mov_b32_e32 v43, 0
	v_mov_b32_e32 v44, 0
	v_mov_b32_e32 v45, 0
	v_mov_b32_e32 v46, 0
	v_mov_b32_e32 v47, 0
	v_mov_b32_e32 v48, 0
	v_mov_b32_e32 v49, 0
	v_mov_b32_e32 v50, 0
	v_mov_b32_e32 v51, 0
	v_mov_b32_e32 v52, 0
	v_mov_b32_e32 v53, 0
	v_mov_b32_e32 v54, 0
	v_mov_b32_e32 v55, 0
	v_mov_b32_e32 v56, 0
	v_mov_b32_e32 v57, 0
	v_mov_b32_e32 v58, 0
	v_mov_b32_e32 v59, 0
	v_mov_b32_e32 v60, 0
	v_mov_b32_e32 v61, 0
	v_mov_b32_e32 v62, 0
	v_mov_b32_e32 v63, 0
	v_mov_b32_e32 v64, 0
	v_mov_b32_e32 v65, 0
	v_mov_b32_e32 v66, 0
	v_mov_b32_e32 v67, 0
	v_mov_b32_e32 v68, 0
	v_mov_b32_e32 v69, 0
	v_mov_b32_e32 v70, 0
	v_mov_b32_e32 v71, 0
	v_mov_b32_e32 v72, 0
	v_mov_b32_e32 v73, 0
	v_mov_b32_e32 v74, 0
	v_mov_b32_e32 v75, 0
	v_mov_b32_e32 v76, 0
	v_mov_b32_e32 v77, 0
	v_mov_b32_e32 v78, 0
	v_mov_b32_e32 v79, 0
	v_mov_b32_e32 v80, 0
	v_mov_b32_e32 v81, 0
	v_mov_b32_e32 v82, 0
	v_mov_b32_e32 v83, 0
	v_mov_b32_e32 v84, 0
	v_mov_b32_e32 v85, 0
	v_mov_b32_e32 v86, 0
	v_mov_b32_e32 v87, 0
	v_mov_b32_e32 v88, 0
	v_mov_b32_e32 v89, 0
	v_mov_b32_e32 v90, 0
	v_mov_b32_e32 v91, 0
	v_mov_b32_e32 v92, 0
	v_mov_b32_e32 v93, 0
	v_mov_b32_e32 v94, 0
	v_mov_b32_e32 v95, 0
	v_mov_b32_e32 v96, 0
	v_mov_b32_e32 v97, 0
	v_mov_b32_e32 v98, 0
	v_mov_b32_e32 v99, 0
	v_mov_b32_e32 v100, 0
	v_mov_b32_e32 v101, 0
	v_mov_b32_e32 v102, 0
	v_mov_b32_e32 v103, 0
	v_mov_b32_e32 v104, 0
	v_mov_b32_e32 v105, 0
	v_mov_b32_e32 v106, 0
	v_mov_b32_e32 v107, 0
	v_mov_b32_e32 v108, 0
	v_mov_b32_e32 v109, 0
	v_mov_b32_e32 v110, 0
	v_mov_b32_e32 v111, 0
	v_mov_b32_e32 v112, 0
	v_mov_b32_e32 v113, 0
	v_mov_b32_e32 v114, 0
	v_mov_b32_e32 v115, 0
	v_mov_b32_e32 v116, 0
	v_mov_b32_e32 v117, 0
	v_mov_b32_e32 v118, 0
	v_mov_b32_e32 v119, 0
	v_mov_b32_e32 v120, 0
	v_mov_b32_e32 v121, 0
	v_mov_b32_e32 v122, 0
	v_mov_b32_e32 v123, 0
	v_mov_b32_e32 v124, 0
	v_mov_b32_e32 v125, 0
	v_mov_b32_e32 v126, 0
	v_mov_b32_e32 v127, 0
	v_mov_b32_e32 v128, 0
	v_mov_b32_e32 v129, 0
	s_setprio 0
	s_waitcnt vmcnt(12)
	s_barrier
	ds_read_b128 v[146:149], v136 offset:0
	ds_read_b128 v[152:155], v136 offset:1024
	ds_read_b128 v[156:159], v136 offset:2048
	ds_read_b128 v[162:165], v136 offset:3072
	ds_read_b128 v[166:169], v136 offset:4096
	ds_read_b128 v[170:173], v136 offset:5120
	ds_read_b128 v[176:179], v136 offset:6144
	ds_read_b128 v[180:183], v136 offset:7168
	ds_read_b128 v[184:187], v137 offset:16384
	ds_read_b128 v[188:191], v137 offset:17408
	ds_read_b128 v[192:195], v137 offset:18432
	ds_read_b128 v[196:199], v137 offset:19456
	s_movk_i32 s38, 0x6000
	s_mov_b32 s39, 0
	s_movk_i32 s15, 14
	.p2align 6
